# GEMM epilogue stores made write-through (sc1) so the grid barrier's L2 writeback finds less dirty data
# baseline (speedup 1.0000x reference)
.LBB0_276:
	v_lshl_or_b32 v154, s49, 8, v147
	v_cvt_pk_bf16_f32 v70, v70, v71
	v_cvt_pk_bf16_f32 v71, v72, v73
	v_cvt_pk_bf16_f32 v72, v66, v67
	v_add_u32_e32 v66, 0x80, v138
	v_mov_b32_e32 v67, v139
	v_ashrrev_i32_e32 v155, 31, v154
	v_lshlrev_b64 v[156:157], 15, v[138:139]
	v_cvt_pk_bf16_f32 v110, v110, v111
	v_cvt_pk_bf16_f32 v111, v112, v113
	v_cvt_pk_bf16_f32 v112, v106, v107
	v_or_b32_e32 v106, 16, v138
	v_mov_b32_e32 v107, v139
	v_lshlrev_b64 v[66:67], 15, v[66:67]
	v_cvt_pk_bf16_f32 v46, v46, v47
	v_cvt_pk_bf16_f32 v47, v48, v49
	v_cvt_pk_bf16_f32 v48, v42, v43
	v_add_u32_e32 v42, 0x90, v138
	v_mov_b32_e32 v43, v139
	v_lshl_add_u64 v[156:157], s[96:97], 0, v[156:157]
	v_lshlrev_b64 v[154:155], 1, v[154:155]
	v_lshlrev_b64 v[106:107], 15, v[106:107]
	v_cvt_pk_bf16_f32 v94, v94, v95
	v_cvt_pk_bf16_f32 v95, v96, v97
	v_cvt_pk_bf16_f32 v96, v90, v91
	v_or_b32_e32 v90, 32, v138
	v_mov_b32_e32 v91, v139
	v_lshl_add_u64 v[66:67], s[96:97], 0, v[66:67]
	v_lshlrev_b64 v[42:43], 15, v[42:43]
	v_cvt_pk_bf16_f32 v30, v30, v31
	v_cvt_pk_bf16_f32 v31, v32, v33
	v_cvt_pk_bf16_f32 v32, v26, v27
	v_add_u32_e32 v26, 0xa0, v138
	v_mov_b32_e32 v27, v139
	v_lshl_add_u64 v[156:157], v[156:157], 0, v[154:155]
	v_cvt_pk_bf16_f32 v113, v108, v109
	v_lshl_add_u64 v[106:107], s[96:97], 0, v[106:107]
	v_lshlrev_b64 v[90:91], 15, v[90:91]
	v_cvt_pk_bf16_f32 v78, v78, v79
	v_cvt_pk_bf16_f32 v79, v80, v81
	v_cvt_pk_bf16_f32 v80, v74, v75
	v_or_b32_e32 v74, 48, v138
	v_mov_b32_e32 v75, v139
	v_lshl_add_u64 v[66:67], v[66:67], 0, v[154:155]
	v_cvt_pk_bf16_f32 v49, v44, v45
	v_lshl_add_u64 v[42:43], s[96:97], 0, v[42:43]
	v_lshlrev_b64 v[26:27], 15, v[26:27]
	v_add_u32_e32 v138, 0xb0, v138
	global_store_dwordx4 v[156:157], v[110:113], off offset:256 sc1
	v_cvt_pk_bf16_f32 v97, v92, v93
	v_lshl_add_u64 v[90:91], s[96:97], 0, v[90:91]
	v_lshl_add_u64 v[110:111], v[106:107], 0, v[154:155]
	v_lshlrev_b64 v[74:75], 15, v[74:75]
	global_store_dwordx4 v[66:67], v[46:49], off offset:256 sc1
	v_cvt_pk_bf16_f32 v33, v28, v29
	v_lshl_add_u64 v[26:27], s[96:97], 0, v[26:27]
	v_lshl_add_u64 v[46:47], v[42:43], 0, v[154:155]
	v_cvt_pk_bf16_f32 v14, v14, v15
	v_cvt_pk_bf16_f32 v15, v16, v17
	v_cvt_pk_bf16_f32 v16, v10, v11
	v_lshlrev_b64 v[10:11], 15, v[138:139]
	global_store_dwordx4 v[110:111], v[94:97], off offset:256 sc1
	v_cvt_pk_bf16_f32 v81, v76, v77
	v_lshl_add_u64 v[74:75], s[96:97], 0, v[74:75]
	v_lshl_add_u64 v[94:95], v[90:91], 0, v[154:155]
	global_store_dwordx4 v[46:47], v[30:33], off offset:256 sc1
	v_cvt_pk_bf16_f32 v17, v12, v13
	v_lshl_add_u64 v[10:11], s[96:97], 0, v[10:11]
	v_lshl_add_u64 v[30:31], v[26:27], 0, v[154:155]
	v_cvt_pk_bf16_f32 v126, v126, v127
	v_cvt_pk_bf16_f32 v127, v128, v129
	v_cvt_pk_bf16_f32 v128, v122, v123
	v_cvt_pk_bf16_f32 v129, v124, v125
	v_cvt_pk_bf16_f32 v106, v118, v119
	v_cvt_pk_bf16_f32 v107, v120, v121
	v_cvt_pk_bf16_f32 v108, v114, v115
	v_cvt_pk_bf16_f32 v109, v116, v117
	v_cvt_pk_bf16_f32 v90, v102, v103
	v_cvt_pk_bf16_f32 v91, v104, v105
	v_cvt_pk_bf16_f32 v92, v98, v99
	v_cvt_pk_bf16_f32 v93, v100, v101
	global_store_dwordx4 v[94:95], v[78:81], off offset:256 sc1
	v_cvt_pk_bf16_f32 v76, v82, v83
	v_cvt_pk_bf16_f32 v77, v84, v85
	v_lshl_add_u64 v[78:79], v[74:75], 0, v[154:155]
	v_cvt_pk_bf16_f32 v74, v86, v87
	v_cvt_pk_bf16_f32 v75, v88, v89
	v_cvt_pk_bf16_f32 v73, v68, v69
	v_cvt_pk_bf16_f32 v62, v62, v63
	v_cvt_pk_bf16_f32 v63, v64, v65
	v_cvt_pk_bf16_f32 v64, v58, v59
	v_cvt_pk_bf16_f32 v65, v60, v61
	v_cvt_pk_bf16_f32 v42, v54, v55
	v_cvt_pk_bf16_f32 v43, v56, v57
	v_cvt_pk_bf16_f32 v44, v50, v51
	v_cvt_pk_bf16_f32 v45, v52, v53
	v_cvt_pk_bf16_f32 v26, v38, v39
	v_cvt_pk_bf16_f32 v27, v40, v41
	v_cvt_pk_bf16_f32 v28, v34, v35
	v_cvt_pk_bf16_f32 v29, v36, v37
	global_store_dwordx4 v[30:31], v[14:17], off offset:256 sc1
	v_cvt_pk_bf16_f32 v12, v18, v19
	v_cvt_pk_bf16_f32 v13, v20, v21
	v_lshl_add_u64 v[14:15], v[10:11], 0, v[154:155]
	v_cvt_pk_bf16_f32 v10, v22, v23
	v_cvt_pk_bf16_f32 v11, v24, v25
	v_cvt_pk_bf16_f32 v6, v6, v7
	v_cvt_pk_bf16_f32 v7, v8, v9
	v_cvt_pk_bf16_f32 v8, v2, v3
	v_cvt_pk_bf16_f32 v9, v4, v5
	global_store_dwordx4 v[156:157], v[126:129], off sc1
	global_store_dwordx4 v[110:111], v[106:109], off sc1
	global_store_dwordx4 v[94:95], v[90:93], off sc1
	global_store_dwordx4 v[78:79], v[74:77], off sc1
	global_store_dwordx4 v[78:79], v[70:73], off offset:256 sc1
	global_store_dwordx4 v[66:67], v[62:65], off sc1
	global_store_dwordx4 v[46:47], v[42:45], off sc1
	global_store_dwordx4 v[30:31], v[26:29], off sc1
	global_store_dwordx4 v[14:15], v[10:13], off sc1
	global_store_dwordx4 v[14:15], v[6:9], off offset:256 sc1
	s_andn2_b64 vcc, exec, s[20:21]
	s_mov_b64 s[20:21], -1
	s_cbranch_vccnz .LBB0_270
	s_branch .LBB0_282

.LBB0_278:
	s_andn2_b64 vcc, exec, s[18:19]
	s_cbranch_vccnz .LBB0_280
	v_lshlrev_b64 v[154:155], 8, v[138:139]
	v_lshl_add_u64 v[154:155], v[140:141], 0, v[154:155]
	global_store_dwordx4 v[154:155], v[126:129], off sc1
	global_store_dwordx4 v[154:155], v[122:125], off offset:16 sc1
	v_or_b32_e32 v154, 16, v138
	v_mov_b32_e32 v155, v139
	v_lshlrev_b64 v[154:155], 8, v[154:155]
	v_lshl_add_u64 v[154:155], v[140:141], 0, v[154:155]
	global_store_dwordx4 v[154:155], v[118:121], off sc1
	global_store_dwordx4 v[154:155], v[114:117], off offset:16 sc1
	v_or_b32_e32 v154, 32, v138
	v_mov_b32_e32 v155, v139
	v_lshlrev_b64 v[154:155], 8, v[154:155]
	v_lshl_add_u64 v[154:155], v[140:141], 0, v[154:155]
	global_store_dwordx4 v[154:155], v[102:105], off sc1
	global_store_dwordx4 v[154:155], v[98:101], off offset:16 sc1
	v_or_b32_e32 v154, 48, v138
	v_mov_b32_e32 v155, v139
	v_lshlrev_b64 v[154:155], 8, v[154:155]
	v_lshl_add_u64 v[154:155], v[140:141], 0, v[154:155]
	global_store_dwordx4 v[154:155], v[86:89], off sc1
	global_store_dwordx4 v[154:155], v[82:85], off offset:16 sc1
	v_add_u32_e32 v154, 0x80, v138
	v_mov_b32_e32 v155, v139
	v_lshlrev_b64 v[154:155], 8, v[154:155]
	v_lshl_add_u64 v[154:155], v[140:141], 0, v[154:155]
	global_store_dwordx4 v[154:155], v[62:65], off sc1
	global_store_dwordx4 v[154:155], v[58:61], off offset:16 sc1
	v_add_u32_e32 v154, 0x90, v138
	v_mov_b32_e32 v155, v139
	v_lshlrev_b64 v[154:155], 8, v[154:155]
	v_lshl_add_u64 v[154:155], v[140:141], 0, v[154:155]
	global_store_dwordx4 v[154:155], v[54:57], off sc1
	global_store_dwordx4 v[154:155], v[50:53], off offset:16 sc1
	v_add_u32_e32 v154, 0xa0, v138
	v_mov_b32_e32 v155, v139
	v_lshlrev_b64 v[154:155], 8, v[154:155]
	v_lshl_add_u64 v[154:155], v[140:141], 0, v[154:155]
	global_store_dwordx4 v[154:155], v[38:41], off sc1
	global_store_dwordx4 v[154:155], v[34:37], off offset:16 sc1
	v_add_u32_e32 v154, 0xb0, v138
	v_mov_b32_e32 v155, v139
	v_lshlrev_b64 v[154:155], 8, v[154:155]
	v_lshl_add_u64 v[154:155], v[140:141], 0, v[154:155]
	global_store_dwordx4 v[154:155], v[22:25], off sc1
	global_store_dwordx4 v[154:155], v[18:21], off offset:16 sc1

.LBB0_1012:
	v_lshl_add_u32 v146, s46, 8, v152
	v_lshl_or_b32 v144, s45, 8, v154
	v_ashrrev_i32_e32 v147, 31, v146
	v_ashrrev_i32_e32 v145, 31, v144
	v_lshlrev_b64 v[142:143], 12, v[146:147]
	v_lshl_add_u64 v[142:143], v[142:143], 0, v[144:145]
	v_lshl_add_u64 v[172:173], v[142:143], 2, s[60:61]
	global_load_dwordx4 v[158:161], v[172:173], off offset:16
	global_load_dwordx4 v[168:171], v[172:173], off
	global_load_dwordx4 v[176:179], v[172:173], off offset:528
	global_load_dwordx4 v[180:183], v[172:173], off offset:512
	s_mov_b64 s[22:23], 0x80000
	s_andn2_b64 vcc, exec, s[20:21]
	s_waitcnt vmcnt(0)
	v_pk_add_f32 v[160:161], v[124:125], v[160:161]
	v_pk_add_f32 v[126:127], v[126:127], v[168:169]
	v_pk_add_f32 v[128:129], v[128:129], v[170:171]
	v_pk_add_f32 v[124:125], v[122:123], v[158:159]
	v_cvt_pk_bf16_f32 v122, v126, v127
	v_cvt_pk_bf16_f32 v123, v128, v129
	v_lshl_add_u64 v[126:127], v[142:143], 1, s[96:97]
	v_cvt_pk_bf16_f32 v124, v124, v125
	v_cvt_pk_bf16_f32 v125, v160, v161
	global_store_dwordx4 v[126:127], v[122:125], off sc1
	v_pk_add_f32 v[118:119], v[118:119], v[180:181]
	v_pk_add_f32 v[120:121], v[120:121], v[182:183]
	v_pk_add_f32 v[122:123], v[116:117], v[178:179]
	v_pk_add_f32 v[116:117], v[114:115], v[176:177]
	v_cvt_pk_bf16_f32 v114, v118, v119
	v_cvt_pk_bf16_f32 v115, v120, v121
	s_nop 0
	v_cvt_pk_bf16_f32 v116, v116, v117
	v_cvt_pk_bf16_f32 v117, v122, v123
	global_store_dwordx4 v[126:127], v[114:117], off offset:256 sc1
	s_nop 1
	v_or_b32_e32 v114, 16, v146
	v_ashrrev_i32_e32 v115, 31, v114
	v_lshlrev_b64 v[114:115], 12, v[114:115]
	v_lshl_add_u64 v[158:159], v[114:115], 0, v[144:145]
	v_lshl_add_u64 v[126:127], v[158:159], 2, s[60:61]
	global_load_dwordx4 v[114:117], v[126:127], off offset:16
	global_load_dwordx4 v[118:121], v[126:127], off
	global_load_dwordx4 v[122:125], v[126:127], off offset:528
	s_nop 0
	global_load_dwordx4 v[126:129], v[126:127], off offset:512
	s_waitcnt vmcnt(3)
	v_pk_add_f32 v[116:117], v[108:109], v[116:117]
	s_waitcnt vmcnt(2)
	v_pk_add_f32 v[110:111], v[110:111], v[118:119]
	v_pk_add_f32 v[112:113], v[112:113], v[120:121]
	v_pk_add_f32 v[108:109], v[106:107], v[114:115]
	v_cvt_pk_bf16_f32 v106, v110, v111
	v_cvt_pk_bf16_f32 v107, v112, v113
	v_lshl_add_u64 v[110:111], v[158:159], 1, s[96:97]
	v_cvt_pk_bf16_f32 v108, v108, v109
	v_cvt_pk_bf16_f32 v109, v116, v117
	global_store_dwordx4 v[110:111], v[106:109], off sc1
	s_waitcnt vmcnt(1)
	v_pk_add_f32 v[102:103], v[102:103], v[126:127]
	v_pk_add_f32 v[104:105], v[104:105], v[128:129]
	v_pk_add_f32 v[106:107], v[100:101], v[124:125]
	v_pk_add_f32 v[100:101], v[98:99], v[122:123]
	v_cvt_pk_bf16_f32 v98, v102, v103
	v_cvt_pk_bf16_f32 v99, v104, v105
	s_nop 0
	v_cvt_pk_bf16_f32 v100, v100, v101
	v_cvt_pk_bf16_f32 v101, v106, v107
	global_store_dwordx4 v[110:111], v[98:101], off offset:256 sc1
	s_nop 1
	v_or_b32_e32 v98, 32, v146
	v_ashrrev_i32_e32 v99, 31, v98
	v_lshlrev_b64 v[98:99], 12, v[98:99]
	v_lshl_add_u64 v[114:115], v[98:99], 0, v[144:145]
	v_lshl_add_u64 v[110:111], v[114:115], 2, s[60:61]
	global_load_dwordx4 v[98:101], v[110:111], off offset:16
	global_load_dwordx4 v[102:105], v[110:111], off
	global_load_dwordx4 v[106:109], v[110:111], off offset:528
	s_nop 0
	global_load_dwordx4 v[110:113], v[110:111], off offset:512
	s_waitcnt vmcnt(3)
	v_pk_add_f32 v[100:101], v[92:93], v[100:101]
	s_waitcnt vmcnt(2)
	v_pk_add_f32 v[94:95], v[94:95], v[102:103]
	v_pk_add_f32 v[96:97], v[96:97], v[104:105]
	v_pk_add_f32 v[92:93], v[90:91], v[98:99]
	v_cvt_pk_bf16_f32 v90, v94, v95
	v_cvt_pk_bf16_f32 v91, v96, v97
	v_lshl_add_u64 v[94:95], v[114:115], 1, s[96:97]
	v_cvt_pk_bf16_f32 v92, v92, v93
	v_cvt_pk_bf16_f32 v93, v100, v101
	global_store_dwordx4 v[94:95], v[90:93], off sc1
	s_waitcnt vmcnt(1)
	v_pk_add_f32 v[86:87], v[86:87], v[110:111]
	v_pk_add_f32 v[88:89], v[88:89], v[112:113]
	v_pk_add_f32 v[90:91], v[84:85], v[108:109]
	v_pk_add_f32 v[84:85], v[82:83], v[106:107]
	v_cvt_pk_bf16_f32 v82, v86, v87
	v_cvt_pk_bf16_f32 v83, v88, v89
	s_nop 0
	v_cvt_pk_bf16_f32 v84, v84, v85
	v_cvt_pk_bf16_f32 v85, v90, v91
	global_store_dwordx4 v[94:95], v[82:85], off offset:256 sc1
	s_nop 1
	v_or_b32_e32 v82, 48, v146
	v_ashrrev_i32_e32 v83, 31, v82
	v_lshlrev_b64 v[82:83], 12, v[82:83]
	v_lshl_add_u64 v[98:99], v[82:83], 0, v[144:145]
	v_lshl_add_u64 v[94:95], v[98:99], 2, s[60:61]
	global_load_dwordx4 v[82:85], v[94:95], off offset:16
	global_load_dwordx4 v[86:89], v[94:95], off
	global_load_dwordx4 v[90:93], v[94:95], off offset:528
	s_nop 0
	global_load_dwordx4 v[94:97], v[94:95], off offset:512
	s_waitcnt vmcnt(3)
	v_pk_add_f32 v[84:85], v[76:77], v[84:85]
	s_waitcnt vmcnt(2)
	v_pk_add_f32 v[78:79], v[78:79], v[86:87]
	v_pk_add_f32 v[80:81], v[80:81], v[88:89]
	v_pk_add_f32 v[76:77], v[74:75], v[82:83]
	v_cvt_pk_bf16_f32 v74, v78, v79
	v_cvt_pk_bf16_f32 v75, v80, v81
	v_lshl_add_u64 v[78:79], v[98:99], 1, s[96:97]
	v_cvt_pk_bf16_f32 v76, v76, v77
	v_cvt_pk_bf16_f32 v77, v84, v85
	global_store_dwordx4 v[78:79], v[74:77], off sc1
	v_lshl_add_u64 v[82:83], v[142:143], 0, s[22:23]
	s_waitcnt vmcnt(1)
	v_pk_add_f32 v[72:73], v[72:73], v[96:97]
	v_pk_add_f32 v[74:75], v[68:69], v[92:93]
	v_pk_add_f32 v[68:69], v[66:67], v[90:91]
	v_pk_add_f32 v[70:71], v[70:71], v[94:95]
	s_mov_b64 s[22:23], 0x90000
	v_cvt_pk_bf16_f32 v66, v70, v71
	v_cvt_pk_bf16_f32 v67, v72, v73
	v_cvt_pk_bf16_f32 v68, v68, v69
	v_cvt_pk_bf16_f32 v69, v74, v75
	global_store_dwordx4 v[78:79], v[66:69], off offset:256 sc1
	v_lshl_add_u64 v[78:79], v[82:83], 2, s[60:61]
	global_load_dwordx4 v[66:69], v[78:79], off offset:16
	global_load_dwordx4 v[70:73], v[78:79], off
	global_load_dwordx4 v[74:77], v[78:79], off offset:528
	s_nop 0
	global_load_dwordx4 v[78:81], v[78:79], off offset:512
	s_waitcnt vmcnt(3)
	v_pk_add_f32 v[68:69], v[60:61], v[68:69]
	s_waitcnt vmcnt(2)
	v_pk_add_f32 v[62:63], v[62:63], v[70:71]
	v_pk_add_f32 v[64:65], v[64:65], v[72:73]
	v_pk_add_f32 v[60:61], v[58:59], v[66:67]
	v_cvt_pk_bf16_f32 v58, v62, v63
	v_cvt_pk_bf16_f32 v59, v64, v65
	v_lshl_add_u64 v[62:63], v[82:83], 1, s[96:97]
	v_cvt_pk_bf16_f32 v60, v60, v61
	v_cvt_pk_bf16_f32 v61, v68, v69
	global_store_dwordx4 v[62:63], v[58:61], off sc1
	v_lshl_add_u64 v[66:67], v[142:143], 0, s[22:23]
	s_waitcnt vmcnt(1)
	v_pk_add_f32 v[56:57], v[56:57], v[80:81]
	v_pk_add_f32 v[58:59], v[52:53], v[76:77]
	v_pk_add_f32 v[52:53], v[50:51], v[74:75]
	v_pk_add_f32 v[54:55], v[54:55], v[78:79]
	s_mov_b64 s[22:23], 0xa0000
	v_cvt_pk_bf16_f32 v50, v54, v55
	v_cvt_pk_bf16_f32 v51, v56, v57
	v_cvt_pk_bf16_f32 v52, v52, v53
	v_cvt_pk_bf16_f32 v53, v58, v59
	global_store_dwordx4 v[62:63], v[50:53], off offset:256 sc1
	v_lshl_add_u64 v[62:63], v[66:67], 2, s[60:61]
	global_load_dwordx4 v[50:53], v[62:63], off offset:16
	global_load_dwordx4 v[54:57], v[62:63], off
	global_load_dwordx4 v[58:61], v[62:63], off offset:528
	s_nop 0
	global_load_dwordx4 v[62:65], v[62:63], off offset:512
	s_waitcnt vmcnt(3)
	v_pk_add_f32 v[52:53], v[44:45], v[52:53]
	s_waitcnt vmcnt(2)
	v_pk_add_f32 v[46:47], v[46:47], v[54:55]
	v_pk_add_f32 v[48:49], v[48:49], v[56:57]
	v_pk_add_f32 v[44:45], v[42:43], v[50:51]
	v_cvt_pk_bf16_f32 v42, v46, v47
	v_cvt_pk_bf16_f32 v43, v48, v49
	v_lshl_add_u64 v[46:47], v[66:67], 1, s[96:97]
	v_cvt_pk_bf16_f32 v44, v44, v45
	v_cvt_pk_bf16_f32 v45, v52, v53
	global_store_dwordx4 v[46:47], v[42:45], off sc1
	v_lshl_add_u64 v[50:51], v[142:143], 0, s[22:23]
	s_waitcnt vmcnt(1)
	v_pk_add_f32 v[40:41], v[40:41], v[64:65]
	v_pk_add_f32 v[42:43], v[36:37], v[60:61]
	v_pk_add_f32 v[36:37], v[34:35], v[58:59]
	v_pk_add_f32 v[38:39], v[38:39], v[62:63]
	s_mov_b64 s[22:23], 0xb0000
	v_cvt_pk_bf16_f32 v34, v38, v39
	v_cvt_pk_bf16_f32 v35, v40, v41
	v_cvt_pk_bf16_f32 v36, v36, v37
	v_cvt_pk_bf16_f32 v37, v42, v43
	global_store_dwordx4 v[46:47], v[34:37], off offset:256 sc1
	v_lshl_add_u64 v[46:47], v[50:51], 2, s[60:61]
	global_load_dwordx4 v[34:37], v[46:47], off offset:16
	global_load_dwordx4 v[38:41], v[46:47], off
	global_load_dwordx4 v[42:45], v[46:47], off offset:528
	s_nop 0
	global_load_dwordx4 v[46:49], v[46:47], off offset:512
	s_waitcnt vmcnt(3)
	v_pk_add_f32 v[36:37], v[28:29], v[36:37]
	s_waitcnt vmcnt(2)
	v_pk_add_f32 v[30:31], v[30:31], v[38:39]
	v_pk_add_f32 v[32:33], v[32:33], v[40:41]
	v_pk_add_f32 v[28:29], v[26:27], v[34:35]
	v_cvt_pk_bf16_f32 v26, v30, v31
	v_cvt_pk_bf16_f32 v27, v32, v33
	v_lshl_add_u64 v[30:31], v[50:51], 1, s[96:97]
	v_cvt_pk_bf16_f32 v28, v28, v29
	v_cvt_pk_bf16_f32 v29, v36, v37
	global_store_dwordx4 v[30:31], v[26:29], off sc1
	v_lshl_add_u64 v[34:35], v[142:143], 0, s[22:23]
	s_waitcnt vmcnt(1)
	v_pk_add_f32 v[24:25], v[24:25], v[48:49]
	v_pk_add_f32 v[26:27], v[20:21], v[44:45]
	v_pk_add_f32 v[20:21], v[18:19], v[42:43]
	v_pk_add_f32 v[22:23], v[22:23], v[46:47]
	s_mov_b64 s[22:23], -1
	v_cvt_pk_bf16_f32 v18, v22, v23
	v_cvt_pk_bf16_f32 v19, v24, v25
	v_cvt_pk_bf16_f32 v20, v20, v21
	v_cvt_pk_bf16_f32 v21, v26, v27
	global_store_dwordx4 v[30:31], v[18:21], off offset:256 sc1
	v_lshl_add_u64 v[30:31], v[34:35], 2, s[60:61]
	global_load_dwordx4 v[18:21], v[30:31], off offset:16
	global_load_dwordx4 v[22:25], v[30:31], off
	global_load_dwordx4 v[26:29], v[30:31], off offset:528
	s_nop 0
	global_load_dwordx4 v[30:33], v[30:31], off offset:512
	s_waitcnt vmcnt(3)
	v_pk_add_f32 v[20:21], v[12:13], v[20:21]
	s_waitcnt vmcnt(2)
	v_pk_add_f32 v[14:15], v[14:15], v[22:23]
	v_pk_add_f32 v[16:17], v[16:17], v[24:25]
	v_pk_add_f32 v[12:13], v[10:11], v[18:19]
	v_cvt_pk_bf16_f32 v10, v14, v15
	v_cvt_pk_bf16_f32 v11, v16, v17
	v_lshl_add_u64 v[14:15], v[34:35], 1, s[96:97]
	v_cvt_pk_bf16_f32 v12, v12, v13
	v_cvt_pk_bf16_f32 v13, v20, v21
	global_store_dwordx4 v[14:15], v[10:13], off sc1
	s_waitcnt vmcnt(1)
	v_pk_add_f32 v[8:9], v[8:9], v[32:33]
	v_pk_add_f32 v[6:7], v[6:7], v[30:31]
	v_pk_add_f32 v[10:11], v[4:5], v[28:29]
	v_pk_add_f32 v[4:5], v[2:3], v[26:27]
	v_cvt_pk_bf16_f32 v2, v6, v7
	v_cvt_pk_bf16_f32 v3, v8, v9
	s_nop 0
	v_cvt_pk_bf16_f32 v4, v4, v5
	v_cvt_pk_bf16_f32 v5, v10, v11
	global_store_dwordx4 v[14:15], v[2:5], off offset:256 sc1
	s_cbranch_vccnz .LBB0_1007
	s_andn2_b64 vcc, exec, s[12:13]
	s_cbranch_vccnz .LBB0_1006
	s_barrier
	s_branch .LBB0_1006

.LBB0_1019:
	s_add_i32 s21, s20, 0x100
	s_and_b64 s[18:19], s[18:19], exec
	s_cselect_b32 s19, 0, s21
	s_cselect_b32 s18, 0, 0
	s_add_u32 s22, s8, s19
	s_addc_u32 s23, s9, s18
	ds_read_b128 v[144:147], v139
	ds_read_b128 v[150:153], v139 offset:1024
	ds_read_b128 v[154:157], v139 offset:2048
	ds_read_b128 v[158:161], v139 offset:3072
	ds_read_b128 v[168:171], v140
	ds_read_b128 v[176:179], v140 offset:1024
	ds_read_b128 v[180:183], v140 offset:2048
	ds_read_b128 v[184:187], v140 offset:3072
	s_add_u32 s24, s10, s19
	s_addc_u32 s25, s11, s18
	s_add_u32 s30, s12, s20
	s_addc_u32 s31, s13, 0
	s_add_u32 s26, s24, 0x100000
	s_addc_u32 s27, s25, 0
	s_add_u32 s20, s22, 0x100000
	s_addc_u32 s21, s23, 0
	s_add_u32 s18, s24, 0x100080
	s_addc_u32 s19, s25, 0
	v_lshl_add_u64 v[172:173], s[30:31], 0, v[130:131]
	s_mov_b32 m0, s40
	v_lshl_add_u64 v[172:173], v[172:173], 0, s[14:15]
	ds_read_b128 v[188:191], v141
	ds_read_b128 v[192:195], v141 offset:1024
	ds_read_b128 v[202:205], v141 offset:2048
	ds_read_b128 v[206:209], v141 offset:3072
	ds_read_b128 v[210:213], v141 offset:4096
	ds_read_b128 v[214:217], v141 offset:5120
	ds_read_b128 v[218:221], v141 offset:6144
	ds_read_b128 v[222:225], v141 offset:7168
	global_load_lds_dwordx4 v[172:173], off
	v_lshl_add_u64 v[172:173], s[30:31], 0, v[134:135]
	v_lshl_add_u64 v[172:173], v[172:173], 0, s[14:15]
	s_mov_b32 m0, s41
	s_nop 0
	global_load_lds_dwordx4 v[172:173], off
	s_waitcnt vmcnt(8)
	s_waitcnt lgkmcnt(0)
	s_barrier
	v_mfma_f32_16x16x32_bf16 v[126:129], v[144:147], v[188:191], v[126:129]
	v_mfma_f32_16x16x32_bf16 v[126:129], v[150:153], v[192:195], v[126:129]
	v_mfma_f32_16x16x32_bf16 v[122:125], v[158:161], v[192:195], v[122:125]
	v_mfma_f32_16x16x32_bf16 v[122:125], v[154:157], v[188:191], v[122:125]
	v_mfma_f32_16x16x32_bf16 v[114:117], v[154:157], v[202:205], v[114:117]
	v_mfma_f32_16x16x32_bf16 v[114:117], v[158:161], v[206:209], v[114:117]
	v_mfma_f32_16x16x32_bf16 v[118:121], v[150:153], v[206:209], v[118:121]
	v_mfma_f32_16x16x32_bf16 v[118:121], v[144:147], v[202:205], v[118:121]
	v_mfma_f32_16x16x32_bf16 v[102:105], v[144:147], v[210:213], v[102:105]
	v_mfma_f32_16x16x32_bf16 v[102:105], v[150:153], v[214:217], v[102:105]
	v_mfma_f32_16x16x32_bf16 v[98:101], v[158:161], v[214:217], v[98:101]
	v_mfma_f32_16x16x32_bf16 v[98:101], v[154:157], v[210:213], v[98:101]
	v_mfma_f32_16x16x32_bf16 v[82:85], v[154:157], v[218:221], v[82:85]
	v_mfma_f32_16x16x32_bf16 v[82:85], v[158:161], v[222:225], v[82:85]
	v_mfma_f32_16x16x32_bf16 v[86:89], v[150:153], v[222:225], v[86:89]
	v_mfma_f32_16x16x32_bf16 v[86:89], v[144:147], v[218:221], v[86:89]
	v_mfma_f32_16x16x32_bf16 v[70:73], v[168:171], v[218:221], v[70:73]
	v_mfma_f32_16x16x32_bf16 v[70:73], v[176:179], v[222:225], v[70:73]
	v_mfma_f32_16x16x32_bf16 v[66:69], v[184:187], v[222:225], v[66:69]
	v_mfma_f32_16x16x32_bf16 v[66:69], v[180:183], v[218:221], v[66:69]
	v_mfma_f32_16x16x32_bf16 v[74:77], v[180:183], v[210:213], v[74:77]
	v_mfma_f32_16x16x32_bf16 v[74:77], v[184:187], v[214:217], v[74:77]
	v_mfma_f32_16x16x32_bf16 v[78:81], v[176:179], v[214:217], v[78:81]
	v_mfma_f32_16x16x32_bf16 v[78:81], v[168:171], v[210:213], v[78:81]
	v_mfma_f32_16x16x32_bf16 v[94:97], v[168:171], v[202:205], v[94:97]
	v_mfma_f32_16x16x32_bf16 v[94:97], v[176:179], v[206:209], v[94:97]
	v_mfma_f32_16x16x32_bf16 v[90:93], v[184:187], v[206:209], v[90:93]
	v_mfma_f32_16x16x32_bf16 v[90:93], v[180:183], v[202:205], v[90:93]
	v_mfma_f32_16x16x32_bf16 v[106:109], v[180:183], v[188:191], v[106:109]
	v_mfma_f32_16x16x32_bf16 v[106:109], v[184:187], v[192:195], v[106:109]
	v_mfma_f32_16x16x32_bf16 v[110:113], v[176:179], v[192:195], v[110:113]
	v_mfma_f32_16x16x32_bf16 v[110:113], v[168:171], v[188:191], v[110:113]
	s_barrier
	s_mov_b32 m0, s42
	v_lshl_add_u64 v[172:173], s[24:25], 0, v[132:133]
	ds_read_b128 v[188:191], v141 offset:16384
	ds_read_b128 v[192:195], v141 offset:17408
	ds_read_b128 v[202:205], v141 offset:18432
	ds_read_b128 v[206:209], v141 offset:19456
	ds_read_b128 v[210:213], v141 offset:20480
	ds_read_b128 v[214:217], v141 offset:21504
	ds_read_b128 v[218:221], v141 offset:22528
	ds_read_b128 v[222:225], v141 offset:23552
	global_load_lds_dwordx4 v[172:173], off
	v_lshl_add_u64 v[196:197], s[24:25], 0, v[136:137]
	s_mov_b32 m0, s43
	v_lshl_add_u64 v[226:227], s[26:27], 0, v[132:133]
	global_load_lds_dwordx4 v[196:197], off
	s_mov_b32 m0, s44
	v_lshl_add_u64 v[228:229], s[22:23], 0, v[134:135]
	global_load_lds_dwordx4 v[226:227], off
	v_lshl_add_u64 v[226:227], s[26:27], 0, v[136:137]
	s_mov_b32 m0, s45
	s_nop 0
	global_load_lds_dwordx4 v[226:227], off
	v_lshl_add_u64 v[226:227], s[22:23], 0, v[130:131]
	s_mov_b32 m0, s7
	s_nop 0
	global_load_lds_dwordx4 v[226:227], off
	s_mov_b32 m0, s34
	s_nop 0
	global_load_lds_dwordx4 v[228:229], off
	s_waitcnt vmcnt(8)
	s_waitcnt lgkmcnt(0)
	s_barrier
	v_mfma_f32_16x16x32_bf16 v[62:65], v[144:147], v[188:191], v[62:65]
	v_mfma_f32_16x16x32_bf16 v[62:65], v[150:153], v[192:195], v[62:65]
	v_mfma_f32_16x16x32_bf16 v[58:61], v[158:161], v[192:195], v[58:61]
	v_mfma_f32_16x16x32_bf16 v[58:61], v[154:157], v[188:191], v[58:61]
	v_mfma_f32_16x16x32_bf16 v[50:53], v[154:157], v[202:205], v[50:53]
	v_mfma_f32_16x16x32_bf16 v[50:53], v[158:161], v[206:209], v[50:53]
	v_mfma_f32_16x16x32_bf16 v[54:57], v[150:153], v[206:209], v[54:57]
	v_mfma_f32_16x16x32_bf16 v[54:57], v[144:147], v[202:205], v[54:57]
	v_mfma_f32_16x16x32_bf16 v[38:41], v[144:147], v[210:213], v[38:41]
	v_mfma_f32_16x16x32_bf16 v[38:41], v[150:153], v[214:217], v[38:41]
	v_mfma_f32_16x16x32_bf16 v[34:37], v[158:161], v[214:217], v[34:37]
	v_mfma_f32_16x16x32_bf16 v[34:37], v[154:157], v[210:213], v[34:37]
	v_mfma_f32_16x16x32_bf16 v[18:21], v[154:157], v[218:221], v[18:21]
	v_mfma_f32_16x16x32_bf16 v[18:21], v[158:161], v[222:225], v[18:21]
	v_mfma_f32_16x16x32_bf16 v[22:25], v[150:153], v[222:225], v[22:25]
	v_mfma_f32_16x16x32_bf16 v[22:25], v[144:147], v[218:221], v[22:25]
	v_mfma_f32_16x16x32_bf16 v[6:9], v[168:171], v[218:221], v[6:9]
	v_mfma_f32_16x16x32_bf16 v[6:9], v[176:179], v[222:225], v[6:9]
	v_mfma_f32_16x16x32_bf16 v[2:5], v[184:187], v[222:225], v[2:5]
	v_mfma_f32_16x16x32_bf16 v[2:5], v[180:183], v[218:221], v[2:5]
	v_mfma_f32_16x16x32_bf16 v[10:13], v[180:183], v[210:213], v[10:13]
	v_mfma_f32_16x16x32_bf16 v[10:13], v[184:187], v[214:217], v[10:13]
	v_mfma_f32_16x16x32_bf16 v[14:17], v[176:179], v[214:217], v[14:17]
	v_mfma_f32_16x16x32_bf16 v[14:17], v[168:171], v[210:213], v[14:17]
	v_mfma_f32_16x16x32_bf16 v[30:33], v[168:171], v[202:205], v[30:33]
	v_mfma_f32_16x16x32_bf16 v[30:33], v[176:179], v[206:209], v[30:33]
	v_mfma_f32_16x16x32_bf16 v[26:29], v[184:187], v[206:209], v[26:29]
	v_mfma_f32_16x16x32_bf16 v[26:29], v[180:183], v[202:205], v[26:29]
	v_mfma_f32_16x16x32_bf16 v[42:45], v[180:183], v[188:191], v[42:45]
	v_mfma_f32_16x16x32_bf16 v[42:45], v[184:187], v[192:195], v[42:45]
	v_mfma_f32_16x16x32_bf16 v[46:49], v[176:179], v[192:195], v[46:49]
	v_mfma_f32_16x16x32_bf16 v[46:49], v[168:171], v[188:191], v[46:49]
	s_barrier
	ds_read_b128 v[144:147], v142
	ds_read_b128 v[150:153], v142 offset:1024
	ds_read_b128 v[154:157], v142 offset:2048
	ds_read_b128 v[158:161], v142 offset:3072
	ds_read_b128 v[168:171], v143
	ds_read_b128 v[176:179], v143 offset:1024
	ds_read_b128 v[180:183], v143 offset:2048
	ds_read_b128 v[184:187], v143 offset:3072
	s_mov_b32 m0, s35
	v_lshl_add_u64 v[230:231], s[20:21], 0, v[130:131]
	ds_read_b128 v[188:191], v141 offset:32768
	ds_read_b128 v[192:195], v141 offset:33792
	ds_read_b128 v[202:205], v141 offset:34816
	ds_read_b128 v[206:209], v141 offset:35840
	ds_read_b128 v[210:213], v141 offset:36864
	ds_read_b128 v[214:217], v141 offset:37888
	ds_read_b128 v[218:221], v141 offset:38912
	ds_read_b128 v[222:225], v141 offset:39936
	global_load_lds_dwordx4 v[230:231], off
	v_lshl_add_u64 v[230:231], s[20:21], 0, v[134:135]
	s_mov_b32 m0, s36
	s_nop 0
	global_load_lds_dwordx4 v[230:231], off
	s_waitcnt vmcnt(8)
	s_waitcnt lgkmcnt(0)
	s_barrier
	v_mfma_f32_16x16x32_bf16 v[126:129], v[144:147], v[188:191], v[126:129]
	v_mfma_f32_16x16x32_bf16 v[126:129], v[150:153], v[192:195], v[126:129]
	v_mfma_f32_16x16x32_bf16 v[122:125], v[158:161], v[192:195], v[122:125]
	v_mfma_f32_16x16x32_bf16 v[122:125], v[154:157], v[188:191], v[122:125]
	v_mfma_f32_16x16x32_bf16 v[114:117], v[154:157], v[202:205], v[114:117]
	v_mfma_f32_16x16x32_bf16 v[114:117], v[158:161], v[206:209], v[114:117]
	v_mfma_f32_16x16x32_bf16 v[118:121], v[150:153], v[206:209], v[118:121]
	v_mfma_f32_16x16x32_bf16 v[118:121], v[144:147], v[202:205], v[118:121]
	v_mfma_f32_16x16x32_bf16 v[102:105], v[144:147], v[210:213], v[102:105]
	v_mfma_f32_16x16x32_bf16 v[102:105], v[150:153], v[214:217], v[102:105]
	v_mfma_f32_16x16x32_bf16 v[98:101], v[158:161], v[214:217], v[98:101]
	v_mfma_f32_16x16x32_bf16 v[98:101], v[154:157], v[210:213], v[98:101]
	v_mfma_f32_16x16x32_bf16 v[82:85], v[154:157], v[218:221], v[82:85]
	v_mfma_f32_16x16x32_bf16 v[82:85], v[158:161], v[222:225], v[82:85]
	v_mfma_f32_16x16x32_bf16 v[86:89], v[150:153], v[222:225], v[86:89]
	v_mfma_f32_16x16x32_bf16 v[86:89], v[144:147], v[218:221], v[86:89]
	v_mfma_f32_16x16x32_bf16 v[70:73], v[168:171], v[218:221], v[70:73]
	v_mfma_f32_16x16x32_bf16 v[70:73], v[176:179], v[222:225], v[70:73]
	v_mfma_f32_16x16x32_bf16 v[66:69], v[184:187], v[222:225], v[66:69]
	v_mfma_f32_16x16x32_bf16 v[66:69], v[180:183], v[218:221], v[66:69]
	v_mfma_f32_16x16x32_bf16 v[74:77], v[180:183], v[210:213], v[74:77]
	v_mfma_f32_16x16x32_bf16 v[74:77], v[184:187], v[214:217], v[74:77]
	v_mfma_f32_16x16x32_bf16 v[78:81], v[176:179], v[214:217], v[78:81]
	v_mfma_f32_16x16x32_bf16 v[78:81], v[168:171], v[210:213], v[78:81]
	v_mfma_f32_16x16x32_bf16 v[94:97], v[168:171], v[202:205], v[94:97]
	v_mfma_f32_16x16x32_bf16 v[94:97], v[176:179], v[206:209], v[94:97]
	v_mfma_f32_16x16x32_bf16 v[90:93], v[184:187], v[206:209], v[90:93]
	v_mfma_f32_16x16x32_bf16 v[90:93], v[180:183], v[202:205], v[90:93]
	v_mfma_f32_16x16x32_bf16 v[106:109], v[180:183], v[188:191], v[106:109]
	v_mfma_f32_16x16x32_bf16 v[106:109], v[184:187], v[192:195], v[106:109]
	v_mfma_f32_16x16x32_bf16 v[110:113], v[176:179], v[192:195], v[110:113]
	v_mfma_f32_16x16x32_bf16 v[110:113], v[168:171], v[188:191], v[110:113]
	s_barrier
	s_mov_b32 m0, s46
	v_lshl_add_u64 v[172:173], v[172:173], 0, s[14:15]
	ds_read_b128 v[188:191], v141 offset:49152
	ds_read_b128 v[192:195], v141 offset:50176
	ds_read_b128 v[202:205], v141 offset:51200
	ds_read_b128 v[206:209], v141 offset:52224
	ds_read_b128 v[210:213], v141 offset:53248
	ds_read_b128 v[214:217], v141 offset:54272
	ds_read_b128 v[218:221], v141 offset:55296
	ds_read_b128 v[222:225], v141 offset:56320
	global_load_lds_dwordx4 v[172:173], off
	v_lshl_add_u64 v[172:173], v[196:197], 0, s[14:15]
	s_mov_b32 m0, s47
	s_nop 0
	global_load_lds_dwordx4 v[172:173], off
	v_lshl_add_u64 v[172:173], s[18:19], 0, v[132:133]
	s_mov_b32 m0, s48
	s_nop 0
	global_load_lds_dwordx4 v[172:173], off
	v_lshl_add_u64 v[172:173], s[18:19], 0, v[136:137]
	s_mov_b32 m0, s49
	s_nop 0
	global_load_lds_dwordx4 v[172:173], off
	v_lshl_add_u64 v[172:173], v[226:227], 0, s[14:15]
	s_mov_b32 m0, s38
	s_nop 0
	global_load_lds_dwordx4 v[172:173], off
	v_lshl_add_u64 v[172:173], v[228:229], 0, s[14:15]
	s_mov_b32 m0, s39
	s_nop 0
	global_load_lds_dwordx4 v[172:173], off
	s_waitcnt vmcnt(8)
	s_waitcnt lgkmcnt(0)
	s_barrier
	v_mfma_f32_16x16x32_bf16 v[62:65], v[144:147], v[188:191], v[62:65]
	v_mfma_f32_16x16x32_bf16 v[62:65], v[150:153], v[192:195], v[62:65]
	v_mfma_f32_16x16x32_bf16 v[58:61], v[158:161], v[192:195], v[58:61]
	v_mfma_f32_16x16x32_bf16 v[58:61], v[154:157], v[188:191], v[58:61]
	v_mfma_f32_16x16x32_bf16 v[50:53], v[154:157], v[202:205], v[50:53]
	v_mfma_f32_16x16x32_bf16 v[50:53], v[158:161], v[206:209], v[50:53]
	v_mfma_f32_16x16x32_bf16 v[54:57], v[150:153], v[206:209], v[54:57]
	v_mfma_f32_16x16x32_bf16 v[54:57], v[144:147], v[202:205], v[54:57]
	v_mfma_f32_16x16x32_bf16 v[38:41], v[144:147], v[210:213], v[38:41]
	v_mfma_f32_16x16x32_bf16 v[38:41], v[150:153], v[214:217], v[38:41]
	v_mfma_f32_16x16x32_bf16 v[34:37], v[158:161], v[214:217], v[34:37]
	v_mfma_f32_16x16x32_bf16 v[34:37], v[154:157], v[210:213], v[34:37]
	v_mfma_f32_16x16x32_bf16 v[18:21], v[154:157], v[218:221], v[18:21]
	v_mfma_f32_16x16x32_bf16 v[18:21], v[158:161], v[222:225], v[18:21]
	v_mfma_f32_16x16x32_bf16 v[22:25], v[150:153], v[222:225], v[22:25]
	v_mfma_f32_16x16x32_bf16 v[22:25], v[144:147], v[218:221], v[22:25]
	v_mfma_f32_16x16x32_bf16 v[6:9], v[168:171], v[218:221], v[6:9]
	v_mfma_f32_16x16x32_bf16 v[6:9], v[176:179], v[222:225], v[6:9]
	v_mfma_f32_16x16x32_bf16 v[2:5], v[184:187], v[222:225], v[2:5]
	v_mfma_f32_16x16x32_bf16 v[2:5], v[180:183], v[218:221], v[2:5]
	v_mfma_f32_16x16x32_bf16 v[10:13], v[180:183], v[210:213], v[10:13]
	v_mfma_f32_16x16x32_bf16 v[10:13], v[184:187], v[214:217], v[10:13]
	v_mfma_f32_16x16x32_bf16 v[14:17], v[176:179], v[214:217], v[14:17]
	v_mfma_f32_16x16x32_bf16 v[14:17], v[168:171], v[210:213], v[14:17]
	v_mfma_f32_16x16x32_bf16 v[30:33], v[168:171], v[202:205], v[30:33]
	v_mfma_f32_16x16x32_bf16 v[30:33], v[176:179], v[206:209], v[30:33]
	v_mfma_f32_16x16x32_bf16 v[26:29], v[184:187], v[206:209], v[26:29]
	v_mfma_f32_16x16x32_bf16 v[26:29], v[180:183], v[202:205], v[26:29]
	v_mfma_f32_16x16x32_bf16 v[42:45], v[180:183], v[188:191], v[42:45]
	v_mfma_f32_16x16x32_bf16 v[42:45], v[184:187], v[192:195], v[42:45]
	v_mfma_f32_16x16x32_bf16 v[46:49], v[176:179], v[192:195], v[46:49]
	v_mfma_f32_16x16x32_bf16 v[46:49], v[168:171], v[188:191], v[46:49]
	s_barrier
	s_andn2_b64 vcc, exec, s[16:17]
	s_mov_b64 s[18:19], -1
	s_mov_b64 s[16:17], 0
	s_movk_i32 s20, 0x100
	s_cbranch_vccz .LBB0_1019
	s_lshl_b32 s7, s33, 21
	v_readlane_b32 s0, v249, 29
	v_lshl_or_b32 v130, s6, 8, v148
	v_mov_b32_e32 v139, 0
	s_add_u32 s8, s0, s7
	v_readlane_b32 s0, v249, 31
	v_or_b32_e32 v130, s37, v130
	v_cvt_pk_bf16_f32 v70, v70, v71
	v_cvt_pk_bf16_f32 v71, v72, v73
	v_cvt_pk_bf16_f32 v72, v66, v67
	v_add_u32_e32 v66, 0x80, v138
	v_mov_b32_e32 v67, v139
	s_addc_u32 s9, s0, 0
	v_ashrrev_i32_e32 v131, 31, v130
	v_lshlrev_b64 v[132:133], 13, v[138:139]
	v_cvt_pk_bf16_f32 v110, v110, v111
	v_cvt_pk_bf16_f32 v111, v112, v113
	v_cvt_pk_bf16_f32 v112, v106, v107
	v_or_b32_e32 v106, 16, v138
	v_mov_b32_e32 v107, v139
	v_lshlrev_b64 v[66:67], 13, v[66:67]
	v_cvt_pk_bf16_f32 v46, v46, v47
	v_cvt_pk_bf16_f32 v47, v48, v49
	v_cvt_pk_bf16_f32 v48, v42, v43
	v_add_u32_e32 v42, 0x90, v138
	v_mov_b32_e32 v43, v139
	v_lshl_add_u64 v[132:133], s[8:9], 0, v[132:133]
	v_lshlrev_b64 v[130:131], 1, v[130:131]
	v_lshlrev_b64 v[106:107], 13, v[106:107]
	v_cvt_pk_bf16_f32 v94, v94, v95
	v_cvt_pk_bf16_f32 v95, v96, v97
	v_cvt_pk_bf16_f32 v96, v90, v91
	v_or_b32_e32 v90, 32, v138
	v_mov_b32_e32 v91, v139
	v_lshl_add_u64 v[66:67], s[8:9], 0, v[66:67]
	v_lshlrev_b64 v[42:43], 13, v[42:43]
	v_cvt_pk_bf16_f32 v30, v30, v31
	v_cvt_pk_bf16_f32 v31, v32, v33
	v_cvt_pk_bf16_f32 v32, v26, v27
	v_add_u32_e32 v26, 0xa0, v138
	v_mov_b32_e32 v27, v139
	v_lshl_add_u64 v[132:133], v[132:133], 0, v[130:131]
	v_cvt_pk_bf16_f32 v113, v108, v109
	v_lshl_add_u64 v[106:107], s[8:9], 0, v[106:107]
	v_lshlrev_b64 v[90:91], 13, v[90:91]
	v_cvt_pk_bf16_f32 v78, v78, v79
	v_cvt_pk_bf16_f32 v79, v80, v81
	v_cvt_pk_bf16_f32 v80, v74, v75
	v_or_b32_e32 v74, 48, v138
	v_mov_b32_e32 v75, v139
	v_lshl_add_u64 v[66:67], v[66:67], 0, v[130:131]
	v_cvt_pk_bf16_f32 v49, v44, v45
	v_lshl_add_u64 v[42:43], s[8:9], 0, v[42:43]
	v_lshlrev_b64 v[26:27], 13, v[26:27]
	v_add_u32_e32 v138, 0xb0, v138
	global_store_dwordx4 v[132:133], v[110:113], off offset:256 sc1
	v_cvt_pk_bf16_f32 v97, v92, v93
	v_lshl_add_u64 v[90:91], s[8:9], 0, v[90:91]
	v_lshl_add_u64 v[110:111], v[106:107], 0, v[130:131]
	v_lshlrev_b64 v[74:75], 13, v[74:75]
	global_store_dwordx4 v[66:67], v[46:49], off offset:256 sc1
	v_cvt_pk_bf16_f32 v33, v28, v29
	v_lshl_add_u64 v[26:27], s[8:9], 0, v[26:27]
	v_lshl_add_u64 v[46:47], v[42:43], 0, v[130:131]
	v_cvt_pk_bf16_f32 v14, v14, v15
	v_cvt_pk_bf16_f32 v15, v16, v17
	v_cvt_pk_bf16_f32 v16, v10, v11
	v_lshlrev_b64 v[10:11], 13, v[138:139]
	global_store_dwordx4 v[110:111], v[94:97], off offset:256 sc1
	v_cvt_pk_bf16_f32 v81, v76, v77
	v_lshl_add_u64 v[74:75], s[8:9], 0, v[74:75]
	v_lshl_add_u64 v[94:95], v[90:91], 0, v[130:131]
	global_store_dwordx4 v[46:47], v[30:33], off offset:256 sc1
	v_cvt_pk_bf16_f32 v17, v12, v13
	v_lshl_add_u64 v[10:11], s[8:9], 0, v[10:11]
	v_lshl_add_u64 v[30:31], v[26:27], 0, v[130:131]
	v_cvt_pk_bf16_f32 v126, v126, v127
	v_cvt_pk_bf16_f32 v127, v128, v129
	v_cvt_pk_bf16_f32 v128, v122, v123
	v_cvt_pk_bf16_f32 v129, v124, v125
	v_cvt_pk_bf16_f32 v106, v118, v119
	v_cvt_pk_bf16_f32 v107, v120, v121
	v_cvt_pk_bf16_f32 v108, v114, v115
	v_cvt_pk_bf16_f32 v109, v116, v117
	v_cvt_pk_bf16_f32 v90, v102, v103
	v_cvt_pk_bf16_f32 v91, v104, v105
	v_cvt_pk_bf16_f32 v92, v98, v99
	v_cvt_pk_bf16_f32 v93, v100, v101
	global_store_dwordx4 v[94:95], v[78:81], off offset:256 sc1
	v_cvt_pk_bf16_f32 v76, v82, v83
	v_cvt_pk_bf16_f32 v77, v84, v85
	v_lshl_add_u64 v[78:79], v[74:75], 0, v[130:131]
	v_cvt_pk_bf16_f32 v74, v86, v87
	v_cvt_pk_bf16_f32 v75, v88, v89
	v_cvt_pk_bf16_f32 v73, v68, v69
	v_cvt_pk_bf16_f32 v62, v62, v63
	v_cvt_pk_bf16_f32 v63, v64, v65
	v_cvt_pk_bf16_f32 v64, v58, v59
	v_cvt_pk_bf16_f32 v65, v60, v61
	v_cvt_pk_bf16_f32 v42, v54, v55
	v_cvt_pk_bf16_f32 v43, v56, v57
	v_cvt_pk_bf16_f32 v44, v50, v51
	v_cvt_pk_bf16_f32 v45, v52, v53
	v_cvt_pk_bf16_f32 v26, v38, v39
	v_cvt_pk_bf16_f32 v27, v40, v41
	v_cvt_pk_bf16_f32 v28, v34, v35
	v_cvt_pk_bf16_f32 v29, v36, v37
	global_store_dwordx4 v[30:31], v[14:17], off offset:256 sc1
	v_cvt_pk_bf16_f32 v12, v18, v19
	v_cvt_pk_bf16_f32 v13, v20, v21
	v_lshl_add_u64 v[14:15], v[10:11], 0, v[130:131]
	v_cvt_pk_bf16_f32 v10, v22, v23
	v_cvt_pk_bf16_f32 v11, v24, v25
	v_cvt_pk_bf16_f32 v6, v6, v7
	v_cvt_pk_bf16_f32 v7, v8, v9
	v_cvt_pk_bf16_f32 v8, v2, v3
	v_cvt_pk_bf16_f32 v9, v4, v5
	global_store_dwordx4 v[132:133], v[126:129], off sc1
	global_store_dwordx4 v[110:111], v[106:109], off sc1
	global_store_dwordx4 v[94:95], v[90:93], off sc1
	global_store_dwordx4 v[78:79], v[74:77], off sc1
	global_store_dwordx4 v[78:79], v[70:73], off offset:256 sc1
	global_store_dwordx4 v[66:67], v[62:65], off sc1
	global_store_dwordx4 v[46:47], v[42:45], off sc1
	global_store_dwordx4 v[30:31], v[26:29], off sc1
	global_store_dwordx4 v[14:15], v[10:13], off sc1
	global_store_dwordx4 v[14:15], v[6:9], off offset:256 sc1
	s_waitcnt vmcnt(0)
	s_cmpk_lt_u32 s3, 0x100
	s_cbranch_scc0 .LBB0_1022
	s_barrier

.LBB0_1175:
	v_readlane_b32 s0, v249, 6
	v_lshl_or_b32 v144, s52, 7, v147
	v_readlane_b32 s1, v249, 7
	v_lshl_add_u32 v153, s53, 8, v146
	v_ashrrev_i32_e32 v145, 31, v144
	v_mov_b64_e32 v[142:143], s[0:1]
	v_mad_u64_u32 v[154:155], s[20:21], v153, s41, v[142:143]
	v_lshlrev_b64 v[144:145], 1, v[144:145]
	v_lshl_add_u64 v[154:155], v[154:155], 0, v[144:145]
	v_mov_b32_e32 v192, 0xbfb8aa3b
	v_mov_b32_e32 v193, 0xbfb8aa3b
	v_mov_b32_e32 v194, 1.0
	v_mov_b32_e32 v195, 1.0
	s_mov_b64 s[22:23], 0x56000
	s_mov_b64 s[24:25], 0x1ae000
	v_pk_mul_f32 v[176:177], v[126:127], v[192:193]
	v_pk_mul_f32 v[178:179], v[128:129], v[192:193]
	v_pk_mul_f32 v[180:181], v[118:119], v[192:193]
	v_pk_mul_f32 v[182:183], v[120:121], v[192:193]
	v_exp_f32_e32 v176, v176
	v_exp_f32_e32 v177, v177
	v_exp_f32_e32 v178, v178
	v_exp_f32_e32 v179, v179
	v_exp_f32_e32 v180, v180
	v_exp_f32_e32 v181, v181
	v_exp_f32_e32 v182, v182
	v_exp_f32_e32 v183, v183
	v_pk_add_f32 v[176:177], v[176:177], v[194:195]
	v_pk_add_f32 v[178:179], v[178:179], v[194:195]
	v_pk_add_f32 v[180:181], v[180:181], v[194:195]
	v_pk_add_f32 v[182:183], v[182:183], v[194:195]
	v_rcp_f32_e32 v176, v176
	v_rcp_f32_e32 v177, v177
	v_rcp_f32_e32 v178, v178
	v_rcp_f32_e32 v179, v179
	v_rcp_f32_e32 v180, v180
	v_rcp_f32_e32 v181, v181
	v_rcp_f32_e32 v182, v182
	v_rcp_f32_e32 v183, v183
	v_lshl_add_u64 v[156:157], v[154:155], 0, s[22:23]
	v_pk_mul_f32 v[126:127], v[126:127], v[176:177]
	v_pk_mul_f32 v[128:129], v[128:129], v[178:179]
	v_pk_mul_f32 v[118:119], v[118:119], v[180:181]
	v_pk_mul_f32 v[120:121], v[120:121], v[182:183]
	v_pk_mul_f32 v[126:127], v[126:127], v[122:123]
	v_pk_mul_f32 v[128:129], v[128:129], v[124:125]
	v_pk_mul_f32 v[118:119], v[118:119], v[114:115]
	v_pk_mul_f32 v[120:121], v[120:121], v[116:117]
	v_cvt_pk_bf16_f32 v184, v126, v127
	v_cvt_pk_bf16_f32 v185, v128, v129
	v_cvt_pk_bf16_f32 v186, v118, v119
	v_cvt_pk_bf16_f32 v187, v120, v121
	global_store_dwordx4 v[154:155], v[184:187], off sc1
	v_pk_mul_f32 v[176:177], v[110:111], v[192:193]
	v_pk_mul_f32 v[178:179], v[112:113], v[192:193]
	v_pk_mul_f32 v[180:181], v[102:103], v[192:193]
	v_pk_mul_f32 v[182:183], v[104:105], v[192:193]
	v_exp_f32_e32 v176, v176
	v_exp_f32_e32 v177, v177
	v_exp_f32_e32 v178, v178
	v_exp_f32_e32 v179, v179
	v_exp_f32_e32 v180, v180
	v_exp_f32_e32 v181, v181
	v_exp_f32_e32 v182, v182
	v_exp_f32_e32 v183, v183
	v_pk_add_f32 v[176:177], v[176:177], v[194:195]
	v_pk_add_f32 v[178:179], v[178:179], v[194:195]
	v_pk_add_f32 v[180:181], v[180:181], v[194:195]
	v_pk_add_f32 v[182:183], v[182:183], v[194:195]
	v_rcp_f32_e32 v176, v176
	v_rcp_f32_e32 v177, v177
	v_rcp_f32_e32 v178, v178
	v_rcp_f32_e32 v179, v179
	v_rcp_f32_e32 v180, v180
	v_rcp_f32_e32 v181, v181
	v_rcp_f32_e32 v182, v182
	v_rcp_f32_e32 v183, v183
	v_lshl_add_u64 v[154:155], v[156:157], 0, s[22:23]
	v_pk_mul_f32 v[110:111], v[110:111], v[176:177]
	v_pk_mul_f32 v[112:113], v[112:113], v[178:179]
	v_pk_mul_f32 v[102:103], v[102:103], v[180:181]
	v_pk_mul_f32 v[104:105], v[104:105], v[182:183]
	v_pk_mul_f32 v[110:111], v[110:111], v[106:107]
	v_pk_mul_f32 v[112:113], v[112:113], v[108:109]
	v_pk_mul_f32 v[102:103], v[102:103], v[98:99]
	v_pk_mul_f32 v[104:105], v[104:105], v[100:101]
	v_cvt_pk_bf16_f32 v188, v110, v111
	v_cvt_pk_bf16_f32 v189, v112, v113
	v_cvt_pk_bf16_f32 v190, v102, v103
	v_cvt_pk_bf16_f32 v191, v104, v105
	global_store_dwordx4 v[156:157], v[188:191], off sc1
	v_pk_mul_f32 v[176:177], v[94:95], v[192:193]
	v_pk_mul_f32 v[178:179], v[96:97], v[192:193]
	v_pk_mul_f32 v[180:181], v[86:87], v[192:193]
	v_pk_mul_f32 v[182:183], v[88:89], v[192:193]
	v_exp_f32_e32 v176, v176
	v_exp_f32_e32 v177, v177
	v_exp_f32_e32 v178, v178
	v_exp_f32_e32 v179, v179
	v_exp_f32_e32 v180, v180
	v_exp_f32_e32 v181, v181
	v_exp_f32_e32 v182, v182
	v_exp_f32_e32 v183, v183
	v_pk_add_f32 v[176:177], v[176:177], v[194:195]
	v_pk_add_f32 v[178:179], v[178:179], v[194:195]
	v_pk_add_f32 v[180:181], v[180:181], v[194:195]
	v_pk_add_f32 v[182:183], v[182:183], v[194:195]
	v_rcp_f32_e32 v176, v176
	v_rcp_f32_e32 v177, v177
	v_rcp_f32_e32 v178, v178
	v_rcp_f32_e32 v179, v179
	v_rcp_f32_e32 v180, v180
	v_rcp_f32_e32 v181, v181
	v_rcp_f32_e32 v182, v182
	v_rcp_f32_e32 v183, v183
	v_lshl_add_u64 v[156:157], v[154:155], 0, s[22:23]
	v_pk_mul_f32 v[94:95], v[94:95], v[176:177]
	v_pk_mul_f32 v[96:97], v[96:97], v[178:179]
	v_pk_mul_f32 v[86:87], v[86:87], v[180:181]
	v_pk_mul_f32 v[88:89], v[88:89], v[182:183]
	v_pk_mul_f32 v[94:95], v[94:95], v[90:91]
	v_pk_mul_f32 v[96:97], v[96:97], v[92:93]
	v_pk_mul_f32 v[86:87], v[86:87], v[82:83]
	v_pk_mul_f32 v[88:89], v[88:89], v[84:85]
	v_cvt_pk_bf16_f32 v184, v94, v95
	v_cvt_pk_bf16_f32 v185, v96, v97
	v_cvt_pk_bf16_f32 v186, v86, v87
	v_cvt_pk_bf16_f32 v187, v88, v89
	global_store_dwordx4 v[154:155], v[184:187], off sc1
	v_pk_mul_f32 v[176:177], v[78:79], v[192:193]
	v_pk_mul_f32 v[178:179], v[80:81], v[192:193]
	v_pk_mul_f32 v[180:181], v[70:71], v[192:193]
	v_pk_mul_f32 v[182:183], v[72:73], v[192:193]
	v_exp_f32_e32 v176, v176
	v_exp_f32_e32 v177, v177
	v_exp_f32_e32 v178, v178
	v_exp_f32_e32 v179, v179
	v_exp_f32_e32 v180, v180
	v_exp_f32_e32 v181, v181
	v_exp_f32_e32 v182, v182
	v_exp_f32_e32 v183, v183
	v_pk_add_f32 v[176:177], v[176:177], v[194:195]
	v_pk_add_f32 v[178:179], v[178:179], v[194:195]
	v_pk_add_f32 v[180:181], v[180:181], v[194:195]
	v_pk_add_f32 v[182:183], v[182:183], v[194:195]
	v_rcp_f32_e32 v176, v176
	v_rcp_f32_e32 v177, v177
	v_rcp_f32_e32 v178, v178
	v_rcp_f32_e32 v179, v179
	v_rcp_f32_e32 v180, v180
	v_rcp_f32_e32 v181, v181
	v_rcp_f32_e32 v182, v182
	v_rcp_f32_e32 v183, v183
	v_lshl_add_u64 v[154:155], v[156:157], 0, s[24:25]
	v_pk_mul_f32 v[78:79], v[78:79], v[176:177]
	v_pk_mul_f32 v[80:81], v[80:81], v[178:179]
	v_pk_mul_f32 v[70:71], v[70:71], v[180:181]
	v_pk_mul_f32 v[72:73], v[72:73], v[182:183]
	v_pk_mul_f32 v[78:79], v[78:79], v[74:75]
	v_pk_mul_f32 v[80:81], v[80:81], v[76:77]
	v_pk_mul_f32 v[70:71], v[70:71], v[66:67]
	v_pk_mul_f32 v[72:73], v[72:73], v[68:69]
	v_cvt_pk_bf16_f32 v188, v78, v79
	v_cvt_pk_bf16_f32 v189, v80, v81
	v_cvt_pk_bf16_f32 v190, v70, v71
	v_cvt_pk_bf16_f32 v191, v72, v73
	global_store_dwordx4 v[156:157], v[188:191], off sc1
	v_pk_mul_f32 v[176:177], v[62:63], v[192:193]
	v_pk_mul_f32 v[178:179], v[64:65], v[192:193]
	v_pk_mul_f32 v[180:181], v[54:55], v[192:193]
	v_pk_mul_f32 v[182:183], v[56:57], v[192:193]
	v_exp_f32_e32 v176, v176
	v_exp_f32_e32 v177, v177
	v_exp_f32_e32 v178, v178
	v_exp_f32_e32 v179, v179
	v_exp_f32_e32 v180, v180
	v_exp_f32_e32 v181, v181
	v_exp_f32_e32 v182, v182
	v_exp_f32_e32 v183, v183
	v_pk_add_f32 v[176:177], v[176:177], v[194:195]
	v_pk_add_f32 v[178:179], v[178:179], v[194:195]
	v_pk_add_f32 v[180:181], v[180:181], v[194:195]
	v_pk_add_f32 v[182:183], v[182:183], v[194:195]
	v_rcp_f32_e32 v176, v176
	v_rcp_f32_e32 v177, v177
	v_rcp_f32_e32 v178, v178
	v_rcp_f32_e32 v179, v179
	v_rcp_f32_e32 v180, v180
	v_rcp_f32_e32 v181, v181
	v_rcp_f32_e32 v182, v182
	v_rcp_f32_e32 v183, v183
	v_lshl_add_u64 v[156:157], v[154:155], 0, s[22:23]
	v_pk_mul_f32 v[62:63], v[62:63], v[176:177]
	v_pk_mul_f32 v[64:65], v[64:65], v[178:179]
	v_pk_mul_f32 v[54:55], v[54:55], v[180:181]
	v_pk_mul_f32 v[56:57], v[56:57], v[182:183]
	v_pk_mul_f32 v[62:63], v[62:63], v[58:59]
	v_pk_mul_f32 v[64:65], v[64:65], v[60:61]
	v_pk_mul_f32 v[54:55], v[54:55], v[50:51]
	v_pk_mul_f32 v[56:57], v[56:57], v[52:53]
	v_cvt_pk_bf16_f32 v184, v62, v63
	v_cvt_pk_bf16_f32 v185, v64, v65
	v_cvt_pk_bf16_f32 v186, v54, v55
	v_cvt_pk_bf16_f32 v187, v56, v57
	global_store_dwordx4 v[154:155], v[184:187], off sc1
	v_pk_mul_f32 v[176:177], v[46:47], v[192:193]
	v_pk_mul_f32 v[178:179], v[48:49], v[192:193]
	v_pk_mul_f32 v[180:181], v[38:39], v[192:193]
	v_pk_mul_f32 v[182:183], v[40:41], v[192:193]
	v_exp_f32_e32 v176, v176
	v_exp_f32_e32 v177, v177
	v_exp_f32_e32 v178, v178
	v_exp_f32_e32 v179, v179
	v_exp_f32_e32 v180, v180
	v_exp_f32_e32 v181, v181
	v_exp_f32_e32 v182, v182
	v_exp_f32_e32 v183, v183
	v_pk_add_f32 v[176:177], v[176:177], v[194:195]
	v_pk_add_f32 v[178:179], v[178:179], v[194:195]
	v_pk_add_f32 v[180:181], v[180:181], v[194:195]
	v_pk_add_f32 v[182:183], v[182:183], v[194:195]
	v_rcp_f32_e32 v176, v176
	v_rcp_f32_e32 v177, v177
	v_rcp_f32_e32 v178, v178
	v_rcp_f32_e32 v179, v179
	v_rcp_f32_e32 v180, v180
	v_rcp_f32_e32 v181, v181
	v_rcp_f32_e32 v182, v182
	v_rcp_f32_e32 v183, v183
	v_lshl_add_u64 v[154:155], v[156:157], 0, s[22:23]
	v_pk_mul_f32 v[46:47], v[46:47], v[176:177]
	v_pk_mul_f32 v[48:49], v[48:49], v[178:179]
	v_pk_mul_f32 v[38:39], v[38:39], v[180:181]
	v_pk_mul_f32 v[40:41], v[40:41], v[182:183]
	v_pk_mul_f32 v[46:47], v[46:47], v[42:43]
	v_pk_mul_f32 v[48:49], v[48:49], v[44:45]
	v_pk_mul_f32 v[38:39], v[38:39], v[34:35]
	v_pk_mul_f32 v[40:41], v[40:41], v[36:37]
	v_cvt_pk_bf16_f32 v188, v46, v47
	v_cvt_pk_bf16_f32 v189, v48, v49
	v_cvt_pk_bf16_f32 v190, v38, v39
	v_cvt_pk_bf16_f32 v191, v40, v41
	global_store_dwordx4 v[156:157], v[188:191], off sc1
	v_pk_mul_f32 v[176:177], v[30:31], v[192:193]
	v_pk_mul_f32 v[178:179], v[32:33], v[192:193]
	v_pk_mul_f32 v[180:181], v[22:23], v[192:193]
	v_pk_mul_f32 v[182:183], v[24:25], v[192:193]
	v_exp_f32_e32 v176, v176
	v_exp_f32_e32 v177, v177
	v_exp_f32_e32 v178, v178
	v_exp_f32_e32 v179, v179
	v_exp_f32_e32 v180, v180
	v_exp_f32_e32 v181, v181
	v_exp_f32_e32 v182, v182
	v_exp_f32_e32 v183, v183
	v_pk_add_f32 v[176:177], v[176:177], v[194:195]
	v_pk_add_f32 v[178:179], v[178:179], v[194:195]
	v_pk_add_f32 v[180:181], v[180:181], v[194:195]
	v_pk_add_f32 v[182:183], v[182:183], v[194:195]
	v_rcp_f32_e32 v176, v176
	v_rcp_f32_e32 v177, v177
	v_rcp_f32_e32 v178, v178
	v_rcp_f32_e32 v179, v179
	v_rcp_f32_e32 v180, v180
	v_rcp_f32_e32 v181, v181
	v_rcp_f32_e32 v182, v182
	v_rcp_f32_e32 v183, v183
	v_lshl_add_u64 v[156:157], v[154:155], 0, s[22:23]
	v_pk_mul_f32 v[30:31], v[30:31], v[176:177]
	v_pk_mul_f32 v[32:33], v[32:33], v[178:179]
	v_pk_mul_f32 v[22:23], v[22:23], v[180:181]
	v_pk_mul_f32 v[24:25], v[24:25], v[182:183]
	v_pk_mul_f32 v[30:31], v[30:31], v[26:27]
	v_pk_mul_f32 v[32:33], v[32:33], v[28:29]
	v_pk_mul_f32 v[22:23], v[22:23], v[18:19]
	v_pk_mul_f32 v[24:25], v[24:25], v[20:21]
	v_cvt_pk_bf16_f32 v184, v30, v31
	v_cvt_pk_bf16_f32 v185, v32, v33
	v_cvt_pk_bf16_f32 v186, v22, v23
	v_cvt_pk_bf16_f32 v187, v24, v25
	global_store_dwordx4 v[154:155], v[184:187], off sc1
	v_pk_mul_f32 v[176:177], v[14:15], v[192:193]
	v_pk_mul_f32 v[178:179], v[16:17], v[192:193]
	v_pk_mul_f32 v[180:181], v[6:7], v[192:193]
	v_pk_mul_f32 v[182:183], v[8:9], v[192:193]
	v_exp_f32_e32 v176, v176
	v_exp_f32_e32 v177, v177
	v_exp_f32_e32 v178, v178
	v_exp_f32_e32 v179, v179
	v_exp_f32_e32 v180, v180
	v_exp_f32_e32 v181, v181
	v_exp_f32_e32 v182, v182
	v_exp_f32_e32 v183, v183
	v_pk_add_f32 v[176:177], v[176:177], v[194:195]
	v_pk_add_f32 v[178:179], v[178:179], v[194:195]
	v_pk_add_f32 v[180:181], v[180:181], v[194:195]
	v_pk_add_f32 v[182:183], v[182:183], v[194:195]
	v_rcp_f32_e32 v176, v176
	v_rcp_f32_e32 v177, v177
	v_rcp_f32_e32 v178, v178
	v_rcp_f32_e32 v179, v179
	v_rcp_f32_e32 v180, v180
	v_rcp_f32_e32 v181, v181
	v_rcp_f32_e32 v182, v182
	v_rcp_f32_e32 v183, v183
	s_nop 0
	v_pk_mul_f32 v[14:15], v[14:15], v[176:177]
	v_pk_mul_f32 v[16:17], v[16:17], v[178:179]
	v_pk_mul_f32 v[6:7], v[6:7], v[180:181]
	v_pk_mul_f32 v[8:9], v[8:9], v[182:183]
	v_pk_mul_f32 v[14:15], v[14:15], v[10:11]
	v_pk_mul_f32 v[16:17], v[16:17], v[12:13]
	v_pk_mul_f32 v[6:7], v[6:7], v[2:3]
	v_pk_mul_f32 v[8:9], v[8:9], v[4:5]
	v_cvt_pk_bf16_f32 v188, v14, v15
	v_cvt_pk_bf16_f32 v189, v16, v17
	v_cvt_pk_bf16_f32 v190, v6, v7
	v_cvt_pk_bf16_f32 v191, v8, v9
	global_store_dwordx4 v[156:157], v[188:191], off sc1
	v_readlane_b32 s60, v250, 50
	v_readlane_b32 s72, v250, 62
	v_readlane_b32 s73, v250, 63
	v_readlane_b32 s74, v249, 0
	v_readlane_b32 s75, v249, 1
	v_readlane_b32 s61, v250, 51
	v_readlane_b32 s62, v250, 52
	v_readlane_b32 s63, v250, 53
	v_readlane_b32 s64, v250, 54
	v_readlane_b32 s65, v250, 55
	v_readlane_b32 s66, v250, 56
	v_readlane_b32 s67, v250, 57
	v_readlane_b32 s68, v250, 58
	v_readlane_b32 s69, v250, 59
	v_readlane_b32 s70, v250, 60
	v_readlane_b32 s71, v250, 61
	s_andn2_b64 vcc, exec, s[18:19]
	s_mov_b64 s[20:21], -1
	s_cbranch_vccnz .LBB0_1170
	s_andn2_b64 vcc, exec, s[12:13]
	s_cbranch_vccnz .LBB0_1169
	s_barrier
	s_branch .LBB0_1169

.LBB0_1421:
	v_lshl_add_u32 v144, s51, 8, v154
	v_lshl_or_b32 v142, s33, 8, v155
	v_ashrrev_i32_e32 v145, 31, v144
	v_ashrrev_i32_e32 v143, 31, v142
	v_lshlrev_b64 v[146:147], 13, v[144:145]
	v_lshl_add_u64 v[168:169], s[96:97], 0, v[146:147]
	v_lshlrev_b64 v[146:147], 1, v[142:143]
	v_lshl_add_u64 v[142:143], v[168:169], 0, v[146:147]
	global_load_dwordx4 v[168:171], v[142:143], off
	s_mov_b64 s[22:23], 0x100000
	s_waitcnt vmcnt(0)
	v_lshlrev_b32_e32 v172, 16, v168
	v_and_b32_e32 v173, 0xffff0000, v168
	v_lshlrev_b32_e32 v176, 16, v169
	v_and_b32_e32 v177, 0xffff0000, v169
	v_lshlrev_b32_e32 v178, 16, v170
	v_and_b32_e32 v179, 0xffff0000, v170
	v_lshlrev_b32_e32 v180, 16, v171
	v_and_b32_e32 v181, 0xffff0000, v171
	global_load_dwordx4 v[168:171], v[142:143], off offset:256
	v_pk_add_f32 v[128:129], v[128:129], v[176:177]
	v_pk_add_f32 v[126:127], v[126:127], v[172:173]
	v_pk_add_f32 v[172:173], v[124:125], v[180:181]
	v_pk_add_f32 v[124:125], v[122:123], v[178:179]
	v_cvt_pk_bf16_f32 v122, v126, v127
	v_cvt_pk_bf16_f32 v123, v128, v129
	s_waitcnt vmcnt(0)
	v_lshlrev_b32_e32 v182, 16, v168
	v_and_b32_e32 v183, 0xffff0000, v168
	v_lshlrev_b32_e32 v184, 16, v170
	v_and_b32_e32 v185, 0xffff0000, v170
	v_lshlrev_b32_e32 v170, 16, v171
	v_and_b32_e32 v171, 0xffff0000, v171
	v_lshlrev_b32_e32 v168, 16, v169
	v_and_b32_e32 v169, 0xffff0000, v169
	v_cvt_pk_bf16_f32 v124, v124, v125
	v_cvt_pk_bf16_f32 v125, v172, v173
	global_store_dwordx4 v[142:143], v[122:125], off sc1
	v_pk_add_f32 v[118:119], v[118:119], v[182:183]
	v_pk_add_f32 v[120:121], v[120:121], v[168:169]
	v_pk_add_f32 v[122:123], v[116:117], v[170:171]
	v_pk_add_f32 v[116:117], v[114:115], v[184:185]
	v_cvt_pk_bf16_f32 v114, v118, v119
	v_cvt_pk_bf16_f32 v115, v120, v121
	s_nop 0
	v_cvt_pk_bf16_f32 v116, v116, v117
	v_cvt_pk_bf16_f32 v117, v122, v123
	global_store_dwordx4 v[142:143], v[114:117], off offset:256 sc1
	s_nop 1
	v_or_b32_e32 v114, 16, v144
	v_ashrrev_i32_e32 v115, 31, v114
	v_lshlrev_b64 v[114:115], 13, v[114:115]
	v_lshl_add_u64 v[114:115], s[96:97], 0, v[114:115]
	v_lshl_add_u64 v[118:119], v[114:115], 0, v[146:147]
	global_load_dwordx4 v[114:117], v[118:119], off
	s_waitcnt vmcnt(0)
	v_lshlrev_b32_e32 v120, 16, v114
	v_and_b32_e32 v121, 0xffff0000, v114
	v_lshlrev_b32_e32 v122, 16, v115
	v_and_b32_e32 v123, 0xffff0000, v115
	v_lshlrev_b32_e32 v124, 16, v116
	v_and_b32_e32 v125, 0xffff0000, v116
	v_lshlrev_b32_e32 v126, 16, v117
	v_and_b32_e32 v127, 0xffff0000, v117
	global_load_dwordx4 v[114:117], v[118:119], off offset:256
	v_pk_add_f32 v[112:113], v[112:113], v[122:123]
	v_pk_add_f32 v[110:111], v[110:111], v[120:121]
	v_pk_add_f32 v[120:121], v[108:109], v[126:127]
	v_pk_add_f32 v[108:109], v[106:107], v[124:125]
	v_cvt_pk_bf16_f32 v106, v110, v111
	v_cvt_pk_bf16_f32 v107, v112, v113
	s_waitcnt vmcnt(0)
	v_lshlrev_b32_e32 v128, 16, v114
	v_and_b32_e32 v129, 0xffff0000, v114
	v_lshlrev_b32_e32 v168, 16, v116
	v_and_b32_e32 v169, 0xffff0000, v116
	v_lshlrev_b32_e32 v116, 16, v117
	v_and_b32_e32 v117, 0xffff0000, v117
	v_lshlrev_b32_e32 v114, 16, v115
	v_and_b32_e32 v115, 0xffff0000, v115
	v_cvt_pk_bf16_f32 v108, v108, v109
	v_cvt_pk_bf16_f32 v109, v120, v121
	global_store_dwordx4 v[118:119], v[106:109], off sc1
	v_pk_add_f32 v[102:103], v[102:103], v[128:129]
	v_pk_add_f32 v[104:105], v[104:105], v[114:115]
	v_pk_add_f32 v[106:107], v[100:101], v[116:117]
	v_pk_add_f32 v[100:101], v[98:99], v[168:169]
	v_cvt_pk_bf16_f32 v98, v102, v103
	v_cvt_pk_bf16_f32 v99, v104, v105
	s_nop 0
	v_cvt_pk_bf16_f32 v100, v100, v101
	v_cvt_pk_bf16_f32 v101, v106, v107
	global_store_dwordx4 v[118:119], v[98:101], off offset:256 sc1
	s_nop 1
	v_or_b32_e32 v98, 32, v144
	v_ashrrev_i32_e32 v99, 31, v98
	v_lshlrev_b64 v[98:99], 13, v[98:99]
	v_lshl_add_u64 v[98:99], s[96:97], 0, v[98:99]
	v_lshl_add_u64 v[102:103], v[98:99], 0, v[146:147]
	global_load_dwordx4 v[98:101], v[102:103], off
	s_waitcnt vmcnt(0)
	v_lshlrev_b32_e32 v104, 16, v98
	v_and_b32_e32 v105, 0xffff0000, v98
	v_lshlrev_b32_e32 v106, 16, v99
	v_and_b32_e32 v107, 0xffff0000, v99
	v_lshlrev_b32_e32 v108, 16, v100
	v_and_b32_e32 v109, 0xffff0000, v100
	v_lshlrev_b32_e32 v110, 16, v101
	v_and_b32_e32 v111, 0xffff0000, v101
	global_load_dwordx4 v[98:101], v[102:103], off offset:256
	v_pk_add_f32 v[96:97], v[96:97], v[106:107]
	v_pk_add_f32 v[94:95], v[94:95], v[104:105]
	v_pk_add_f32 v[104:105], v[92:93], v[110:111]
	v_pk_add_f32 v[92:93], v[90:91], v[108:109]
	v_cvt_pk_bf16_f32 v90, v94, v95
	v_cvt_pk_bf16_f32 v91, v96, v97
	s_waitcnt vmcnt(0)
	v_lshlrev_b32_e32 v112, 16, v98
	v_and_b32_e32 v113, 0xffff0000, v98
	v_lshlrev_b32_e32 v114, 16, v100
	v_and_b32_e32 v115, 0xffff0000, v100
	v_lshlrev_b32_e32 v100, 16, v101
	v_and_b32_e32 v101, 0xffff0000, v101
	v_lshlrev_b32_e32 v98, 16, v99
	v_and_b32_e32 v99, 0xffff0000, v99
	v_cvt_pk_bf16_f32 v92, v92, v93
	v_cvt_pk_bf16_f32 v93, v104, v105
	global_store_dwordx4 v[102:103], v[90:93], off sc1
	v_pk_add_f32 v[86:87], v[86:87], v[112:113]
	v_pk_add_f32 v[88:89], v[88:89], v[98:99]
	v_pk_add_f32 v[90:91], v[84:85], v[100:101]
	v_pk_add_f32 v[84:85], v[82:83], v[114:115]
	v_cvt_pk_bf16_f32 v82, v86, v87
	v_cvt_pk_bf16_f32 v83, v88, v89
	s_nop 0
	v_cvt_pk_bf16_f32 v84, v84, v85
	v_cvt_pk_bf16_f32 v85, v90, v91
	global_store_dwordx4 v[102:103], v[82:85], off offset:256 sc1
	s_nop 1
	v_or_b32_e32 v82, 48, v144
	v_ashrrev_i32_e32 v83, 31, v82
	v_lshlrev_b64 v[82:83], 13, v[82:83]
	v_lshl_add_u64 v[82:83], s[96:97], 0, v[82:83]
	v_lshl_add_u64 v[86:87], v[82:83], 0, v[146:147]
	global_load_dwordx4 v[82:85], v[86:87], off
	s_waitcnt vmcnt(0)
	v_lshlrev_b32_e32 v88, 16, v82
	v_and_b32_e32 v89, 0xffff0000, v82
	v_lshlrev_b32_e32 v90, 16, v83
	v_and_b32_e32 v91, 0xffff0000, v83
	v_lshlrev_b32_e32 v92, 16, v84
	v_and_b32_e32 v93, 0xffff0000, v84
	v_lshlrev_b32_e32 v94, 16, v85
	v_and_b32_e32 v95, 0xffff0000, v85
	global_load_dwordx4 v[82:85], v[86:87], off offset:256
	v_pk_add_f32 v[80:81], v[80:81], v[90:91]
	v_pk_add_f32 v[78:79], v[78:79], v[88:89]
	v_pk_add_f32 v[88:89], v[76:77], v[94:95]
	v_pk_add_f32 v[76:77], v[74:75], v[92:93]
	v_cvt_pk_bf16_f32 v74, v78, v79
	v_cvt_pk_bf16_f32 v75, v80, v81
	s_waitcnt vmcnt(0)
	v_lshlrev_b32_e32 v96, 16, v82
	v_and_b32_e32 v97, 0xffff0000, v82
	v_lshlrev_b32_e32 v82, 16, v83
	v_and_b32_e32 v83, 0xffff0000, v83
	v_lshlrev_b32_e32 v98, 16, v84
	v_and_b32_e32 v99, 0xffff0000, v84
	v_lshlrev_b32_e32 v84, 16, v85
	v_and_b32_e32 v85, 0xffff0000, v85
	v_cvt_pk_bf16_f32 v76, v76, v77
	v_cvt_pk_bf16_f32 v77, v88, v89
	global_store_dwordx4 v[86:87], v[74:77], off sc1
	v_pk_add_f32 v[72:73], v[72:73], v[82:83]
	v_pk_add_f32 v[70:71], v[70:71], v[96:97]
	v_pk_add_f32 v[74:75], v[68:69], v[84:85]
	v_pk_add_f32 v[68:69], v[66:67], v[98:99]
	v_cvt_pk_bf16_f32 v66, v70, v71
	v_cvt_pk_bf16_f32 v67, v72, v73
	s_nop 0
	v_cvt_pk_bf16_f32 v68, v68, v69
	v_cvt_pk_bf16_f32 v69, v74, v75
	global_store_dwordx4 v[86:87], v[66:69], off offset:256 sc1
	s_nop 1
	v_lshl_add_u64 v[66:67], v[142:143], 0, s[22:23]
	s_mov_b32 s22, 0x100000
	v_add_co_u32_e32 v72, vcc, s22, v142
	s_mov_b64 s[22:23], 0x120000
	s_nop 0
	v_addc_co_u32_e32 v73, vcc, 0, v143, vcc
	global_load_dwordx4 v[68:71], v[72:73], off
	s_waitcnt vmcnt(0)
	v_lshlrev_b32_e32 v74, 16, v68
	v_and_b32_e32 v75, 0xffff0000, v68
	v_lshlrev_b32_e32 v76, 16, v69
	v_and_b32_e32 v77, 0xffff0000, v69
	v_lshlrev_b32_e32 v78, 16, v70
	v_and_b32_e32 v79, 0xffff0000, v70
	v_lshlrev_b32_e32 v80, 16, v71
	v_and_b32_e32 v81, 0xffff0000, v71
	global_load_dwordx4 v[68:71], v[66:67], off offset:256
	v_pk_add_f32 v[64:65], v[64:65], v[76:77]
	v_pk_add_f32 v[62:63], v[62:63], v[74:75]
	v_pk_add_f32 v[74:75], v[60:61], v[80:81]
	v_pk_add_f32 v[60:61], v[58:59], v[78:79]
	v_cvt_pk_bf16_f32 v58, v62, v63
	v_cvt_pk_bf16_f32 v59, v64, v65
	s_waitcnt vmcnt(0)
	v_lshlrev_b32_e32 v82, 16, v68
	v_and_b32_e32 v83, 0xffff0000, v68
	v_lshlrev_b32_e32 v68, 16, v69
	v_and_b32_e32 v69, 0xffff0000, v69
	v_lshlrev_b32_e32 v84, 16, v70
	v_and_b32_e32 v85, 0xffff0000, v70
	v_lshlrev_b32_e32 v70, 16, v71
	v_and_b32_e32 v71, 0xffff0000, v71
	v_cvt_pk_bf16_f32 v60, v60, v61
	v_cvt_pk_bf16_f32 v61, v74, v75
	global_store_dwordx4 v[72:73], v[58:61], off sc1
	v_pk_add_f32 v[56:57], v[56:57], v[68:69]
	v_pk_add_f32 v[54:55], v[54:55], v[82:83]
	v_pk_add_f32 v[58:59], v[52:53], v[70:71]
	v_pk_add_f32 v[52:53], v[50:51], v[84:85]
	v_cvt_pk_bf16_f32 v50, v54, v55
	v_cvt_pk_bf16_f32 v51, v56, v57
	s_nop 0
	v_cvt_pk_bf16_f32 v52, v52, v53
	v_cvt_pk_bf16_f32 v53, v58, v59
	global_store_dwordx4 v[66:67], v[50:53], off offset:256 sc1
	s_nop 1
	v_lshl_add_u64 v[50:51], v[142:143], 0, s[22:23]
	s_mov_b32 s22, 0x120000
	v_add_co_u32_e32 v56, vcc, s22, v142
	s_mov_b64 s[22:23], 0x140000
	s_nop 0
	v_addc_co_u32_e32 v57, vcc, 0, v143, vcc
	global_load_dwordx4 v[52:55], v[56:57], off
	s_waitcnt vmcnt(0)
	v_lshlrev_b32_e32 v58, 16, v52
	v_and_b32_e32 v59, 0xffff0000, v52
	v_lshlrev_b32_e32 v60, 16, v53
	v_and_b32_e32 v61, 0xffff0000, v53
	v_lshlrev_b32_e32 v62, 16, v54
	v_and_b32_e32 v63, 0xffff0000, v54
	v_lshlrev_b32_e32 v64, 16, v55
	v_and_b32_e32 v65, 0xffff0000, v55
	global_load_dwordx4 v[52:55], v[50:51], off offset:256
	v_pk_add_f32 v[48:49], v[48:49], v[60:61]
	v_pk_add_f32 v[46:47], v[46:47], v[58:59]
	v_pk_add_f32 v[58:59], v[44:45], v[64:65]
	v_pk_add_f32 v[44:45], v[42:43], v[62:63]
	v_cvt_pk_bf16_f32 v42, v46, v47
	v_cvt_pk_bf16_f32 v43, v48, v49
	s_waitcnt vmcnt(0)
	v_lshlrev_b32_e32 v66, 16, v52
	v_and_b32_e32 v67, 0xffff0000, v52
	v_lshlrev_b32_e32 v52, 16, v53
	v_and_b32_e32 v53, 0xffff0000, v53
	v_lshlrev_b32_e32 v68, 16, v54
	v_and_b32_e32 v69, 0xffff0000, v54
	v_lshlrev_b32_e32 v54, 16, v55
	v_and_b32_e32 v55, 0xffff0000, v55
	v_cvt_pk_bf16_f32 v44, v44, v45
	v_cvt_pk_bf16_f32 v45, v58, v59
	global_store_dwordx4 v[56:57], v[42:45], off sc1
	v_pk_add_f32 v[40:41], v[40:41], v[52:53]
	v_pk_add_f32 v[38:39], v[38:39], v[66:67]
	v_pk_add_f32 v[42:43], v[36:37], v[54:55]
	v_pk_add_f32 v[36:37], v[34:35], v[68:69]
	v_cvt_pk_bf16_f32 v34, v38, v39
	v_cvt_pk_bf16_f32 v35, v40, v41
	s_nop 0
	v_cvt_pk_bf16_f32 v36, v36, v37
	v_cvt_pk_bf16_f32 v37, v42, v43
	global_store_dwordx4 v[50:51], v[34:37], off offset:256 sc1
	s_nop 1
	v_lshl_add_u64 v[34:35], v[142:143], 0, s[22:23]
	s_mov_b32 s22, 0x140000
	v_add_co_u32_e32 v40, vcc, s22, v142
	s_mov_b64 s[22:23], 0x160000
	s_nop 0
	v_addc_co_u32_e32 v41, vcc, 0, v143, vcc
	global_load_dwordx4 v[36:39], v[40:41], off
	s_waitcnt vmcnt(0)
	v_lshlrev_b32_e32 v42, 16, v36
	v_and_b32_e32 v43, 0xffff0000, v36
	v_lshlrev_b32_e32 v44, 16, v37
	v_and_b32_e32 v45, 0xffff0000, v37
	v_lshlrev_b32_e32 v46, 16, v38
	v_and_b32_e32 v47, 0xffff0000, v38
	v_lshlrev_b32_e32 v48, 16, v39
	v_and_b32_e32 v49, 0xffff0000, v39
	global_load_dwordx4 v[36:39], v[34:35], off offset:256
	v_pk_add_f32 v[32:33], v[32:33], v[44:45]
	v_pk_add_f32 v[30:31], v[30:31], v[42:43]
	v_pk_add_f32 v[42:43], v[28:29], v[48:49]
	v_pk_add_f32 v[28:29], v[26:27], v[46:47]
	v_cvt_pk_bf16_f32 v26, v30, v31
	v_cvt_pk_bf16_f32 v27, v32, v33
	s_waitcnt vmcnt(0)
	v_lshlrev_b32_e32 v50, 16, v36
	v_and_b32_e32 v51, 0xffff0000, v36
	v_lshlrev_b32_e32 v36, 16, v37
	v_and_b32_e32 v37, 0xffff0000, v37
	v_lshlrev_b32_e32 v52, 16, v38
	v_and_b32_e32 v53, 0xffff0000, v38
	v_lshlrev_b32_e32 v38, 16, v39
	v_and_b32_e32 v39, 0xffff0000, v39
	v_cvt_pk_bf16_f32 v28, v28, v29
	v_cvt_pk_bf16_f32 v29, v42, v43
	global_store_dwordx4 v[40:41], v[26:29], off sc1
	v_pk_add_f32 v[24:25], v[24:25], v[36:37]
	v_pk_add_f32 v[22:23], v[22:23], v[50:51]
	v_pk_add_f32 v[26:27], v[20:21], v[38:39]
	v_pk_add_f32 v[20:21], v[18:19], v[52:53]
	v_cvt_pk_bf16_f32 v18, v22, v23
	v_cvt_pk_bf16_f32 v19, v24, v25
	s_nop 0
	v_cvt_pk_bf16_f32 v20, v20, v21
	v_cvt_pk_bf16_f32 v21, v26, v27
	global_store_dwordx4 v[34:35], v[18:21], off offset:256 sc1
	s_nop 1
	v_lshl_add_u64 v[18:19], v[142:143], 0, s[22:23]
	s_mov_b32 s22, 0x160000
	v_add_co_u32_e32 v24, vcc, s22, v142
	s_mov_b64 s[22:23], -1
	s_nop 0
	v_addc_co_u32_e32 v25, vcc, 0, v143, vcc
	global_load_dwordx4 v[20:23], v[24:25], off
	s_and_b64 vcc, exec, s[4:5]
	s_waitcnt vmcnt(0)
	v_lshlrev_b32_e32 v26, 16, v20
	v_and_b32_e32 v27, 0xffff0000, v20
	v_lshlrev_b32_e32 v28, 16, v21
	v_and_b32_e32 v29, 0xffff0000, v21
	v_lshlrev_b32_e32 v30, 16, v22
	v_and_b32_e32 v31, 0xffff0000, v22
	v_lshlrev_b32_e32 v32, 16, v23
	v_and_b32_e32 v33, 0xffff0000, v23
	global_load_dwordx4 v[20:23], v[18:19], off offset:256
	v_pk_add_f32 v[16:17], v[16:17], v[28:29]
	v_pk_add_f32 v[14:15], v[14:15], v[26:27]
	v_pk_add_f32 v[26:27], v[12:13], v[32:33]
	v_pk_add_f32 v[12:13], v[10:11], v[30:31]
	v_cvt_pk_bf16_f32 v10, v14, v15
	v_cvt_pk_bf16_f32 v11, v16, v17
	s_waitcnt vmcnt(0)
	v_lshlrev_b32_e32 v36, 16, v22
	v_and_b32_e32 v37, 0xffff0000, v22
	v_lshlrev_b32_e32 v22, 16, v23
	v_and_b32_e32 v23, 0xffff0000, v23
	v_lshlrev_b32_e32 v34, 16, v20
	v_and_b32_e32 v35, 0xffff0000, v20
	v_lshlrev_b32_e32 v20, 16, v21
	v_and_b32_e32 v21, 0xffff0000, v21
	v_cvt_pk_bf16_f32 v12, v12, v13
	v_cvt_pk_bf16_f32 v13, v26, v27
	global_store_dwordx4 v[24:25], v[10:13], off sc1
	v_pk_add_f32 v[8:9], v[8:9], v[20:21]
	v_pk_add_f32 v[6:7], v[6:7], v[34:35]
	v_pk_add_f32 v[10:11], v[4:5], v[22:23]
	v_pk_add_f32 v[4:5], v[2:3], v[36:37]
	v_cvt_pk_bf16_f32 v2, v6, v7
	v_cvt_pk_bf16_f32 v3, v8, v9
	s_nop 0
	v_cvt_pk_bf16_f32 v4, v4, v5
	v_cvt_pk_bf16_f32 v5, v10, v11
	global_store_dwordx4 v[18:19], v[2:5], off offset:256 sc1
	s_cbranch_vccnz .LBB0_1414
	s_and_b64 s[4:5], s[20:21], exec
	s_cselect_b32 s33, s52, s33
	s_cselect_b32 s51, s34, s51
	s_andn2_b64 vcc, exec, s[10:11]
	s_cbranch_vccnz .LBB0_1413
	s_barrier
	s_branch .LBB0_1413

.LBB0_1432:
	ds_read_b128 v[150:153], v139
	ds_read_b128 v[154:157], v139 offset:1024
	ds_read_b128 v[158:161], v139 offset:2048
	ds_read_b128 v[168:171], v139 offset:3072
	ds_read_b128 v[176:179], v144
	ds_read_b128 v[180:183], v144 offset:1024
	ds_read_b128 v[184:187], v144 offset:2048
	ds_read_b128 v[188:191], v144 offset:3072
	s_add_i32 s42, s15, 2
	s_add_u32 s14, s12, 0xc2050080
	s_addc_u32 s16, s13, -1
	s_cmp_lg_u32 s30, s15
	s_cselect_b32 s14, s14, 0
	s_cselect_b32 s15, s16, 0
	s_add_u32 s16, s4, s14
	s_addc_u32 s17, s5, s15
	s_add_u32 s14, s8, s14
	s_addc_u32 s15, s9, s15
	s_mov_b32 m0, s31
	v_lshl_add_u64 v[172:173], v[140:141], 0, s[12:13]
	ds_read_b128 v[192:195], v145
	ds_read_b128 v[204:207], v145 offset:1024
	ds_read_b128 v[208:211], v145 offset:2048
	ds_read_b128 v[212:215], v145 offset:3072
	ds_read_b128 v[216:219], v145 offset:4096
	ds_read_b128 v[220:223], v145 offset:5120
	ds_read_b128 v[224:227], v145 offset:6144
	ds_read_b128 v[228:231], v145 offset:7168
	global_load_lds_dwordx4 v[172:173], off
	v_lshl_add_u64 v[172:173], v[142:143], 0, s[12:13]
	s_mov_b32 m0, s33
	s_nop 0
	global_load_lds_dwordx4 v[172:173], off
	s_waitcnt vmcnt(8)
	s_waitcnt lgkmcnt(0)
	s_barrier
	v_mfma_f32_16x16x32_bf16 v[126:129], v[150:153], v[192:195], v[126:129]
	v_mfma_f32_16x16x32_bf16 v[126:129], v[154:157], v[204:207], v[126:129]
	v_mfma_f32_16x16x32_bf16 v[122:125], v[168:171], v[204:207], v[122:125]
	v_mfma_f32_16x16x32_bf16 v[122:125], v[158:161], v[192:195], v[122:125]
	v_mfma_f32_16x16x32_bf16 v[114:117], v[158:161], v[208:211], v[114:117]
	v_mfma_f32_16x16x32_bf16 v[114:117], v[168:171], v[212:215], v[114:117]
	v_mfma_f32_16x16x32_bf16 v[118:121], v[154:157], v[212:215], v[118:121]
	v_mfma_f32_16x16x32_bf16 v[118:121], v[150:153], v[208:211], v[118:121]
	v_mfma_f32_16x16x32_bf16 v[102:105], v[150:153], v[216:219], v[102:105]
	v_mfma_f32_16x16x32_bf16 v[102:105], v[154:157], v[220:223], v[102:105]
	v_mfma_f32_16x16x32_bf16 v[98:101], v[168:171], v[220:223], v[98:101]
	v_mfma_f32_16x16x32_bf16 v[98:101], v[158:161], v[216:219], v[98:101]
	v_mfma_f32_16x16x32_bf16 v[82:85], v[158:161], v[224:227], v[82:85]
	v_mfma_f32_16x16x32_bf16 v[82:85], v[168:171], v[228:231], v[82:85]
	v_mfma_f32_16x16x32_bf16 v[86:89], v[154:157], v[228:231], v[86:89]
	v_mfma_f32_16x16x32_bf16 v[86:89], v[150:153], v[224:227], v[86:89]
	v_mfma_f32_16x16x32_bf16 v[70:73], v[176:179], v[224:227], v[70:73]
	v_mfma_f32_16x16x32_bf16 v[70:73], v[180:183], v[228:231], v[70:73]
	v_mfma_f32_16x16x32_bf16 v[66:69], v[188:191], v[228:231], v[66:69]
	v_mfma_f32_16x16x32_bf16 v[66:69], v[184:187], v[224:227], v[66:69]
	v_mfma_f32_16x16x32_bf16 v[74:77], v[184:187], v[216:219], v[74:77]
	v_mfma_f32_16x16x32_bf16 v[74:77], v[188:191], v[220:223], v[74:77]
	v_mfma_f32_16x16x32_bf16 v[78:81], v[180:183], v[220:223], v[78:81]
	v_mfma_f32_16x16x32_bf16 v[78:81], v[176:179], v[216:219], v[78:81]
	v_mfma_f32_16x16x32_bf16 v[94:97], v[176:179], v[208:211], v[94:97]
	v_mfma_f32_16x16x32_bf16 v[94:97], v[180:183], v[212:215], v[94:97]
	v_mfma_f32_16x16x32_bf16 v[90:93], v[188:191], v[212:215], v[90:93]
	v_mfma_f32_16x16x32_bf16 v[90:93], v[184:187], v[208:211], v[90:93]
	v_mfma_f32_16x16x32_bf16 v[106:109], v[184:187], v[192:195], v[106:109]
	v_mfma_f32_16x16x32_bf16 v[106:109], v[188:191], v[204:207], v[106:109]
	v_mfma_f32_16x16x32_bf16 v[110:113], v[180:183], v[204:207], v[110:113]
	v_mfma_f32_16x16x32_bf16 v[110:113], v[176:179], v[192:195], v[110:113]
	s_barrier
	s_mov_b32 m0, s34
	v_lshl_add_u64 v[172:173], s[14:15], 0, v[132:133]
	s_add_u32 s44, s14, 0x2b0000
	ds_read_b128 v[192:195], v145 offset:16384
	ds_read_b128 v[204:207], v145 offset:17408
	ds_read_b128 v[208:211], v145 offset:18432
	ds_read_b128 v[212:215], v145 offset:19456
	ds_read_b128 v[216:219], v145 offset:20480
	ds_read_b128 v[220:223], v145 offset:21504
	ds_read_b128 v[224:227], v145 offset:22528
	ds_read_b128 v[228:231], v145 offset:23552
	global_load_lds_dwordx4 v[172:173], off
	v_lshl_add_u64 v[196:197], s[14:15], 0, v[136:137]
	s_mov_b32 m0, s35
	s_addc_u32 s45, s15, 0
	global_load_lds_dwordx4 v[196:197], off
	v_lshl_add_u64 v[232:233], s[44:45], 0, v[132:133]
	s_mov_b32 m0, s36
	v_lshl_add_u64 v[234:235], s[16:17], 0, v[134:135]
	global_load_lds_dwordx4 v[232:233], off
	v_lshl_add_u64 v[232:233], s[44:45], 0, v[136:137]
	s_mov_b32 m0, s37
	s_nop 0
	global_load_lds_dwordx4 v[232:233], off
	v_lshl_add_u64 v[232:233], s[16:17], 0, v[130:131]
	s_mov_b32 m0, s21
	s_nop 0
	global_load_lds_dwordx4 v[232:233], off
	s_mov_b32 m0, s22
	s_nop 0
	global_load_lds_dwordx4 v[234:235], off
	s_waitcnt vmcnt(8)
	s_waitcnt lgkmcnt(0)
	s_barrier
	v_mfma_f32_16x16x32_bf16 v[62:65], v[150:153], v[192:195], v[62:65]
	v_mfma_f32_16x16x32_bf16 v[62:65], v[154:157], v[204:207], v[62:65]
	v_mfma_f32_16x16x32_bf16 v[58:61], v[168:171], v[204:207], v[58:61]
	v_mfma_f32_16x16x32_bf16 v[58:61], v[158:161], v[192:195], v[58:61]
	v_mfma_f32_16x16x32_bf16 v[50:53], v[158:161], v[208:211], v[50:53]
	v_mfma_f32_16x16x32_bf16 v[50:53], v[168:171], v[212:215], v[50:53]
	v_mfma_f32_16x16x32_bf16 v[54:57], v[154:157], v[212:215], v[54:57]
	v_mfma_f32_16x16x32_bf16 v[54:57], v[150:153], v[208:211], v[54:57]
	v_mfma_f32_16x16x32_bf16 v[38:41], v[150:153], v[216:219], v[38:41]
	v_mfma_f32_16x16x32_bf16 v[38:41], v[154:157], v[220:223], v[38:41]
	v_mfma_f32_16x16x32_bf16 v[34:37], v[168:171], v[220:223], v[34:37]
	v_mfma_f32_16x16x32_bf16 v[34:37], v[158:161], v[216:219], v[34:37]
	v_mfma_f32_16x16x32_bf16 v[18:21], v[158:161], v[224:227], v[18:21]
	v_mfma_f32_16x16x32_bf16 v[18:21], v[168:171], v[228:231], v[18:21]
	v_mfma_f32_16x16x32_bf16 v[22:25], v[154:157], v[228:231], v[22:25]
	v_mfma_f32_16x16x32_bf16 v[22:25], v[150:153], v[224:227], v[22:25]
	v_mfma_f32_16x16x32_bf16 v[6:9], v[176:179], v[224:227], v[6:9]
	v_mfma_f32_16x16x32_bf16 v[6:9], v[180:183], v[228:231], v[6:9]
	v_mfma_f32_16x16x32_bf16 v[2:5], v[188:191], v[228:231], v[2:5]
	v_mfma_f32_16x16x32_bf16 v[2:5], v[184:187], v[224:227], v[2:5]
	v_mfma_f32_16x16x32_bf16 v[10:13], v[184:187], v[216:219], v[10:13]
	v_mfma_f32_16x16x32_bf16 v[10:13], v[188:191], v[220:223], v[10:13]
	v_mfma_f32_16x16x32_bf16 v[14:17], v[180:183], v[220:223], v[14:17]
	v_mfma_f32_16x16x32_bf16 v[14:17], v[176:179], v[216:219], v[14:17]
	v_mfma_f32_16x16x32_bf16 v[30:33], v[176:179], v[208:211], v[30:33]
	v_mfma_f32_16x16x32_bf16 v[30:33], v[180:183], v[212:215], v[30:33]
	v_mfma_f32_16x16x32_bf16 v[26:29], v[188:191], v[212:215], v[26:29]
	v_mfma_f32_16x16x32_bf16 v[26:29], v[184:187], v[208:211], v[26:29]
	v_mfma_f32_16x16x32_bf16 v[42:45], v[184:187], v[192:195], v[42:45]
	v_mfma_f32_16x16x32_bf16 v[42:45], v[188:191], v[204:207], v[42:45]
	v_mfma_f32_16x16x32_bf16 v[46:49], v[180:183], v[204:207], v[46:49]
	v_mfma_f32_16x16x32_bf16 v[46:49], v[176:179], v[192:195], v[46:49]
	s_barrier
	ds_read_b128 v[150:153], v146
	ds_read_b128 v[154:157], v146 offset:1024
	ds_read_b128 v[158:161], v146 offset:2048
	ds_read_b128 v[168:171], v146 offset:3072
	ds_read_b128 v[176:179], v147
	ds_read_b128 v[180:183], v147 offset:1024
	ds_read_b128 v[184:187], v147 offset:2048
	ds_read_b128 v[188:191], v147 offset:3072
	s_add_u32 s16, s16, 0x2b0000
	s_addc_u32 s17, s17, 0
	s_mov_b32 m0, s23
	v_lshl_add_u64 v[236:237], s[16:17], 0, v[130:131]
	ds_read_b128 v[192:195], v145 offset:32768
	ds_read_b128 v[204:207], v145 offset:33792
	ds_read_b128 v[208:211], v145 offset:34816
	ds_read_b128 v[212:215], v145 offset:35840
	ds_read_b128 v[216:219], v145 offset:36864
	ds_read_b128 v[220:223], v145 offset:37888
	ds_read_b128 v[224:227], v145 offset:38912
	ds_read_b128 v[228:231], v145 offset:39936
	global_load_lds_dwordx4 v[236:237], off
	v_lshl_add_u64 v[236:237], s[16:17], 0, v[134:135]
	s_mov_b32 m0, s24
	s_nop 0
	global_load_lds_dwordx4 v[236:237], off
	s_waitcnt vmcnt(8)
	s_waitcnt lgkmcnt(0)
	s_barrier
	v_mfma_f32_16x16x32_bf16 v[126:129], v[150:153], v[192:195], v[126:129]
	v_mfma_f32_16x16x32_bf16 v[126:129], v[154:157], v[204:207], v[126:129]
	v_mfma_f32_16x16x32_bf16 v[122:125], v[168:171], v[204:207], v[122:125]
	v_mfma_f32_16x16x32_bf16 v[122:125], v[158:161], v[192:195], v[122:125]
	v_mfma_f32_16x16x32_bf16 v[114:117], v[158:161], v[208:211], v[114:117]
	v_mfma_f32_16x16x32_bf16 v[114:117], v[168:171], v[212:215], v[114:117]
	v_mfma_f32_16x16x32_bf16 v[118:121], v[154:157], v[212:215], v[118:121]
	v_mfma_f32_16x16x32_bf16 v[118:121], v[150:153], v[208:211], v[118:121]
	v_mfma_f32_16x16x32_bf16 v[102:105], v[150:153], v[216:219], v[102:105]
	v_mfma_f32_16x16x32_bf16 v[102:105], v[154:157], v[220:223], v[102:105]
	v_mfma_f32_16x16x32_bf16 v[98:101], v[168:171], v[220:223], v[98:101]
	v_mfma_f32_16x16x32_bf16 v[98:101], v[158:161], v[216:219], v[98:101]
	v_mfma_f32_16x16x32_bf16 v[82:85], v[158:161], v[224:227], v[82:85]
	v_mfma_f32_16x16x32_bf16 v[82:85], v[168:171], v[228:231], v[82:85]
	v_mfma_f32_16x16x32_bf16 v[86:89], v[154:157], v[228:231], v[86:89]
	v_mfma_f32_16x16x32_bf16 v[86:89], v[150:153], v[224:227], v[86:89]
	v_mfma_f32_16x16x32_bf16 v[70:73], v[176:179], v[224:227], v[70:73]
	v_mfma_f32_16x16x32_bf16 v[70:73], v[180:183], v[228:231], v[70:73]
	v_mfma_f32_16x16x32_bf16 v[66:69], v[188:191], v[228:231], v[66:69]
	v_mfma_f32_16x16x32_bf16 v[66:69], v[184:187], v[224:227], v[66:69]
	v_mfma_f32_16x16x32_bf16 v[74:77], v[184:187], v[216:219], v[74:77]
	v_mfma_f32_16x16x32_bf16 v[74:77], v[188:191], v[220:223], v[74:77]
	v_mfma_f32_16x16x32_bf16 v[78:81], v[180:183], v[220:223], v[78:81]
	v_mfma_f32_16x16x32_bf16 v[78:81], v[176:179], v[216:219], v[78:81]
	v_mfma_f32_16x16x32_bf16 v[94:97], v[176:179], v[208:211], v[94:97]
	v_mfma_f32_16x16x32_bf16 v[94:97], v[180:183], v[212:215], v[94:97]
	v_mfma_f32_16x16x32_bf16 v[90:93], v[188:191], v[212:215], v[90:93]
	v_mfma_f32_16x16x32_bf16 v[90:93], v[184:187], v[208:211], v[90:93]
	v_mfma_f32_16x16x32_bf16 v[106:109], v[184:187], v[192:195], v[106:109]
	v_mfma_f32_16x16x32_bf16 v[106:109], v[188:191], v[204:207], v[106:109]
	v_mfma_f32_16x16x32_bf16 v[110:113], v[180:183], v[204:207], v[110:113]
	v_mfma_f32_16x16x32_bf16 v[110:113], v[176:179], v[192:195], v[110:113]
	s_barrier
	s_mov_b32 m0, s38
	v_lshl_add_u64 v[172:173], v[172:173], 0, s[10:11]
	s_add_u32 s14, s14, 0x2b0080
	ds_read_b128 v[192:195], v145 offset:49152
	ds_read_b128 v[204:207], v145 offset:50176
	ds_read_b128 v[208:211], v145 offset:51200
	ds_read_b128 v[212:215], v145 offset:52224
	ds_read_b128 v[216:219], v145 offset:53248
	ds_read_b128 v[220:223], v145 offset:54272
	ds_read_b128 v[224:227], v145 offset:55296
	ds_read_b128 v[228:231], v145 offset:56320
	global_load_lds_dwordx4 v[172:173], off
	v_lshl_add_u64 v[172:173], v[196:197], 0, s[10:11]
	s_mov_b32 m0, s39
	s_addc_u32 s15, s15, 0
	global_load_lds_dwordx4 v[172:173], off
	v_lshl_add_u64 v[172:173], s[14:15], 0, v[132:133]
	s_mov_b32 m0, s40
	s_nop 0
	global_load_lds_dwordx4 v[172:173], off
	v_lshl_add_u64 v[172:173], s[14:15], 0, v[136:137]
	s_mov_b32 m0, s41
	s_nop 0
	global_load_lds_dwordx4 v[172:173], off
	v_lshl_add_u64 v[172:173], v[232:233], 0, s[10:11]
	s_mov_b32 m0, s26
	s_nop 0
	global_load_lds_dwordx4 v[172:173], off
	v_lshl_add_u64 v[172:173], v[234:235], 0, s[10:11]
	s_mov_b32 m0, s27
	s_nop 0
	global_load_lds_dwordx4 v[172:173], off
	s_waitcnt vmcnt(8)
	s_waitcnt lgkmcnt(0)
	s_barrier
	v_mfma_f32_16x16x32_bf16 v[62:65], v[150:153], v[192:195], v[62:65]
	v_mfma_f32_16x16x32_bf16 v[62:65], v[154:157], v[204:207], v[62:65]
	v_mfma_f32_16x16x32_bf16 v[58:61], v[168:171], v[204:207], v[58:61]
	v_mfma_f32_16x16x32_bf16 v[58:61], v[158:161], v[192:195], v[58:61]
	v_mfma_f32_16x16x32_bf16 v[50:53], v[158:161], v[208:211], v[50:53]
	v_mfma_f32_16x16x32_bf16 v[50:53], v[168:171], v[212:215], v[50:53]
	v_mfma_f32_16x16x32_bf16 v[54:57], v[154:157], v[212:215], v[54:57]
	v_mfma_f32_16x16x32_bf16 v[54:57], v[150:153], v[208:211], v[54:57]
	v_mfma_f32_16x16x32_bf16 v[38:41], v[150:153], v[216:219], v[38:41]
	v_mfma_f32_16x16x32_bf16 v[38:41], v[154:157], v[220:223], v[38:41]
	v_mfma_f32_16x16x32_bf16 v[34:37], v[168:171], v[220:223], v[34:37]
	v_mfma_f32_16x16x32_bf16 v[34:37], v[158:161], v[216:219], v[34:37]
	v_mfma_f32_16x16x32_bf16 v[18:21], v[158:161], v[224:227], v[18:21]
	v_mfma_f32_16x16x32_bf16 v[18:21], v[168:171], v[228:231], v[18:21]
	v_mfma_f32_16x16x32_bf16 v[22:25], v[154:157], v[228:231], v[22:25]
	v_mfma_f32_16x16x32_bf16 v[22:25], v[150:153], v[224:227], v[22:25]
	v_mfma_f32_16x16x32_bf16 v[6:9], v[176:179], v[224:227], v[6:9]
	v_mfma_f32_16x16x32_bf16 v[6:9], v[180:183], v[228:231], v[6:9]
	v_mfma_f32_16x16x32_bf16 v[2:5], v[188:191], v[228:231], v[2:5]
	v_mfma_f32_16x16x32_bf16 v[2:5], v[184:187], v[224:227], v[2:5]
	v_mfma_f32_16x16x32_bf16 v[10:13], v[184:187], v[216:219], v[10:13]
	v_mfma_f32_16x16x32_bf16 v[10:13], v[188:191], v[220:223], v[10:13]
	v_mfma_f32_16x16x32_bf16 v[14:17], v[180:183], v[220:223], v[14:17]
	v_mfma_f32_16x16x32_bf16 v[14:17], v[176:179], v[216:219], v[14:17]
	v_mfma_f32_16x16x32_bf16 v[30:33], v[176:179], v[208:211], v[30:33]
	v_mfma_f32_16x16x32_bf16 v[30:33], v[180:183], v[212:215], v[30:33]
	v_mfma_f32_16x16x32_bf16 v[26:29], v[188:191], v[212:215], v[26:29]
	v_mfma_f32_16x16x32_bf16 v[26:29], v[184:187], v[208:211], v[26:29]
	v_mfma_f32_16x16x32_bf16 v[42:45], v[184:187], v[192:195], v[42:45]
	v_mfma_f32_16x16x32_bf16 v[42:45], v[188:191], v[204:207], v[42:45]
	v_mfma_f32_16x16x32_bf16 v[46:49], v[180:183], v[204:207], v[46:49]
	v_mfma_f32_16x16x32_bf16 v[46:49], v[176:179], v[192:195], v[46:49]
	s_barrier
	s_add_u32 s12, s12, 0x100
	s_addc_u32 s13, s13, 0
	s_cmp_ge_u32 s42, s19
	s_mov_b32 s15, s42
	s_cbranch_scc0 .LBB0_1432
	s_lshl_b32 s4, s18, 21
	v_readlane_b32 s0, v249, 29
	v_lshl_or_b32 v130, s20, 8, v148
	v_mov_b32_e32 v139, 0
	s_add_u32 s4, s0, s4
	v_readlane_b32 s0, v249, 31
	v_or_b32_e32 v130, s25, v130
	v_cvt_pk_bf16_f32 v70, v70, v71
	v_cvt_pk_bf16_f32 v71, v72, v73
	v_cvt_pk_bf16_f32 v72, v66, v67
	v_add_u32_e32 v66, 0x80, v138
	v_mov_b32_e32 v67, v139
	s_addc_u32 s5, s0, 0
	v_ashrrev_i32_e32 v131, 31, v130
	v_lshlrev_b64 v[132:133], 13, v[138:139]
	v_cvt_pk_bf16_f32 v110, v110, v111
	v_cvt_pk_bf16_f32 v111, v112, v113
	v_cvt_pk_bf16_f32 v112, v106, v107
	v_or_b32_e32 v106, 16, v138
	v_mov_b32_e32 v107, v139
	v_lshlrev_b64 v[66:67], 13, v[66:67]
	v_cvt_pk_bf16_f32 v46, v46, v47
	v_cvt_pk_bf16_f32 v47, v48, v49
	v_cvt_pk_bf16_f32 v48, v42, v43
	v_add_u32_e32 v42, 0x90, v138
	v_mov_b32_e32 v43, v139
	v_lshl_add_u64 v[132:133], s[4:5], 0, v[132:133]
	v_lshlrev_b64 v[130:131], 1, v[130:131]
	v_lshlrev_b64 v[106:107], 13, v[106:107]
	v_cvt_pk_bf16_f32 v94, v94, v95
	v_cvt_pk_bf16_f32 v95, v96, v97
	v_cvt_pk_bf16_f32 v96, v90, v91
	v_or_b32_e32 v90, 32, v138
	v_mov_b32_e32 v91, v139
	v_lshl_add_u64 v[66:67], s[4:5], 0, v[66:67]
	v_lshlrev_b64 v[42:43], 13, v[42:43]
	v_cvt_pk_bf16_f32 v30, v30, v31
	v_cvt_pk_bf16_f32 v31, v32, v33
	v_cvt_pk_bf16_f32 v32, v26, v27
	v_add_u32_e32 v26, 0xa0, v138
	v_mov_b32_e32 v27, v139
	v_lshl_add_u64 v[132:133], v[132:133], 0, v[130:131]
	v_cvt_pk_bf16_f32 v113, v108, v109
	v_lshl_add_u64 v[106:107], s[4:5], 0, v[106:107]
	v_lshlrev_b64 v[90:91], 13, v[90:91]
	v_cvt_pk_bf16_f32 v78, v78, v79
	v_cvt_pk_bf16_f32 v79, v80, v81
	v_cvt_pk_bf16_f32 v80, v74, v75
	v_or_b32_e32 v74, 48, v138
	v_mov_b32_e32 v75, v139
	v_lshl_add_u64 v[66:67], v[66:67], 0, v[130:131]
	v_cvt_pk_bf16_f32 v49, v44, v45
	v_lshl_add_u64 v[42:43], s[4:5], 0, v[42:43]
	v_lshlrev_b64 v[26:27], 13, v[26:27]
	v_add_u32_e32 v138, 0xb0, v138
	global_store_dwordx4 v[132:133], v[110:113], off offset:256 sc1
	v_cvt_pk_bf16_f32 v97, v92, v93
	v_lshl_add_u64 v[90:91], s[4:5], 0, v[90:91]
	v_lshl_add_u64 v[110:111], v[106:107], 0, v[130:131]
	v_lshlrev_b64 v[74:75], 13, v[74:75]
	global_store_dwordx4 v[66:67], v[46:49], off offset:256 sc1
	v_cvt_pk_bf16_f32 v33, v28, v29
	v_lshl_add_u64 v[26:27], s[4:5], 0, v[26:27]
	v_lshl_add_u64 v[46:47], v[42:43], 0, v[130:131]
	v_cvt_pk_bf16_f32 v14, v14, v15
	v_cvt_pk_bf16_f32 v15, v16, v17
	v_cvt_pk_bf16_f32 v16, v10, v11
	v_lshlrev_b64 v[10:11], 13, v[138:139]
	global_store_dwordx4 v[110:111], v[94:97], off offset:256 sc1
	v_cvt_pk_bf16_f32 v81, v76, v77
	v_lshl_add_u64 v[74:75], s[4:5], 0, v[74:75]
	v_lshl_add_u64 v[94:95], v[90:91], 0, v[130:131]
	global_store_dwordx4 v[46:47], v[30:33], off offset:256 sc1
	v_cvt_pk_bf16_f32 v17, v12, v13
	v_lshl_add_u64 v[10:11], s[4:5], 0, v[10:11]
	v_lshl_add_u64 v[30:31], v[26:27], 0, v[130:131]
	v_cvt_pk_bf16_f32 v126, v126, v127
	v_cvt_pk_bf16_f32 v127, v128, v129
	v_cvt_pk_bf16_f32 v128, v122, v123
	v_cvt_pk_bf16_f32 v129, v124, v125
	v_cvt_pk_bf16_f32 v106, v118, v119
	v_cvt_pk_bf16_f32 v107, v120, v121
	v_cvt_pk_bf16_f32 v108, v114, v115
	v_cvt_pk_bf16_f32 v109, v116, v117
	v_cvt_pk_bf16_f32 v90, v102, v103
	v_cvt_pk_bf16_f32 v91, v104, v105
	v_cvt_pk_bf16_f32 v92, v98, v99
	v_cvt_pk_bf16_f32 v93, v100, v101
	global_store_dwordx4 v[94:95], v[78:81], off offset:256 sc1
	v_cvt_pk_bf16_f32 v76, v82, v83
	v_cvt_pk_bf16_f32 v77, v84, v85
	v_lshl_add_u64 v[78:79], v[74:75], 0, v[130:131]
	v_cvt_pk_bf16_f32 v74, v86, v87
	v_cvt_pk_bf16_f32 v75, v88, v89
	v_cvt_pk_bf16_f32 v73, v68, v69
	v_cvt_pk_bf16_f32 v62, v62, v63
	v_cvt_pk_bf16_f32 v63, v64, v65
	v_cvt_pk_bf16_f32 v64, v58, v59
	v_cvt_pk_bf16_f32 v65, v60, v61
	v_cvt_pk_bf16_f32 v42, v54, v55
	v_cvt_pk_bf16_f32 v43, v56, v57
	v_cvt_pk_bf16_f32 v44, v50, v51
	v_cvt_pk_bf16_f32 v45, v52, v53
	v_cvt_pk_bf16_f32 v26, v38, v39
	v_cvt_pk_bf16_f32 v27, v40, v41
	v_cvt_pk_bf16_f32 v28, v34, v35
	v_cvt_pk_bf16_f32 v29, v36, v37
	global_store_dwordx4 v[30:31], v[14:17], off offset:256 sc1
	v_cvt_pk_bf16_f32 v12, v18, v19
	v_cvt_pk_bf16_f32 v13, v20, v21
	v_lshl_add_u64 v[14:15], v[10:11], 0, v[130:131]
	v_cvt_pk_bf16_f32 v10, v22, v23
	v_cvt_pk_bf16_f32 v11, v24, v25
	v_cvt_pk_bf16_f32 v6, v6, v7
	v_cvt_pk_bf16_f32 v7, v8, v9
	v_cvt_pk_bf16_f32 v8, v2, v3
	v_cvt_pk_bf16_f32 v9, v4, v5
	global_store_dwordx4 v[132:133], v[126:129], off sc1
	global_store_dwordx4 v[110:111], v[106:109], off sc1
	global_store_dwordx4 v[94:95], v[90:93], off sc1
	global_store_dwordx4 v[78:79], v[74:77], off sc1
	global_store_dwordx4 v[78:79], v[70:73], off offset:256 sc1
	global_store_dwordx4 v[66:67], v[62:65], off sc1
	global_store_dwordx4 v[46:47], v[42:45], off sc1
	global_store_dwordx4 v[30:31], v[26:29], off sc1
	global_store_dwordx4 v[14:15], v[10:13], off sc1
	global_store_dwordx4 v[14:15], v[6:9], off offset:256 sc1
	s_waitcnt vmcnt(0)
	s_cmpk_lt_u32 s3, 0x100
	s_cbranch_scc0 .LBB0_1435
	s_barrier

.LBB0_1568:
	s_lshl_b32 s6, s18, 2
	s_lshl_b32 s13, s40, 8
	s_or_b32 s93, s6, s46
	s_add_i32 s13, s13, s47
	s_and_b32 s8, s18, -2
	v_or_b32_e32 v186, s13, v166
	s_mov_b64 s[6:7], -1
	s_cmp_lg_u32 s8, 2
	v_lshlrev_b32_e32 v184, 2, v174
	s_cbranch_scc0 .LBB0_1667
	s_cmp_gt_i32 s18, 1
	v_readlane_b32 s68, v250, 18
	s_cselect_b64 s[8:9], -1, 0
	s_cmp_lt_i32 s18, 2
	v_readlane_b32 s69, v250, 19
	v_readlane_b32 s72, v250, 22
	v_readlane_b32 s73, v250, 23
	s_cselect_b32 s7, s69, s73
	s_cselect_b32 s6, s68, s72
	global_load_dwordx4 v[142:145], v184, s[6:7]
	global_load_dwordx4 v[138:141], v184, s[6:7] offset:64
	global_load_dwordx4 v[134:137], v184, s[6:7] offset:128
	global_load_dwordx4 v[130:133], v184, s[6:7] offset:192
	v_and_b32_e32 v147, 64, v209
	v_xor_b32_e32 v146, 16, v209
	v_add_u32_e32 v147, 64, v147
	v_cmp_lt_i32_e32 vcc, v146, v147
	v_pk_mul_f32 v[148:149], v[126:127], v[126:127]
	v_mov_b32_e32 v187, v173
	v_cndmask_b32_e32 v146, v209, v146, vcc
	v_lshlrev_b32_e32 v211, 2, v146
	v_xor_b32_e32 v146, 32, v209
	v_cmp_lt_i32_e32 vcc, v146, v147
	v_readlane_b32 s74, v250, 24
	s_lshl_b32 s72, s93, 6
	v_cndmask_b32_e32 v146, v209, v146, vcc
	v_lshlrev_b32_e32 v210, 2, v146
	v_pk_mul_f32 v[146:147], v[128:129], v[128:129]
	v_readlane_b32 s75, v250, 25
	v_pk_mov_b32 v[150:151], v[148:149], v[146:147] op_sel:[1,0]
	v_mov_b32_e32 v149, v147
	v_pk_add_f32 v[146:147], v[150:151], v[148:149]
	v_pk_mul_f32 v[148:149], v[124:125], v[124:125]
	v_pk_mul_f32 v[150:151], v[122:123], v[122:123]
	v_pk_add_f32 v[146:147], v[146:147], v[146:147] op_sel:[0,1] op_sel_hi:[1,0]
	v_pk_mov_b32 v[152:153], v[150:151], v[148:149] op_sel:[1,0]
	v_mov_b32_e32 v151, v149
	v_pk_add_f32 v[148:149], v[152:153], v[150:151]
	v_mul_f32_e32 v150, v114, v114
	v_mul_f32_e32 v151, v115, v115
	v_pk_add_f32 v[148:149], v[148:149], v[148:149] op_sel:[0,1] op_sel_hi:[1,0]
	v_mov_b32_e32 v147, v150
	v_mov_b32_e32 v149, v151
	v_pk_add_f32 v[146:147], v[146:147], v[148:149]
	v_mul_f32_e32 v148, v119, v119
	v_mul_f32_e32 v150, v121, v121
	v_mul_f32_e32 v152, v116, v116
	v_mul_f32_e32 v153, v117, v117
	v_pk_fma_f32 v[148:149], v[118:119], v[118:119], v[148:149] op_sel_hi:[1,1,0]
	v_pk_fma_f32 v[150:151], v[120:121], v[120:121], v[150:151] op_sel_hi:[1,1,0]
	v_mov_b32_e32 v149, v152
	v_mov_b32_e32 v151, v153
	v_pk_add_f32 v[148:149], v[148:149], v[150:151]
	s_add_i32 s74, s72, 0xfffffc00
	v_pk_add_f32 v[146:147], v[146:147], v[148:149]
	s_ashr_i32 s75, s74, 31
	v_add_f32_e32 v146, v146, v147
	ds_bpermute_b32 v147, v211, v146
	v_readlane_b32 s70, v250, 20
	v_readlane_b32 s71, v250, 21
	v_readlane_b32 s76, v250, 26
	v_readlane_b32 s77, v250, 27
	s_waitcnt lgkmcnt(0)
	v_add_f32_e32 v146, v146, v147
	ds_bpermute_b32 v147, v210, v146
	v_readlane_b32 s78, v250, 28
	v_readlane_b32 s79, v250, 29
	v_readlane_b32 s80, v250, 30
	v_readlane_b32 s81, v250, 31
	s_waitcnt lgkmcnt(0)
	v_add_f32_e32 v146, v146, v147
	v_fmamk_f32 v146, v146, 0x3c800000, v207
	v_cmp_gt_f32_e32 vcc, s10, v146
	v_mul_f32_e32 v147, 0x4f800000, v146
	v_readlane_b32 s82, v250, 32
	v_cndmask_b32_e32 v146, v146, v147, vcc
	v_sqrt_f32_e32 v147, v146
	v_readlane_b32 s83, v250, 33
	v_add_u32_e32 v148, -1, v147
	v_fma_f32 v149, -v148, v147, v146
	v_cmp_ge_f32_e64 s[6:7], 0, v149
	v_add_u32_e32 v149, 1, v147
	s_nop 0
	v_cndmask_b32_e64 v148, v147, v148, s[6:7]
	v_fma_f32 v147, -v149, v147, v146
	v_cmp_lt_f32_e64 s[6:7], 0, v147
	s_nop 1
	v_cndmask_b32_e64 v147, v148, v149, s[6:7]
	v_mul_f32_e32 v148, 0x37800000, v147
	v_cndmask_b32_e32 v147, v147, v148, vcc
	v_cmp_class_f32_e32 vcc, v146, v208
	s_nop 1
	v_cndmask_b32_e32 v146, v147, v146, vcc
	v_div_scale_f32 v147, s[6:7], v146, v146, 1.0
	v_rcp_f32_e32 v148, v147
	s_mov_b64 s[6:7], -1
	v_fma_f32 v149, -v147, v148, 1.0
	v_fmac_f32_e32 v148, v149, v148
	v_div_scale_f32 v149, vcc, 1.0, v146, 1.0
	v_mul_f32_e32 v150, v149, v148
	v_fma_f32 v151, -v147, v150, v149
	v_fmac_f32_e32 v150, v151, v148
	v_fma_f32 v147, -v147, v150, v149
	v_div_fmas_f32 v147, v147, v148, v150
	v_div_fixup_f32 v146, v147, v146, 1.0
	v_pk_mul_f32 v[148:149], v[126:127], v[146:147] op_sel_hi:[1,0]
	v_pk_mul_f32 v[150:151], v[128:129], v[146:147] op_sel_hi:[1,0]
	s_waitcnt vmcnt(0)
	v_pk_mul_f32 v[158:159], v[142:143], v[148:149]
	v_pk_mul_f32 v[160:161], v[144:145], v[150:151]
	v_pk_mul_f32 v[148:149], v[122:123], v[146:147] op_sel_hi:[1,0]
	v_pk_mul_f32 v[150:151], v[124:125], v[146:147] op_sel_hi:[1,0]
	v_pk_mul_f32 v[154:155], v[138:139], v[148:149]
	v_pk_mul_f32 v[156:157], v[140:141], v[150:151]
	v_pk_mul_f32 v[148:149], v[118:119], v[146:147] op_sel_hi:[1,0]
	v_pk_mul_f32 v[150:151], v[120:121], v[146:147] op_sel_hi:[1,0]
	v_pk_mul_f32 v[188:189], v[114:115], v[146:147] op_sel_hi:[1,0]
	v_pk_mul_f32 v[146:147], v[116:117], v[146:147] op_sel_hi:[1,0]
	v_pk_mul_f32 v[152:153], v[136:137], v[150:151]
	v_pk_mul_f32 v[150:151], v[134:135], v[148:149]
	v_pk_mul_f32 v[148:149], v[132:133], v[146:147]
	v_pk_mul_f32 v[146:147], v[130:131], v[188:189]
	v_lshlrev_b64 v[188:189], 6, v[186:187]
	v_lshl_add_u64 v[192:193], v[178:179], 0, v[188:189]
	global_load_dwordx4 v[188:191], v[192:193], off
	s_nop 0
	global_load_dwordx4 v[192:195], v[192:193], off offset:32
	ds_bpermute_b32 v196, v210, v158
	ds_bpermute_b32 v197, v210, v159
	ds_bpermute_b32 v212, v210, v160
	ds_bpermute_b32 v213, v210, v161
	s_and_b64 vcc, exec, s[8:9]
	s_waitcnt vmcnt(0) lgkmcnt(2)
	v_pk_mul_f32 v[192:193], v[192:193], v[196:197]
	s_waitcnt lgkmcnt(0)
	v_pk_mul_f32 v[194:195], v[194:195], v[212:213]
	v_xor_b32_e32 v196, 0x80000000, v192
	v_xor_b32_e32 v172, 0x80000000, v194
	v_xor_b32_e32 v185, 0x80000000, v195
	v_xor_b32_e32 v197, 0x80000000, v193
	v_cndmask_b32_e64 v193, v193, v197, s[4:5]
	v_cndmask_b32_e64 v192, v192, v196, s[4:5]
	v_cndmask_b32_e64 v195, v195, v185, s[4:5]
	v_cndmask_b32_e64 v194, v194, v172, s[4:5]
	v_pk_fma_f32 v[160:161], v[190:191], v[160:161], v[194:195]
	v_pk_fma_f32 v[158:159], v[188:189], v[158:159], v[192:193]
	v_lshlrev_b32_e32 v188, 1, v174
	s_cbranch_vccz .LBB0_1571
	v_readlane_b32 s6, v249, 9
	v_lshlrev_b64 v[190:191], 13, v[186:187]
	v_readlane_b32 s7, v249, 10
	v_mov_b32_e32 v189, v173
	v_pk_mul_f32 v[192:193], v[160:161], s[34:35] op_sel_hi:[1,0]
	v_lshl_add_u64 v[190:191], s[6:7], 0, v[190:191]
	v_lshl_add_u64 v[190:191], s[74:75], 1, v[190:191]
	v_pk_mul_f32 v[194:195], v[158:159], s[34:35] op_sel_hi:[1,0]
	v_lshl_add_u64 v[190:191], v[190:191], 0, v[188:189]
	v_cvt_pk_bf16_f32 v194, v194, v195
	v_cvt_pk_bf16_f32 v195, v192, v193
	global_store_dwordx2 v[190:191], v[194:195], off sc1
	v_pk_mul_f32 v[192:193], v[156:157], s[34:35] op_sel_hi:[1,0]
	v_pk_mul_f32 v[194:195], v[154:155], s[34:35] op_sel_hi:[1,0]
	s_mov_b64 s[6:7], 0
	v_cvt_pk_bf16_f32 v194, v194, v195
	v_cvt_pk_bf16_f32 v195, v192, v193
	global_store_dwordx2 v[190:191], v[194:195], off offset:32 sc1
	v_pk_mul_f32 v[192:193], v[152:153], s[34:35] op_sel_hi:[1,0]
	v_pk_mul_f32 v[194:195], v[150:151], s[34:35] op_sel_hi:[1,0]
	s_nop 0
	v_cvt_pk_bf16_f32 v194, v194, v195
	v_cvt_pk_bf16_f32 v195, v192, v193
	global_store_dwordx2 v[190:191], v[194:195], off offset:64 sc1
	v_pk_mul_f32 v[192:193], v[148:149], s[34:35] op_sel_hi:[1,0]
	v_pk_mul_f32 v[194:195], v[146:147], s[34:35] op_sel_hi:[1,0]
	s_nop 0
	v_cvt_pk_bf16_f32 v194, v194, v195
	v_cvt_pk_bf16_f32 v195, v192, v193
	global_store_dwordx2 v[190:191], v[194:195], off offset:96 sc1

.LBB0_1576:
	v_lshlrev_b64 v[192:193], 11, v[186:187]
	v_lshl_add_u64 v[192:193], s[0:1], 0, v[192:193]
	v_lshl_add_u64 v[192:193], s[72:73], 2, v[192:193]
	v_mov_b32_e32 v185, v173
	v_lshl_add_u64 v[192:193], v[192:193], 0, v[184:185]
	v_cmp_ne_u64_e32 vcc, 0, v[190:191]
	global_store_dwordx4 v[192:193], v[158:161], off sc1
	s_and_saveexec_b64 s[6:7], vcc
	s_xor_b64 s[6:7], exec, s[6:7]
	s_cbranch_execz .LBB0_1578
	global_store_dwordx4 v[190:191], v[158:161], off sc1
	global_store_dwordx4 v[192:193], v[154:157], off offset:64 sc1
	global_store_dwordx4 v[190:191], v[154:157], off offset:64 sc1
	global_store_dwordx4 v[192:193], v[150:153], off offset:128 sc1
	global_store_dwordx4 v[190:191], v[150:153], off offset:128 sc1
.LBB0_1578:
	s_or_saveexec_b64 s[6:7], s[6:7]
	v_mov_b64_e32 v[160:161], v[148:149]
	v_mov_b64_e32 v[194:195], 0xc0
	v_mov_b64_e32 v[158:159], v[146:147]
	s_xor_b64 exec, exec, s[6:7]
	s_cbranch_execz .LBB0_1580
	v_mov_b64_e32 v[160:161], v[152:153]
	v_mov_b64_e32 v[194:195], 0x80
	v_mov_b64_e32 v[158:159], v[150:151]
	v_mov_b64_e32 v[190:191], v[192:193]
	global_store_dwordx4 v[192:193], v[154:157], off offset:64 sc1
.LBB0_1580:
	s_or_b64 exec, exec, s[6:7]
	v_lshl_add_u64 v[150:151], v[192:193], 0, v[194:195]
	global_store_dwordx4 v[150:151], v[158:161], off sc1
	global_store_dwordx4 v[190:191], v[146:149], off offset:192 sc1
.LBB0_1581:
	s_nop 1
	v_pk_mul_f32 v[146:147], v[112:113], v[112:113]
	v_pk_mul_f32 v[148:149], v[110:111], v[110:111]
	v_or_b32_e32 v172, 16, v186
	v_pk_mov_b32 v[150:151], v[148:149], v[146:147] op_sel:[1,0]
	v_mov_b32_e32 v149, v147
	v_pk_add_f32 v[146:147], v[150:151], v[148:149]
	v_pk_mul_f32 v[148:149], v[108:109], v[108:109]
	v_pk_mul_f32 v[150:151], v[106:107], v[106:107]
	v_pk_add_f32 v[146:147], v[146:147], v[146:147] op_sel:[0,1] op_sel_hi:[1,0]
	v_pk_mov_b32 v[152:153], v[150:151], v[148:149] op_sel:[1,0]
	v_mov_b32_e32 v151, v149
	v_pk_add_f32 v[148:149], v[152:153], v[150:151]
	v_mul_f32_e32 v150, v98, v98
	v_mul_f32_e32 v151, v99, v99
	v_pk_add_f32 v[148:149], v[148:149], v[148:149] op_sel:[0,1] op_sel_hi:[1,0]
	v_mov_b32_e32 v147, v150
	v_mov_b32_e32 v149, v151
	v_pk_add_f32 v[146:147], v[146:147], v[148:149]
	v_mul_f32_e32 v148, v103, v103
	v_mul_f32_e32 v150, v105, v105
	v_mul_f32_e32 v152, v100, v100
	v_mul_f32_e32 v153, v101, v101
	v_pk_fma_f32 v[148:149], v[102:103], v[102:103], v[148:149] op_sel_hi:[1,1,0]
	v_pk_fma_f32 v[150:151], v[104:105], v[104:105], v[150:151] op_sel_hi:[1,1,0]
	v_mov_b32_e32 v149, v152
	v_mov_b32_e32 v151, v153
	v_pk_add_f32 v[148:149], v[148:149], v[150:151]
	s_mov_b64 s[40:41], -1
	v_pk_add_f32 v[146:147], v[146:147], v[148:149]
	s_nop 0
	v_add_f32_e32 v146, v146, v147
	ds_bpermute_b32 v147, v211, v146
	s_waitcnt lgkmcnt(0)
	v_add_f32_e32 v146, v146, v147
	ds_bpermute_b32 v147, v210, v146
	s_waitcnt lgkmcnt(0)
	v_add_f32_e32 v146, v146, v147
	v_fmamk_f32 v146, v146, 0x3c800000, v207
	v_cmp_gt_f32_e32 vcc, s10, v146
	v_mul_f32_e32 v147, 0x4f800000, v146
	s_nop 0
	v_cndmask_b32_e32 v146, v146, v147, vcc
	v_sqrt_f32_e32 v147, v146
	s_nop 0
	v_add_u32_e32 v148, -1, v147
	v_fma_f32 v149, -v148, v147, v146
	v_cmp_ge_f32_e64 s[6:7], 0, v149
	v_add_u32_e32 v149, 1, v147
	s_nop 0
	v_cndmask_b32_e64 v148, v147, v148, s[6:7]
	v_fma_f32 v147, -v149, v147, v146
	v_cmp_lt_f32_e64 s[6:7], 0, v147
	s_nop 1
	v_cndmask_b32_e64 v147, v148, v149, s[6:7]
	v_mul_f32_e32 v148, 0x37800000, v147
	v_cndmask_b32_e32 v147, v147, v148, vcc
	v_cmp_class_f32_e32 vcc, v146, v208
	s_nop 1
	v_cndmask_b32_e32 v146, v147, v146, vcc
	v_div_scale_f32 v147, s[6:7], v146, v146, 1.0
	v_rcp_f32_e32 v148, v147
	s_nop 0
	v_fma_f32 v149, -v147, v148, 1.0
	v_fmac_f32_e32 v148, v149, v148
	v_div_scale_f32 v149, vcc, 1.0, v146, 1.0
	v_mul_f32_e32 v150, v149, v148
	v_fma_f32 v151, -v147, v150, v149
	v_fmac_f32_e32 v150, v151, v148
	v_fma_f32 v147, -v147, v150, v149
	v_div_fmas_f32 v147, v147, v148, v150
	v_div_fixup_f32 v146, v147, v146, 1.0
	v_pk_mul_f32 v[148:149], v[110:111], v[146:147] op_sel_hi:[1,0]
	v_pk_mul_f32 v[150:151], v[112:113], v[146:147] op_sel_hi:[1,0]
	v_pk_mul_f32 v[158:159], v[142:143], v[148:149]
	v_pk_mul_f32 v[160:161], v[144:145], v[150:151]
	v_pk_mul_f32 v[148:149], v[106:107], v[146:147] op_sel_hi:[1,0]
	v_pk_mul_f32 v[150:151], v[108:109], v[146:147] op_sel_hi:[1,0]
	v_pk_mul_f32 v[154:155], v[104:105], v[146:147] op_sel_hi:[1,0]
	v_pk_mul_f32 v[152:153], v[140:141], v[150:151]
	v_pk_mul_f32 v[150:151], v[138:139], v[148:149]
	v_pk_mul_f32 v[148:149], v[102:103], v[146:147] op_sel_hi:[1,0]
	v_pk_mul_f32 v[190:191], v[98:99], v[146:147] op_sel_hi:[1,0]
	v_pk_mul_f32 v[146:147], v[100:101], v[146:147] op_sel_hi:[1,0]
	v_pk_mul_f32 v[156:157], v[136:137], v[154:155]
	v_pk_mul_f32 v[154:155], v[134:135], v[148:149]
	v_pk_mul_f32 v[148:149], v[132:133], v[146:147]
	v_pk_mul_f32 v[146:147], v[130:131], v[190:191]
	v_lshlrev_b64 v[190:191], 6, v[172:173]
	v_lshl_add_u64 v[194:195], v[178:179], 0, v[190:191]
	global_load_dwordx4 v[190:193], v[194:195], off
	s_nop 0
	global_load_dwordx4 v[194:197], v[194:195], off offset:32
	ds_bpermute_b32 v212, v210, v158
	ds_bpermute_b32 v213, v210, v159
	ds_bpermute_b32 v214, v210, v160
	ds_bpermute_b32 v215, v210, v161
	s_andn2_b64 vcc, exec, s[8:9]
	s_waitcnt vmcnt(0) lgkmcnt(2)
	v_pk_mul_f32 v[194:195], v[194:195], v[212:213]
	s_waitcnt lgkmcnt(0)
	v_pk_mul_f32 v[196:197], v[196:197], v[214:215]
	v_xor_b32_e32 v189, 0x80000000, v194
	v_xor_b32_e32 v185, 0x80000000, v196
	v_xor_b32_e32 v187, 0x80000000, v197
	v_xor_b32_e32 v212, 0x80000000, v195
	v_cndmask_b32_e64 v195, v195, v212, s[4:5]
	v_cndmask_b32_e64 v194, v194, v189, s[4:5]
	v_cndmask_b32_e64 v197, v197, v187, s[4:5]
	v_cndmask_b32_e64 v196, v196, v185, s[4:5]
	v_cndmask_b32_e64 v185, 0, 1, s[8:9]
	v_pk_fma_f32 v[160:161], v[192:193], v[160:161], v[196:197]
	v_pk_fma_f32 v[158:159], v[190:191], v[158:159], v[194:195]
	v_cmp_ne_u32_e64 s[6:7], 1, v185
	s_cbranch_vccnz .LBB0_1583
	v_readlane_b32 s8, v249, 9
	v_lshlrev_b64 v[190:191], 13, v[172:173]
	v_readlane_b32 s9, v249, 10
	v_mov_b32_e32 v189, v173
	v_pk_mul_f32 v[192:193], v[160:161], s[34:35] op_sel_hi:[1,0]
	v_lshl_add_u64 v[190:191], s[8:9], 0, v[190:191]
	v_lshl_add_u64 v[190:191], s[74:75], 1, v[190:191]
	v_pk_mul_f32 v[194:195], v[158:159], s[34:35] op_sel_hi:[1,0]
	v_lshl_add_u64 v[190:191], v[190:191], 0, v[188:189]
	v_cvt_pk_bf16_f32 v194, v194, v195
	v_cvt_pk_bf16_f32 v195, v192, v193
	global_store_dwordx2 v[190:191], v[194:195], off sc1
	v_pk_mul_f32 v[192:193], v[152:153], s[34:35] op_sel_hi:[1,0]
	v_pk_mul_f32 v[194:195], v[150:151], s[34:35] op_sel_hi:[1,0]
	s_mov_b64 s[40:41], 0
	v_cvt_pk_bf16_f32 v194, v194, v195
	v_cvt_pk_bf16_f32 v195, v192, v193
	global_store_dwordx2 v[190:191], v[194:195], off offset:32 sc1
	v_pk_mul_f32 v[192:193], v[156:157], s[34:35] op_sel_hi:[1,0]
	v_pk_mul_f32 v[194:195], v[154:155], s[34:35] op_sel_hi:[1,0]
	s_nop 0
	v_cvt_pk_bf16_f32 v194, v194, v195
	v_cvt_pk_bf16_f32 v195, v192, v193
	global_store_dwordx2 v[190:191], v[194:195], off offset:64 sc1
	v_pk_mul_f32 v[192:193], v[148:149], s[34:35] op_sel_hi:[1,0]
	v_pk_mul_f32 v[194:195], v[146:147], s[34:35] op_sel_hi:[1,0]
	s_nop 0
	v_cvt_pk_bf16_f32 v194, v194, v195
	v_cvt_pk_bf16_f32 v195, v192, v193
	global_store_dwordx2 v[190:191], v[194:195], off offset:96 sc1

.LBB0_1588:
	v_lshlrev_b64 v[192:193], 11, v[172:173]
	v_lshl_add_u64 v[192:193], s[0:1], 0, v[192:193]
	v_lshl_add_u64 v[192:193], s[72:73], 2, v[192:193]
	v_mov_b32_e32 v185, v173
	v_lshl_add_u64 v[192:193], v[192:193], 0, v[184:185]
	v_cmp_ne_u64_e32 vcc, 0, v[190:191]
	global_store_dwordx4 v[192:193], v[158:161], off sc1
	s_and_saveexec_b64 s[8:9], vcc
	s_xor_b64 s[8:9], exec, s[8:9]
	s_cbranch_execz .LBB0_1590
	global_store_dwordx4 v[190:191], v[158:161], off sc1
	global_store_dwordx4 v[192:193], v[150:153], off offset:64 sc1
	global_store_dwordx4 v[190:191], v[150:153], off offset:64 sc1
	global_store_dwordx4 v[192:193], v[154:157], off offset:128 sc1
	global_store_dwordx4 v[190:191], v[154:157], off offset:128 sc1
.LBB0_1590:
	s_or_saveexec_b64 s[8:9], s[8:9]
	v_mov_b64_e32 v[160:161], v[148:149]
	v_mov_b64_e32 v[194:195], 0xc0
	v_mov_b64_e32 v[158:159], v[146:147]
	s_xor_b64 exec, exec, s[8:9]
	s_cbranch_execz .LBB0_1592
	v_mov_b64_e32 v[160:161], v[156:157]
	v_mov_b64_e32 v[194:195], 0x80
	v_mov_b64_e32 v[158:159], v[154:155]
	v_mov_b64_e32 v[190:191], v[192:193]
	global_store_dwordx4 v[192:193], v[150:153], off offset:64 sc1
.LBB0_1592:
	s_or_b64 exec, exec, s[8:9]
	s_nop 0
	v_lshl_add_u64 v[150:151], v[192:193], 0, v[194:195]
	global_store_dwordx4 v[150:151], v[158:161], off sc1
	global_store_dwordx4 v[190:191], v[146:149], off offset:192 sc1
.LBB0_1593:
	s_nop 1
	v_pk_mul_f32 v[146:147], v[96:97], v[96:97]
	v_pk_mul_f32 v[148:149], v[94:95], v[94:95]
	v_or_b32_e32 v172, 32, v186
	v_pk_mov_b32 v[150:151], v[148:149], v[146:147] op_sel:[1,0]
	v_mov_b32_e32 v149, v147
	v_pk_add_f32 v[146:147], v[150:151], v[148:149]
	v_pk_mul_f32 v[148:149], v[92:93], v[92:93]
	v_pk_mul_f32 v[150:151], v[90:91], v[90:91]
	v_pk_add_f32 v[146:147], v[146:147], v[146:147] op_sel:[0,1] op_sel_hi:[1,0]
	v_pk_mov_b32 v[152:153], v[150:151], v[148:149] op_sel:[1,0]
	v_mov_b32_e32 v151, v149
	v_pk_add_f32 v[148:149], v[152:153], v[150:151]
	v_mul_f32_e32 v150, v82, v82
	v_mul_f32_e32 v151, v83, v83
	v_pk_add_f32 v[148:149], v[148:149], v[148:149] op_sel:[0,1] op_sel_hi:[1,0]
	v_mov_b32_e32 v147, v150
	v_mov_b32_e32 v149, v151
	v_pk_add_f32 v[146:147], v[146:147], v[148:149]
	v_mul_f32_e32 v148, v87, v87
	v_mul_f32_e32 v150, v89, v89
	v_mul_f32_e32 v152, v84, v84
	v_mul_f32_e32 v153, v85, v85
	v_pk_fma_f32 v[148:149], v[86:87], v[86:87], v[148:149] op_sel_hi:[1,1,0]
	v_pk_fma_f32 v[150:151], v[88:89], v[88:89], v[150:151] op_sel_hi:[1,1,0]
	v_mov_b32_e32 v149, v152
	v_mov_b32_e32 v151, v153
	v_pk_add_f32 v[148:149], v[148:149], v[150:151]
	s_nop 0
	v_pk_add_f32 v[146:147], v[146:147], v[148:149]
	s_nop 0
	v_add_f32_e32 v146, v146, v147
	ds_bpermute_b32 v147, v211, v146
	s_waitcnt lgkmcnt(0)
	v_add_f32_e32 v146, v146, v147
	ds_bpermute_b32 v147, v210, v146
	s_waitcnt lgkmcnt(0)
	v_add_f32_e32 v146, v146, v147
	v_fmamk_f32 v146, v146, 0x3c800000, v207
	v_cmp_gt_f32_e32 vcc, s10, v146
	v_mul_f32_e32 v147, 0x4f800000, v146
	s_nop 0
	v_cndmask_b32_e32 v146, v146, v147, vcc
	v_sqrt_f32_e32 v147, v146
	s_nop 0
	v_add_u32_e32 v148, -1, v147
	v_fma_f32 v149, -v148, v147, v146
	v_cmp_ge_f32_e64 s[8:9], 0, v149
	v_add_u32_e32 v149, 1, v147
	s_nop 0
	v_cndmask_b32_e64 v148, v147, v148, s[8:9]
	v_fma_f32 v147, -v149, v147, v146
	v_cmp_lt_f32_e64 s[8:9], 0, v147
	s_nop 1
	v_cndmask_b32_e64 v147, v148, v149, s[8:9]
	v_mul_f32_e32 v148, 0x37800000, v147
	v_cndmask_b32_e32 v147, v147, v148, vcc
	v_cmp_class_f32_e32 vcc, v146, v208
	s_nop 1
	v_cndmask_b32_e32 v146, v147, v146, vcc
	v_div_scale_f32 v147, s[8:9], v146, v146, 1.0
	v_rcp_f32_e32 v148, v147
	s_mov_b64 s[8:9], -1
	v_fma_f32 v149, -v147, v148, 1.0
	v_fmac_f32_e32 v148, v149, v148
	v_div_scale_f32 v149, vcc, 1.0, v146, 1.0
	v_mul_f32_e32 v150, v149, v148
	v_fma_f32 v151, -v147, v150, v149
	v_fmac_f32_e32 v150, v151, v148
	v_fma_f32 v147, -v147, v150, v149
	v_div_fmas_f32 v147, v147, v148, v150
	v_div_fixup_f32 v146, v147, v146, 1.0
	v_pk_mul_f32 v[148:149], v[94:95], v[146:147] op_sel_hi:[1,0]
	v_pk_mul_f32 v[150:151], v[96:97], v[146:147] op_sel_hi:[1,0]
	v_pk_mul_f32 v[158:159], v[142:143], v[148:149]
	v_pk_mul_f32 v[160:161], v[144:145], v[150:151]
	v_pk_mul_f32 v[148:149], v[90:91], v[146:147] op_sel_hi:[1,0]
	v_pk_mul_f32 v[150:151], v[92:93], v[146:147] op_sel_hi:[1,0]
	v_pk_mul_f32 v[154:155], v[88:89], v[146:147] op_sel_hi:[1,0]
	v_pk_mul_f32 v[152:153], v[140:141], v[150:151]
	v_pk_mul_f32 v[150:151], v[138:139], v[148:149]
	v_pk_mul_f32 v[148:149], v[86:87], v[146:147] op_sel_hi:[1,0]
	v_pk_mul_f32 v[190:191], v[82:83], v[146:147] op_sel_hi:[1,0]
	v_pk_mul_f32 v[146:147], v[84:85], v[146:147] op_sel_hi:[1,0]
	v_pk_mul_f32 v[156:157], v[136:137], v[154:155]
	v_pk_mul_f32 v[154:155], v[134:135], v[148:149]
	v_pk_mul_f32 v[148:149], v[132:133], v[146:147]
	v_pk_mul_f32 v[146:147], v[130:131], v[190:191]
	v_lshlrev_b64 v[190:191], 6, v[172:173]
	v_lshl_add_u64 v[194:195], v[178:179], 0, v[190:191]
	global_load_dwordx4 v[190:193], v[194:195], off
	s_nop 0
	global_load_dwordx4 v[194:197], v[194:195], off offset:32
	ds_bpermute_b32 v212, v210, v158
	ds_bpermute_b32 v213, v210, v159
	ds_bpermute_b32 v214, v210, v160
	ds_bpermute_b32 v215, v210, v161
	s_and_b64 vcc, exec, s[6:7]
	s_waitcnt vmcnt(0) lgkmcnt(2)
	v_pk_mul_f32 v[194:195], v[194:195], v[212:213]
	s_waitcnt lgkmcnt(0)
	v_pk_mul_f32 v[196:197], v[196:197], v[214:215]
	v_xor_b32_e32 v189, 0x80000000, v194
	v_xor_b32_e32 v185, 0x80000000, v196
	v_xor_b32_e32 v187, 0x80000000, v197
	v_xor_b32_e32 v212, 0x80000000, v195
	v_cndmask_b32_e64 v195, v195, v212, s[4:5]
	v_cndmask_b32_e64 v194, v194, v189, s[4:5]
	v_cndmask_b32_e64 v197, v197, v187, s[4:5]
	v_cndmask_b32_e64 v196, v196, v185, s[4:5]
	v_pk_fma_f32 v[160:161], v[192:193], v[160:161], v[196:197]
	v_pk_fma_f32 v[158:159], v[190:191], v[158:159], v[194:195]
	s_cbranch_vccnz .LBB0_1595
	v_readlane_b32 s8, v249, 9
	v_lshlrev_b64 v[190:191], 13, v[172:173]
	v_readlane_b32 s9, v249, 10
	v_mov_b32_e32 v189, v173
	v_pk_mul_f32 v[192:193], v[160:161], s[34:35] op_sel_hi:[1,0]
	v_lshl_add_u64 v[190:191], s[8:9], 0, v[190:191]
	v_lshl_add_u64 v[190:191], s[74:75], 1, v[190:191]
	v_pk_mul_f32 v[194:195], v[158:159], s[34:35] op_sel_hi:[1,0]
	v_lshl_add_u64 v[190:191], v[190:191], 0, v[188:189]
	v_cvt_pk_bf16_f32 v194, v194, v195
	v_cvt_pk_bf16_f32 v195, v192, v193
	global_store_dwordx2 v[190:191], v[194:195], off sc1
	v_pk_mul_f32 v[192:193], v[152:153], s[34:35] op_sel_hi:[1,0]
	v_pk_mul_f32 v[194:195], v[150:151], s[34:35] op_sel_hi:[1,0]
	s_mov_b64 s[8:9], 0
	v_cvt_pk_bf16_f32 v194, v194, v195
	v_cvt_pk_bf16_f32 v195, v192, v193
	global_store_dwordx2 v[190:191], v[194:195], off offset:32 sc1
	v_pk_mul_f32 v[192:193], v[156:157], s[34:35] op_sel_hi:[1,0]
	v_pk_mul_f32 v[194:195], v[154:155], s[34:35] op_sel_hi:[1,0]
	s_nop 0
	v_cvt_pk_bf16_f32 v194, v194, v195
	v_cvt_pk_bf16_f32 v195, v192, v193
	global_store_dwordx2 v[190:191], v[194:195], off offset:64 sc1
	v_pk_mul_f32 v[192:193], v[148:149], s[34:35] op_sel_hi:[1,0]
	v_pk_mul_f32 v[194:195], v[146:147], s[34:35] op_sel_hi:[1,0]
	s_nop 0
	v_cvt_pk_bf16_f32 v194, v194, v195
	v_cvt_pk_bf16_f32 v195, v192, v193
	global_store_dwordx2 v[190:191], v[194:195], off offset:96 sc1

.LBB0_1605:
	s_nop 1
	v_pk_mul_f32 v[146:147], v[80:81], v[80:81]
	v_pk_mul_f32 v[148:149], v[78:79], v[78:79]
	v_or_b32_e32 v172, 48, v186
	v_pk_mov_b32 v[150:151], v[148:149], v[146:147] op_sel:[1,0]
	v_mov_b32_e32 v149, v147
	v_pk_add_f32 v[146:147], v[150:151], v[148:149]
	v_pk_mul_f32 v[148:149], v[76:77], v[76:77]
	v_pk_mul_f32 v[150:151], v[74:75], v[74:75]
	v_pk_add_f32 v[146:147], v[146:147], v[146:147] op_sel:[0,1] op_sel_hi:[1,0]
	v_pk_mov_b32 v[152:153], v[150:151], v[148:149] op_sel:[1,0]
	v_mov_b32_e32 v151, v149
	v_pk_add_f32 v[148:149], v[152:153], v[150:151]
	v_mul_f32_e32 v150, v66, v66
	v_mul_f32_e32 v151, v67, v67
	v_pk_add_f32 v[148:149], v[148:149], v[148:149] op_sel:[0,1] op_sel_hi:[1,0]
	v_mov_b32_e32 v147, v150
	v_mov_b32_e32 v149, v151
	v_pk_add_f32 v[146:147], v[146:147], v[148:149]
	v_mul_f32_e32 v148, v71, v71
	v_mul_f32_e32 v150, v73, v73
	v_mul_f32_e32 v152, v68, v68
	v_mul_f32_e32 v153, v69, v69
	v_pk_fma_f32 v[148:149], v[70:71], v[70:71], v[148:149] op_sel_hi:[1,1,0]
	v_pk_fma_f32 v[150:151], v[72:73], v[72:73], v[150:151] op_sel_hi:[1,1,0]
	v_mov_b32_e32 v149, v152
	v_mov_b32_e32 v151, v153
	v_pk_add_f32 v[148:149], v[148:149], v[150:151]
	s_nop 0
	v_pk_add_f32 v[146:147], v[146:147], v[148:149]
	s_nop 0
	v_add_f32_e32 v146, v146, v147
	ds_bpermute_b32 v147, v211, v146
	s_waitcnt lgkmcnt(0)
	v_add_f32_e32 v146, v146, v147
	ds_bpermute_b32 v147, v210, v146
	s_waitcnt lgkmcnt(0)
	v_add_f32_e32 v146, v146, v147
	v_fmamk_f32 v146, v146, 0x3c800000, v207
	v_cmp_gt_f32_e32 vcc, s10, v146
	v_mul_f32_e32 v147, 0x4f800000, v146
	s_nop 0
	v_cndmask_b32_e32 v146, v146, v147, vcc
	v_sqrt_f32_e32 v147, v146
	s_nop 0
	v_add_u32_e32 v148, -1, v147
	v_fma_f32 v149, -v148, v147, v146
	v_cmp_ge_f32_e64 s[8:9], 0, v149
	v_add_u32_e32 v149, 1, v147
	s_nop 0
	v_cndmask_b32_e64 v148, v147, v148, s[8:9]
	v_fma_f32 v147, -v149, v147, v146
	v_cmp_lt_f32_e64 s[8:9], 0, v147
	s_nop 1
	v_cndmask_b32_e64 v147, v148, v149, s[8:9]
	v_mul_f32_e32 v148, 0x37800000, v147
	v_cndmask_b32_e32 v147, v147, v148, vcc
	v_cmp_class_f32_e32 vcc, v146, v208
	s_nop 1
	v_cndmask_b32_e32 v146, v147, v146, vcc
	v_div_scale_f32 v147, s[8:9], v146, v146, 1.0
	v_rcp_f32_e32 v148, v147
	s_mov_b64 s[8:9], -1
	v_fma_f32 v149, -v147, v148, 1.0
	v_fmac_f32_e32 v148, v149, v148
	v_div_scale_f32 v149, vcc, 1.0, v146, 1.0
	v_mul_f32_e32 v150, v149, v148
	v_fma_f32 v151, -v147, v150, v149
	v_fmac_f32_e32 v150, v151, v148
	v_fma_f32 v147, -v147, v150, v149
	v_div_fmas_f32 v147, v147, v148, v150
	v_div_fixup_f32 v146, v147, v146, 1.0
	v_pk_mul_f32 v[148:149], v[78:79], v[146:147] op_sel_hi:[1,0]
	v_pk_mul_f32 v[150:151], v[80:81], v[146:147] op_sel_hi:[1,0]
	v_pk_mul_f32 v[158:159], v[142:143], v[148:149]
	v_pk_mul_f32 v[160:161], v[144:145], v[150:151]
	v_pk_mul_f32 v[148:149], v[74:75], v[146:147] op_sel_hi:[1,0]
	v_pk_mul_f32 v[150:151], v[76:77], v[146:147] op_sel_hi:[1,0]
	v_pk_mul_f32 v[154:155], v[72:73], v[146:147] op_sel_hi:[1,0]
	v_pk_mul_f32 v[152:153], v[140:141], v[150:151]
	v_pk_mul_f32 v[150:151], v[138:139], v[148:149]
	v_pk_mul_f32 v[148:149], v[70:71], v[146:147] op_sel_hi:[1,0]
	v_pk_mul_f32 v[190:191], v[66:67], v[146:147] op_sel_hi:[1,0]
	v_pk_mul_f32 v[146:147], v[68:69], v[146:147] op_sel_hi:[1,0]
	v_pk_mul_f32 v[156:157], v[136:137], v[154:155]
	v_pk_mul_f32 v[154:155], v[134:135], v[148:149]
	v_pk_mul_f32 v[148:149], v[132:133], v[146:147]
	v_pk_mul_f32 v[146:147], v[130:131], v[190:191]
	v_lshlrev_b64 v[190:191], 6, v[172:173]
	v_lshl_add_u64 v[194:195], v[178:179], 0, v[190:191]
	global_load_dwordx4 v[190:193], v[194:195], off
	s_nop 0
	global_load_dwordx4 v[194:197], v[194:195], off offset:32
	ds_bpermute_b32 v212, v210, v158
	ds_bpermute_b32 v213, v210, v159
	ds_bpermute_b32 v214, v210, v160
	ds_bpermute_b32 v215, v210, v161
	s_and_b64 vcc, exec, s[6:7]
	s_waitcnt vmcnt(0) lgkmcnt(2)
	v_pk_mul_f32 v[194:195], v[194:195], v[212:213]
	s_waitcnt lgkmcnt(0)
	v_pk_mul_f32 v[196:197], v[196:197], v[214:215]
	v_xor_b32_e32 v189, 0x80000000, v194
	v_xor_b32_e32 v185, 0x80000000, v196
	v_xor_b32_e32 v187, 0x80000000, v197
	v_xor_b32_e32 v212, 0x80000000, v195
	v_cndmask_b32_e64 v195, v195, v212, s[4:5]
	v_cndmask_b32_e64 v194, v194, v189, s[4:5]
	v_cndmask_b32_e64 v197, v197, v187, s[4:5]
	v_cndmask_b32_e64 v196, v196, v185, s[4:5]
	v_pk_fma_f32 v[160:161], v[192:193], v[160:161], v[196:197]
	v_pk_fma_f32 v[158:159], v[190:191], v[158:159], v[194:195]
	s_cbranch_vccnz .LBB0_1607
	v_readlane_b32 s8, v249, 9
	v_lshlrev_b64 v[190:191], 13, v[172:173]
	v_readlane_b32 s9, v249, 10
	v_mov_b32_e32 v189, v173
	v_pk_mul_f32 v[192:193], v[160:161], s[34:35] op_sel_hi:[1,0]
	v_lshl_add_u64 v[190:191], s[8:9], 0, v[190:191]
	v_lshl_add_u64 v[190:191], s[74:75], 1, v[190:191]
	v_pk_mul_f32 v[194:195], v[158:159], s[34:35] op_sel_hi:[1,0]
	v_lshl_add_u64 v[190:191], v[190:191], 0, v[188:189]
	v_cvt_pk_bf16_f32 v194, v194, v195
	v_cvt_pk_bf16_f32 v195, v192, v193
	global_store_dwordx2 v[190:191], v[194:195], off sc1
	v_pk_mul_f32 v[192:193], v[152:153], s[34:35] op_sel_hi:[1,0]
	v_pk_mul_f32 v[194:195], v[150:151], s[34:35] op_sel_hi:[1,0]
	s_mov_b64 s[8:9], 0
	v_cvt_pk_bf16_f32 v194, v194, v195
	v_cvt_pk_bf16_f32 v195, v192, v193
	global_store_dwordx2 v[190:191], v[194:195], off offset:32 sc1
	v_pk_mul_f32 v[192:193], v[156:157], s[34:35] op_sel_hi:[1,0]
	v_pk_mul_f32 v[194:195], v[154:155], s[34:35] op_sel_hi:[1,0]
	s_nop 0
	v_cvt_pk_bf16_f32 v194, v194, v195
	v_cvt_pk_bf16_f32 v195, v192, v193
	global_store_dwordx2 v[190:191], v[194:195], off offset:64 sc1
	v_pk_mul_f32 v[192:193], v[148:149], s[34:35] op_sel_hi:[1,0]
	v_pk_mul_f32 v[194:195], v[146:147], s[34:35] op_sel_hi:[1,0]
	s_nop 0
	v_cvt_pk_bf16_f32 v194, v194, v195
	v_cvt_pk_bf16_f32 v195, v192, v193
	global_store_dwordx2 v[190:191], v[194:195], off offset:96 sc1

.LBB0_1617:
	s_nop 1
	v_pk_mul_f32 v[146:147], v[64:65], v[64:65]
	v_pk_mul_f32 v[148:149], v[62:63], v[62:63]
	v_add_u32_e32 v172, 0x80, v186
	v_pk_mov_b32 v[150:151], v[148:149], v[146:147] op_sel:[1,0]
	v_mov_b32_e32 v149, v147
	v_pk_add_f32 v[146:147], v[150:151], v[148:149]
	v_pk_mul_f32 v[148:149], v[60:61], v[60:61]
	v_pk_mul_f32 v[150:151], v[58:59], v[58:59]
	v_pk_add_f32 v[146:147], v[146:147], v[146:147] op_sel:[0,1] op_sel_hi:[1,0]
	v_pk_mov_b32 v[152:153], v[150:151], v[148:149] op_sel:[1,0]
	v_mov_b32_e32 v151, v149
	v_pk_add_f32 v[148:149], v[152:153], v[150:151]
	v_mul_f32_e32 v150, v50, v50
	v_mul_f32_e32 v151, v51, v51
	v_pk_add_f32 v[148:149], v[148:149], v[148:149] op_sel:[0,1] op_sel_hi:[1,0]
	v_mov_b32_e32 v147, v150
	v_mov_b32_e32 v149, v151
	v_pk_add_f32 v[146:147], v[146:147], v[148:149]
	v_mul_f32_e32 v148, v55, v55
	v_mul_f32_e32 v150, v57, v57
	v_mul_f32_e32 v152, v52, v52
	v_mul_f32_e32 v153, v53, v53
	v_pk_fma_f32 v[148:149], v[54:55], v[54:55], v[148:149] op_sel_hi:[1,1,0]
	v_pk_fma_f32 v[150:151], v[56:57], v[56:57], v[150:151] op_sel_hi:[1,1,0]
	v_mov_b32_e32 v149, v152
	v_mov_b32_e32 v151, v153
	v_pk_add_f32 v[148:149], v[148:149], v[150:151]
	s_nop 0
	v_pk_add_f32 v[146:147], v[146:147], v[148:149]
	s_nop 0
	v_add_f32_e32 v146, v146, v147
	ds_bpermute_b32 v147, v211, v146
	s_waitcnt lgkmcnt(0)
	v_add_f32_e32 v146, v146, v147
	ds_bpermute_b32 v147, v210, v146
	s_waitcnt lgkmcnt(0)
	v_add_f32_e32 v146, v146, v147
	v_fmamk_f32 v146, v146, 0x3c800000, v207
	v_cmp_gt_f32_e32 vcc, s10, v146
	v_mul_f32_e32 v147, 0x4f800000, v146
	s_nop 0
	v_cndmask_b32_e32 v146, v146, v147, vcc
	v_sqrt_f32_e32 v147, v146
	s_nop 0
	v_add_u32_e32 v148, -1, v147
	v_fma_f32 v149, -v148, v147, v146
	v_cmp_ge_f32_e64 s[8:9], 0, v149
	v_add_u32_e32 v149, 1, v147
	s_nop 0
	v_cndmask_b32_e64 v148, v147, v148, s[8:9]
	v_fma_f32 v147, -v149, v147, v146
	v_cmp_lt_f32_e64 s[8:9], 0, v147
	s_nop 1
	v_cndmask_b32_e64 v147, v148, v149, s[8:9]
	v_mul_f32_e32 v148, 0x37800000, v147
	v_cndmask_b32_e32 v147, v147, v148, vcc
	v_cmp_class_f32_e32 vcc, v146, v208
	s_nop 1
	v_cndmask_b32_e32 v146, v147, v146, vcc
	v_div_scale_f32 v147, s[8:9], v146, v146, 1.0
	v_rcp_f32_e32 v148, v147
	s_mov_b64 s[8:9], -1
	v_fma_f32 v149, -v147, v148, 1.0
	v_fmac_f32_e32 v148, v149, v148
	v_div_scale_f32 v149, vcc, 1.0, v146, 1.0
	v_mul_f32_e32 v150, v149, v148
	v_fma_f32 v151, -v147, v150, v149
	v_fmac_f32_e32 v150, v151, v148
	v_fma_f32 v147, -v147, v150, v149
	v_div_fmas_f32 v147, v147, v148, v150
	v_div_fixup_f32 v146, v147, v146, 1.0
	v_pk_mul_f32 v[148:149], v[62:63], v[146:147] op_sel_hi:[1,0]
	v_pk_mul_f32 v[150:151], v[64:65], v[146:147] op_sel_hi:[1,0]
	v_pk_mul_f32 v[158:159], v[142:143], v[148:149]
	v_pk_mul_f32 v[160:161], v[144:145], v[150:151]
	v_pk_mul_f32 v[148:149], v[58:59], v[146:147] op_sel_hi:[1,0]
	v_pk_mul_f32 v[150:151], v[60:61], v[146:147] op_sel_hi:[1,0]
	v_pk_mul_f32 v[154:155], v[56:57], v[146:147] op_sel_hi:[1,0]
	v_pk_mul_f32 v[152:153], v[140:141], v[150:151]
	v_pk_mul_f32 v[150:151], v[138:139], v[148:149]
	v_pk_mul_f32 v[148:149], v[54:55], v[146:147] op_sel_hi:[1,0]
	v_pk_mul_f32 v[190:191], v[50:51], v[146:147] op_sel_hi:[1,0]
	v_pk_mul_f32 v[146:147], v[52:53], v[146:147] op_sel_hi:[1,0]
	v_pk_mul_f32 v[156:157], v[136:137], v[154:155]
	v_pk_mul_f32 v[154:155], v[134:135], v[148:149]
	v_pk_mul_f32 v[148:149], v[132:133], v[146:147]
	v_pk_mul_f32 v[146:147], v[130:131], v[190:191]
	v_lshlrev_b64 v[190:191], 6, v[172:173]
	v_lshl_add_u64 v[194:195], v[178:179], 0, v[190:191]
	global_load_dwordx4 v[190:193], v[194:195], off
	s_nop 0
	global_load_dwordx4 v[194:197], v[194:195], off offset:32
	ds_bpermute_b32 v212, v210, v158
	ds_bpermute_b32 v213, v210, v159
	ds_bpermute_b32 v214, v210, v160
	ds_bpermute_b32 v215, v210, v161
	s_and_b64 vcc, exec, s[6:7]
	s_waitcnt vmcnt(0) lgkmcnt(2)
	v_pk_mul_f32 v[194:195], v[194:195], v[212:213]
	s_waitcnt lgkmcnt(0)
	v_pk_mul_f32 v[196:197], v[196:197], v[214:215]
	v_xor_b32_e32 v189, 0x80000000, v194
	v_xor_b32_e32 v185, 0x80000000, v196
	v_xor_b32_e32 v187, 0x80000000, v197
	v_xor_b32_e32 v212, 0x80000000, v195
	v_cndmask_b32_e64 v195, v195, v212, s[4:5]
	v_cndmask_b32_e64 v194, v194, v189, s[4:5]
	v_cndmask_b32_e64 v197, v197, v187, s[4:5]
	v_cndmask_b32_e64 v196, v196, v185, s[4:5]
	v_pk_fma_f32 v[160:161], v[192:193], v[160:161], v[196:197]
	v_pk_fma_f32 v[158:159], v[190:191], v[158:159], v[194:195]
	s_cbranch_vccnz .LBB0_1619
	v_readlane_b32 s8, v249, 9
	v_lshlrev_b64 v[190:191], 13, v[172:173]
	v_readlane_b32 s9, v249, 10
	v_mov_b32_e32 v189, v173
	v_pk_mul_f32 v[192:193], v[160:161], s[34:35] op_sel_hi:[1,0]
	v_lshl_add_u64 v[190:191], s[8:9], 0, v[190:191]
	v_lshl_add_u64 v[190:191], s[74:75], 1, v[190:191]
	v_pk_mul_f32 v[194:195], v[158:159], s[34:35] op_sel_hi:[1,0]
	v_lshl_add_u64 v[190:191], v[190:191], 0, v[188:189]
	v_cvt_pk_bf16_f32 v194, v194, v195
	v_cvt_pk_bf16_f32 v195, v192, v193
	global_store_dwordx2 v[190:191], v[194:195], off sc1
	v_pk_mul_f32 v[192:193], v[152:153], s[34:35] op_sel_hi:[1,0]
	v_pk_mul_f32 v[194:195], v[150:151], s[34:35] op_sel_hi:[1,0]
	s_mov_b64 s[8:9], 0
	v_cvt_pk_bf16_f32 v194, v194, v195
	v_cvt_pk_bf16_f32 v195, v192, v193
	global_store_dwordx2 v[190:191], v[194:195], off offset:32 sc1
	v_pk_mul_f32 v[192:193], v[156:157], s[34:35] op_sel_hi:[1,0]
	v_pk_mul_f32 v[194:195], v[154:155], s[34:35] op_sel_hi:[1,0]
	s_nop 0
	v_cvt_pk_bf16_f32 v194, v194, v195
	v_cvt_pk_bf16_f32 v195, v192, v193
	global_store_dwordx2 v[190:191], v[194:195], off offset:64 sc1
	v_pk_mul_f32 v[192:193], v[148:149], s[34:35] op_sel_hi:[1,0]
	v_pk_mul_f32 v[194:195], v[146:147], s[34:35] op_sel_hi:[1,0]
	s_nop 0
	v_cvt_pk_bf16_f32 v194, v194, v195
	v_cvt_pk_bf16_f32 v195, v192, v193
	global_store_dwordx2 v[190:191], v[194:195], off offset:96 sc1

.LBB0_1624:
	v_lshlrev_b64 v[194:195], 11, v[172:173]
	v_lshl_add_u64 v[194:195], s[0:1], 0, v[194:195]
	v_lshl_add_u64 v[194:195], s[72:73], 2, v[194:195]
	v_mov_b32_e32 v185, v173
	v_lshl_add_u64 v[194:195], v[194:195], 0, v[184:185]
	v_cmp_ne_u64_e32 vcc, 0, v[192:193]
	global_store_dwordx4 v[194:195], v[158:161], off sc1
	s_and_saveexec_b64 s[8:9], vcc
	s_xor_b64 s[8:9], exec, s[8:9]
	s_cbranch_execz .LBB0_1626
	global_store_dwordx4 v[192:193], v[158:161], off sc1
	global_store_dwordx4 v[194:195], v[150:153], off offset:64 sc1
	global_store_dwordx4 v[192:193], v[150:153], off offset:64 sc1
	global_store_dwordx4 v[194:195], v[154:157], off offset:128 sc1
	global_store_dwordx4 v[192:193], v[154:157], off offset:128 sc1
.LBB0_1626:
	s_or_saveexec_b64 s[8:9], s[8:9]
	v_mov_b64_e32 v[160:161], v[148:149]
	v_mov_b64_e32 v[196:197], 0xc0
	v_mov_b64_e32 v[158:159], v[146:147]
	s_xor_b64 exec, exec, s[8:9]
	s_cbranch_execz .LBB0_1628
	v_mov_b64_e32 v[160:161], v[156:157]
	v_mov_b64_e32 v[196:197], 0x80
	v_mov_b64_e32 v[158:159], v[154:155]
	v_mov_b64_e32 v[192:193], v[194:195]
	global_store_dwordx4 v[194:195], v[150:153], off offset:64 sc1
.LBB0_1628:
	s_or_b64 exec, exec, s[8:9]
	s_nop 0
	v_lshl_add_u64 v[150:151], v[194:195], 0, v[196:197]
	global_store_dwordx4 v[150:151], v[158:161], off sc1
	global_store_dwordx4 v[192:193], v[146:149], off offset:192 sc1
.LBB0_1629:
	s_nop 1
	v_pk_mul_f32 v[146:147], v[48:49], v[48:49]
	v_pk_mul_f32 v[148:149], v[46:47], v[46:47]
	v_add_u32_e32 v172, 0x90, v186
	v_pk_mov_b32 v[150:151], v[148:149], v[146:147] op_sel:[1,0]
	v_mov_b32_e32 v149, v147
	v_pk_add_f32 v[146:147], v[150:151], v[148:149]
	v_pk_mul_f32 v[148:149], v[44:45], v[44:45]
	v_pk_mul_f32 v[150:151], v[42:43], v[42:43]
	v_pk_add_f32 v[146:147], v[146:147], v[146:147] op_sel:[0,1] op_sel_hi:[1,0]
	v_pk_mov_b32 v[152:153], v[150:151], v[148:149] op_sel:[1,0]
	v_mov_b32_e32 v151, v149
	v_pk_add_f32 v[148:149], v[152:153], v[150:151]
	v_mul_f32_e32 v150, v34, v34
	v_mul_f32_e32 v151, v35, v35
	v_pk_add_f32 v[148:149], v[148:149], v[148:149] op_sel:[0,1] op_sel_hi:[1,0]
	v_mov_b32_e32 v147, v150
	v_mov_b32_e32 v149, v151
	v_pk_add_f32 v[146:147], v[146:147], v[148:149]
	v_mul_f32_e32 v148, v39, v39
	v_mul_f32_e32 v150, v41, v41
	v_mul_f32_e32 v152, v36, v36
	v_mul_f32_e32 v153, v37, v37
	v_pk_fma_f32 v[148:149], v[38:39], v[38:39], v[148:149] op_sel_hi:[1,1,0]
	v_pk_fma_f32 v[150:151], v[40:41], v[40:41], v[150:151] op_sel_hi:[1,1,0]
	v_mov_b32_e32 v149, v152
	v_mov_b32_e32 v151, v153
	v_pk_add_f32 v[148:149], v[148:149], v[150:151]
	s_nop 0
	v_pk_add_f32 v[146:147], v[146:147], v[148:149]
	s_nop 0
	v_add_f32_e32 v146, v146, v147
	ds_bpermute_b32 v147, v211, v146
	s_waitcnt lgkmcnt(0)
	v_add_f32_e32 v146, v146, v147
	ds_bpermute_b32 v147, v210, v146
	s_waitcnt lgkmcnt(0)
	v_add_f32_e32 v146, v146, v147
	v_fmamk_f32 v146, v146, 0x3c800000, v207
	v_cmp_gt_f32_e32 vcc, s10, v146
	v_mul_f32_e32 v147, 0x4f800000, v146
	s_nop 0
	v_cndmask_b32_e32 v146, v146, v147, vcc
	v_sqrt_f32_e32 v147, v146
	s_nop 0
	v_add_u32_e32 v148, -1, v147
	v_fma_f32 v149, -v148, v147, v146
	v_cmp_ge_f32_e64 s[8:9], 0, v149
	v_add_u32_e32 v149, 1, v147
	s_nop 0
	v_cndmask_b32_e64 v148, v147, v148, s[8:9]
	v_fma_f32 v147, -v149, v147, v146
	v_cmp_lt_f32_e64 s[8:9], 0, v147
	s_nop 1
	v_cndmask_b32_e64 v147, v148, v149, s[8:9]
	v_mul_f32_e32 v148, 0x37800000, v147
	v_cndmask_b32_e32 v147, v147, v148, vcc
	v_cmp_class_f32_e32 vcc, v146, v208
	s_nop 1
	v_cndmask_b32_e32 v146, v147, v146, vcc
	v_div_scale_f32 v147, s[8:9], v146, v146, 1.0
	v_rcp_f32_e32 v148, v147
	s_mov_b64 s[8:9], -1
	v_fma_f32 v149, -v147, v148, 1.0
	v_fmac_f32_e32 v148, v149, v148
	v_div_scale_f32 v149, vcc, 1.0, v146, 1.0
	v_mul_f32_e32 v150, v149, v148
	v_fma_f32 v151, -v147, v150, v149
	v_fmac_f32_e32 v150, v151, v148
	v_fma_f32 v147, -v147, v150, v149
	v_div_fmas_f32 v147, v147, v148, v150
	v_div_fixup_f32 v146, v147, v146, 1.0
	v_pk_mul_f32 v[148:149], v[46:47], v[146:147] op_sel_hi:[1,0]
	v_pk_mul_f32 v[150:151], v[48:49], v[146:147] op_sel_hi:[1,0]
	v_pk_mul_f32 v[158:159], v[142:143], v[148:149]
	v_pk_mul_f32 v[160:161], v[144:145], v[150:151]
	v_pk_mul_f32 v[148:149], v[42:43], v[146:147] op_sel_hi:[1,0]
	v_pk_mul_f32 v[150:151], v[44:45], v[146:147] op_sel_hi:[1,0]
	v_pk_mul_f32 v[154:155], v[40:41], v[146:147] op_sel_hi:[1,0]
	v_pk_mul_f32 v[152:153], v[140:141], v[150:151]
	v_pk_mul_f32 v[150:151], v[138:139], v[148:149]
	v_pk_mul_f32 v[148:149], v[38:39], v[146:147] op_sel_hi:[1,0]
	v_pk_mul_f32 v[192:193], v[34:35], v[146:147] op_sel_hi:[1,0]
	v_pk_mul_f32 v[146:147], v[36:37], v[146:147] op_sel_hi:[1,0]
	v_pk_mul_f32 v[156:157], v[136:137], v[154:155]
	v_pk_mul_f32 v[154:155], v[134:135], v[148:149]
	v_pk_mul_f32 v[148:149], v[132:133], v[146:147]
	v_pk_mul_f32 v[146:147], v[130:131], v[192:193]
	v_lshlrev_b64 v[192:193], 6, v[172:173]
	v_lshl_add_u64 v[196:197], v[178:179], 0, v[192:193]
	global_load_dwordx4 v[192:195], v[196:197], off
	global_load_dwordx4 v[212:215], v[196:197], off offset:32
	ds_bpermute_b32 v196, v210, v158
	ds_bpermute_b32 v197, v210, v159
	ds_bpermute_b32 v216, v210, v160
	ds_bpermute_b32 v217, v210, v161
	s_and_b64 vcc, exec, s[6:7]
	s_waitcnt vmcnt(0) lgkmcnt(2)
	v_pk_mul_f32 v[196:197], v[212:213], v[196:197]
	s_waitcnt lgkmcnt(0)
	v_pk_mul_f32 v[212:213], v[214:215], v[216:217]
	v_xor_b32_e32 v189, 0x80000000, v196
	v_xor_b32_e32 v185, 0x80000000, v212
	v_xor_b32_e32 v187, 0x80000000, v213
	v_xor_b32_e32 v214, 0x80000000, v197
	v_cndmask_b32_e64 v197, v197, v214, s[4:5]
	v_cndmask_b32_e64 v196, v196, v189, s[4:5]
	v_cndmask_b32_e64 v213, v213, v187, s[4:5]
	v_cndmask_b32_e64 v212, v212, v185, s[4:5]
	v_pk_fma_f32 v[160:161], v[194:195], v[160:161], v[212:213]
	v_pk_fma_f32 v[158:159], v[192:193], v[158:159], v[196:197]
	s_cbranch_vccnz .LBB0_1631
	v_readlane_b32 s8, v249, 9
	v_lshlrev_b64 v[192:193], 13, v[172:173]
	v_readlane_b32 s9, v249, 10
	v_mov_b32_e32 v189, v173
	v_pk_mul_f32 v[194:195], v[160:161], s[34:35] op_sel_hi:[1,0]
	v_lshl_add_u64 v[192:193], s[8:9], 0, v[192:193]
	v_lshl_add_u64 v[192:193], s[74:75], 1, v[192:193]
	v_pk_mul_f32 v[196:197], v[158:159], s[34:35] op_sel_hi:[1,0]
	v_lshl_add_u64 v[192:193], v[192:193], 0, v[188:189]
	v_cvt_pk_bf16_f32 v196, v196, v197
	v_cvt_pk_bf16_f32 v197, v194, v195
	global_store_dwordx2 v[192:193], v[196:197], off sc1
	v_pk_mul_f32 v[194:195], v[152:153], s[34:35] op_sel_hi:[1,0]
	v_pk_mul_f32 v[196:197], v[150:151], s[34:35] op_sel_hi:[1,0]
	s_mov_b64 s[8:9], 0
	v_cvt_pk_bf16_f32 v196, v196, v197
	v_cvt_pk_bf16_f32 v197, v194, v195
	global_store_dwordx2 v[192:193], v[196:197], off offset:32 sc1
	v_pk_mul_f32 v[194:195], v[156:157], s[34:35] op_sel_hi:[1,0]
	v_pk_mul_f32 v[196:197], v[154:155], s[34:35] op_sel_hi:[1,0]
	s_nop 0
	v_cvt_pk_bf16_f32 v196, v196, v197
	v_cvt_pk_bf16_f32 v197, v194, v195
	global_store_dwordx2 v[192:193], v[196:197], off offset:64 sc1
	v_pk_mul_f32 v[194:195], v[148:149], s[34:35] op_sel_hi:[1,0]
	v_pk_mul_f32 v[196:197], v[146:147], s[34:35] op_sel_hi:[1,0]
	s_nop 0
	v_cvt_pk_bf16_f32 v196, v196, v197
	v_cvt_pk_bf16_f32 v197, v194, v195
	global_store_dwordx2 v[192:193], v[196:197], off offset:96 sc1

.LBB0_1641:
	s_nop 1
	v_pk_mul_f32 v[146:147], v[32:33], v[32:33]
	v_pk_mul_f32 v[148:149], v[30:31], v[30:31]
	v_add_u32_e32 v172, 0xa0, v186
	v_pk_mov_b32 v[150:151], v[148:149], v[146:147] op_sel:[1,0]
	v_mov_b32_e32 v149, v147
	v_pk_add_f32 v[146:147], v[150:151], v[148:149]
	v_pk_mul_f32 v[148:149], v[28:29], v[28:29]
	v_pk_mul_f32 v[150:151], v[26:27], v[26:27]
	v_pk_add_f32 v[146:147], v[146:147], v[146:147] op_sel:[0,1] op_sel_hi:[1,0]
	v_pk_mov_b32 v[152:153], v[150:151], v[148:149] op_sel:[1,0]
	v_mov_b32_e32 v151, v149
	v_pk_add_f32 v[148:149], v[152:153], v[150:151]
	v_mul_f32_e32 v150, v18, v18
	v_mul_f32_e32 v151, v19, v19
	v_pk_add_f32 v[148:149], v[148:149], v[148:149] op_sel:[0,1] op_sel_hi:[1,0]
	v_mov_b32_e32 v147, v150
	v_mov_b32_e32 v149, v151
	v_pk_add_f32 v[146:147], v[146:147], v[148:149]
	v_mul_f32_e32 v148, v23, v23
	v_mul_f32_e32 v150, v25, v25
	v_mul_f32_e32 v152, v20, v20
	v_mul_f32_e32 v153, v21, v21
	v_pk_fma_f32 v[148:149], v[22:23], v[22:23], v[148:149] op_sel_hi:[1,1,0]
	v_pk_fma_f32 v[150:151], v[24:25], v[24:25], v[150:151] op_sel_hi:[1,1,0]
	v_mov_b32_e32 v149, v152
	v_mov_b32_e32 v151, v153
	v_pk_add_f32 v[148:149], v[148:149], v[150:151]
	s_nop 0
	v_pk_add_f32 v[146:147], v[146:147], v[148:149]
	s_nop 0
	v_add_f32_e32 v146, v146, v147
	ds_bpermute_b32 v147, v211, v146
	s_waitcnt lgkmcnt(0)
	v_add_f32_e32 v146, v146, v147
	ds_bpermute_b32 v147, v210, v146
	s_waitcnt lgkmcnt(0)
	v_add_f32_e32 v146, v146, v147
	v_fmamk_f32 v146, v146, 0x3c800000, v207
	v_cmp_gt_f32_e32 vcc, s10, v146
	v_mul_f32_e32 v147, 0x4f800000, v146
	s_nop 0
	v_cndmask_b32_e32 v146, v146, v147, vcc
	v_sqrt_f32_e32 v147, v146
	s_nop 0
	v_add_u32_e32 v148, -1, v147
	v_fma_f32 v149, -v148, v147, v146
	v_cmp_ge_f32_e64 s[8:9], 0, v149
	v_add_u32_e32 v149, 1, v147
	s_nop 0
	v_cndmask_b32_e64 v148, v147, v148, s[8:9]
	v_fma_f32 v147, -v149, v147, v146
	v_cmp_lt_f32_e64 s[8:9], 0, v147
	s_nop 1
	v_cndmask_b32_e64 v147, v148, v149, s[8:9]
	v_mul_f32_e32 v148, 0x37800000, v147
	v_cndmask_b32_e32 v147, v147, v148, vcc
	v_cmp_class_f32_e32 vcc, v146, v208
	s_nop 1
	v_cndmask_b32_e32 v146, v147, v146, vcc
	v_div_scale_f32 v147, s[8:9], v146, v146, 1.0
	v_rcp_f32_e32 v148, v147
	s_mov_b64 s[8:9], -1
	v_fma_f32 v149, -v147, v148, 1.0
	v_fmac_f32_e32 v148, v149, v148
	v_div_scale_f32 v149, vcc, 1.0, v146, 1.0
	v_mul_f32_e32 v150, v149, v148
	v_fma_f32 v151, -v147, v150, v149
	v_fmac_f32_e32 v150, v151, v148
	v_fma_f32 v147, -v147, v150, v149
	v_div_fmas_f32 v147, v147, v148, v150
	v_div_fixup_f32 v146, v147, v146, 1.0
	v_pk_mul_f32 v[148:149], v[30:31], v[146:147] op_sel_hi:[1,0]
	v_pk_mul_f32 v[150:151], v[32:33], v[146:147] op_sel_hi:[1,0]
	v_pk_mul_f32 v[158:159], v[142:143], v[148:149]
	v_pk_mul_f32 v[160:161], v[144:145], v[150:151]
	v_pk_mul_f32 v[148:149], v[26:27], v[146:147] op_sel_hi:[1,0]
	v_pk_mul_f32 v[150:151], v[28:29], v[146:147] op_sel_hi:[1,0]
	v_pk_mul_f32 v[154:155], v[24:25], v[146:147] op_sel_hi:[1,0]
	v_pk_mul_f32 v[152:153], v[140:141], v[150:151]
	v_pk_mul_f32 v[150:151], v[138:139], v[148:149]
	v_pk_mul_f32 v[148:149], v[22:23], v[146:147] op_sel_hi:[1,0]
	v_pk_mul_f32 v[192:193], v[18:19], v[146:147] op_sel_hi:[1,0]
	v_pk_mul_f32 v[146:147], v[20:21], v[146:147] op_sel_hi:[1,0]
	v_pk_mul_f32 v[156:157], v[136:137], v[154:155]
	v_pk_mul_f32 v[154:155], v[134:135], v[148:149]
	v_pk_mul_f32 v[148:149], v[132:133], v[146:147]
	v_pk_mul_f32 v[146:147], v[130:131], v[192:193]
	v_lshlrev_b64 v[192:193], 6, v[172:173]
	v_lshl_add_u64 v[196:197], v[178:179], 0, v[192:193]
	global_load_dwordx4 v[192:195], v[196:197], off
	global_load_dwordx4 v[212:215], v[196:197], off offset:32
	ds_bpermute_b32 v196, v210, v158
	ds_bpermute_b32 v197, v210, v159
	ds_bpermute_b32 v216, v210, v160
	ds_bpermute_b32 v217, v210, v161
	s_and_b64 vcc, exec, s[6:7]
	s_waitcnt vmcnt(0) lgkmcnt(2)
	v_pk_mul_f32 v[196:197], v[212:213], v[196:197]
	s_waitcnt lgkmcnt(0)
	v_pk_mul_f32 v[212:213], v[214:215], v[216:217]
	v_xor_b32_e32 v189, 0x80000000, v196
	v_xor_b32_e32 v185, 0x80000000, v212
	v_xor_b32_e32 v187, 0x80000000, v213
	v_xor_b32_e32 v214, 0x80000000, v197
	v_cndmask_b32_e64 v197, v197, v214, s[4:5]
	v_cndmask_b32_e64 v196, v196, v189, s[4:5]
	v_cndmask_b32_e64 v213, v213, v187, s[4:5]
	v_cndmask_b32_e64 v212, v212, v185, s[4:5]
	v_pk_fma_f32 v[160:161], v[194:195], v[160:161], v[212:213]
	v_pk_fma_f32 v[158:159], v[192:193], v[158:159], v[196:197]
	s_cbranch_vccnz .LBB0_1643
	v_readlane_b32 s8, v249, 9
	v_lshlrev_b64 v[192:193], 13, v[172:173]
	v_readlane_b32 s9, v249, 10
	v_mov_b32_e32 v189, v173
	v_pk_mul_f32 v[194:195], v[160:161], s[34:35] op_sel_hi:[1,0]
	v_lshl_add_u64 v[192:193], s[8:9], 0, v[192:193]
	v_lshl_add_u64 v[192:193], s[74:75], 1, v[192:193]
	v_pk_mul_f32 v[196:197], v[158:159], s[34:35] op_sel_hi:[1,0]
	v_lshl_add_u64 v[192:193], v[192:193], 0, v[188:189]
	v_cvt_pk_bf16_f32 v196, v196, v197
	v_cvt_pk_bf16_f32 v197, v194, v195
	global_store_dwordx2 v[192:193], v[196:197], off sc1
	v_pk_mul_f32 v[194:195], v[152:153], s[34:35] op_sel_hi:[1,0]
	v_pk_mul_f32 v[196:197], v[150:151], s[34:35] op_sel_hi:[1,0]
	s_mov_b64 s[8:9], 0
	v_cvt_pk_bf16_f32 v196, v196, v197
	v_cvt_pk_bf16_f32 v197, v194, v195
	global_store_dwordx2 v[192:193], v[196:197], off offset:32 sc1
	v_pk_mul_f32 v[194:195], v[156:157], s[34:35] op_sel_hi:[1,0]
	v_pk_mul_f32 v[196:197], v[154:155], s[34:35] op_sel_hi:[1,0]
	s_nop 0
	v_cvt_pk_bf16_f32 v196, v196, v197
	v_cvt_pk_bf16_f32 v197, v194, v195
	global_store_dwordx2 v[192:193], v[196:197], off offset:64 sc1
	v_pk_mul_f32 v[194:195], v[148:149], s[34:35] op_sel_hi:[1,0]
	v_pk_mul_f32 v[196:197], v[146:147], s[34:35] op_sel_hi:[1,0]
	s_nop 0
	v_cvt_pk_bf16_f32 v196, v196, v197
	v_cvt_pk_bf16_f32 v197, v194, v195
	global_store_dwordx2 v[192:193], v[196:197], off offset:96 sc1

.LBB0_1653:
	s_nop 1
	v_pk_mul_f32 v[146:147], v[16:17], v[16:17]
	v_pk_mul_f32 v[148:149], v[14:15], v[14:15]
	v_add_u32_e32 v172, 0xb0, v186
	v_pk_mov_b32 v[150:151], v[148:149], v[146:147] op_sel:[1,0]
	v_mov_b32_e32 v149, v147
	v_pk_add_f32 v[146:147], v[150:151], v[148:149]
	v_pk_mul_f32 v[148:149], v[12:13], v[12:13]
	v_pk_mul_f32 v[150:151], v[10:11], v[10:11]
	v_pk_add_f32 v[146:147], v[146:147], v[146:147] op_sel:[0,1] op_sel_hi:[1,0]
	v_pk_mov_b32 v[152:153], v[150:151], v[148:149] op_sel:[1,0]
	v_mov_b32_e32 v151, v149
	v_pk_add_f32 v[148:149], v[152:153], v[150:151]
	v_mul_f32_e32 v150, v2, v2
	v_mul_f32_e32 v151, v3, v3
	v_pk_add_f32 v[148:149], v[148:149], v[148:149] op_sel:[0,1] op_sel_hi:[1,0]
	v_mov_b32_e32 v147, v150
	v_mov_b32_e32 v149, v151
	v_pk_add_f32 v[146:147], v[146:147], v[148:149]
	v_mul_f32_e32 v148, v7, v7
	v_mul_f32_e32 v150, v9, v9
	v_mul_f32_e32 v152, v4, v4
	v_mul_f32_e32 v153, v5, v5
	v_pk_fma_f32 v[148:149], v[6:7], v[6:7], v[148:149] op_sel_hi:[1,1,0]
	v_pk_fma_f32 v[150:151], v[8:9], v[8:9], v[150:151] op_sel_hi:[1,1,0]
	v_mov_b32_e32 v149, v152
	v_mov_b32_e32 v151, v153
	v_pk_add_f32 v[148:149], v[148:149], v[150:151]
	s_nop 0
	v_pk_add_f32 v[146:147], v[146:147], v[148:149]
	s_nop 0
	v_add_f32_e32 v146, v146, v147
	ds_bpermute_b32 v147, v211, v146
	s_waitcnt lgkmcnt(0)
	v_add_f32_e32 v146, v146, v147
	ds_bpermute_b32 v147, v210, v146
	s_waitcnt lgkmcnt(0)
	v_add_f32_e32 v146, v146, v147
	v_fmamk_f32 v146, v146, 0x3c800000, v207
	v_cmp_gt_f32_e32 vcc, s10, v146
	v_mul_f32_e32 v147, 0x4f800000, v146
	s_nop 0
	v_cndmask_b32_e32 v146, v146, v147, vcc
	v_sqrt_f32_e32 v147, v146
	s_nop 0
	v_add_u32_e32 v148, -1, v147
	v_fma_f32 v149, -v148, v147, v146
	v_cmp_ge_f32_e64 s[8:9], 0, v149
	v_add_u32_e32 v149, 1, v147
	s_nop 0
	v_cndmask_b32_e64 v148, v147, v148, s[8:9]
	v_fma_f32 v147, -v149, v147, v146
	v_cmp_lt_f32_e64 s[8:9], 0, v147
	s_nop 1
	v_cndmask_b32_e64 v147, v148, v149, s[8:9]
	v_mul_f32_e32 v148, 0x37800000, v147
	v_cndmask_b32_e32 v147, v147, v148, vcc
	v_cmp_class_f32_e32 vcc, v146, v208
	s_nop 1
	v_cndmask_b32_e32 v146, v147, v146, vcc
	v_div_scale_f32 v147, s[8:9], v146, v146, 1.0
	v_rcp_f32_e32 v148, v147
	s_mov_b64 s[8:9], -1
	v_fma_f32 v149, -v147, v148, 1.0
	v_fmac_f32_e32 v148, v149, v148
	v_div_scale_f32 v149, vcc, 1.0, v146, 1.0
	v_mul_f32_e32 v150, v149, v148
	v_fma_f32 v151, -v147, v150, v149
	v_fmac_f32_e32 v150, v151, v148
	v_fma_f32 v147, -v147, v150, v149
	v_div_fmas_f32 v147, v147, v148, v150
	v_div_fixup_f32 v146, v147, v146, 1.0
	v_pk_mul_f32 v[148:149], v[14:15], v[146:147] op_sel_hi:[1,0]
	v_pk_mul_f32 v[150:151], v[16:17], v[146:147] op_sel_hi:[1,0]
	v_pk_mul_f32 v[142:143], v[142:143], v[148:149]
	v_pk_mul_f32 v[148:149], v[10:11], v[146:147] op_sel_hi:[1,0]
	v_pk_mul_f32 v[144:145], v[144:145], v[150:151]
	v_pk_mul_f32 v[150:151], v[12:13], v[146:147] op_sel_hi:[1,0]
	v_pk_mul_f32 v[138:139], v[138:139], v[148:149]
	v_pk_mul_f32 v[148:149], v[6:7], v[146:147] op_sel_hi:[1,0]
	v_pk_mul_f32 v[140:141], v[140:141], v[150:151]
	v_pk_mul_f32 v[150:151], v[8:9], v[146:147] op_sel_hi:[1,0]
	v_pk_mul_f32 v[134:135], v[134:135], v[148:149]
	v_pk_mul_f32 v[148:149], v[2:3], v[146:147] op_sel_hi:[1,0]
	v_pk_mul_f32 v[146:147], v[4:5], v[146:147] op_sel_hi:[1,0]
	v_pk_mul_f32 v[136:137], v[136:137], v[150:151]
	v_pk_mul_f32 v[132:133], v[132:133], v[146:147]
	v_lshlrev_b64 v[146:147], 6, v[172:173]
	v_lshl_add_u64 v[150:151], v[178:179], 0, v[146:147]
	v_pk_mul_f32 v[130:131], v[130:131], v[148:149]
	global_load_dwordx4 v[146:149], v[150:151], off
	s_nop 0
	global_load_dwordx4 v[150:153], v[150:151], off offset:32
	ds_bpermute_b32 v154, v210, v142
	ds_bpermute_b32 v155, v210, v143
	ds_bpermute_b32 v156, v210, v144
	ds_bpermute_b32 v157, v210, v145
	s_and_b64 vcc, exec, s[6:7]
	s_waitcnt vmcnt(0) lgkmcnt(2)
	v_pk_mul_f32 v[150:151], v[150:151], v[154:155]
	s_waitcnt lgkmcnt(0)
	v_pk_mul_f32 v[152:153], v[152:153], v[156:157]
	v_xor_b32_e32 v156, 0x80000000, v150
	v_xor_b32_e32 v154, 0x80000000, v152
	v_xor_b32_e32 v155, 0x80000000, v153
	v_xor_b32_e32 v157, 0x80000000, v151
	v_cndmask_b32_e64 v151, v151, v157, s[4:5]
	v_cndmask_b32_e64 v150, v150, v156, s[4:5]
	v_cndmask_b32_e64 v153, v153, v155, s[4:5]
	v_cndmask_b32_e64 v152, v152, v154, s[4:5]
	v_pk_fma_f32 v[144:145], v[148:149], v[144:145], v[152:153]
	v_pk_fma_f32 v[142:143], v[146:147], v[142:143], v[150:151]
	s_cbranch_vccnz .LBB0_1655
	v_readlane_b32 s6, v249, 9
	v_lshlrev_b64 v[146:147], 13, v[172:173]
	v_readlane_b32 s7, v249, 10
	v_mov_b32_e32 v189, v173
	v_pk_mul_f32 v[148:149], v[144:145], s[34:35] op_sel_hi:[1,0]
	v_lshl_add_u64 v[146:147], s[6:7], 0, v[146:147]
	v_lshl_add_u64 v[146:147], s[74:75], 1, v[146:147]
	v_pk_mul_f32 v[150:151], v[142:143], s[34:35] op_sel_hi:[1,0]
	v_lshl_add_u64 v[146:147], v[146:147], 0, v[188:189]
	v_cvt_pk_bf16_f32 v150, v150, v151
	v_cvt_pk_bf16_f32 v151, v148, v149
	global_store_dwordx2 v[146:147], v[150:151], off sc1
	v_pk_mul_f32 v[148:149], v[140:141], s[34:35] op_sel_hi:[1,0]
	v_pk_mul_f32 v[150:151], v[138:139], s[34:35] op_sel_hi:[1,0]
	s_mov_b64 s[8:9], 0
	v_cvt_pk_bf16_f32 v150, v150, v151
	v_cvt_pk_bf16_f32 v151, v148, v149
	global_store_dwordx2 v[146:147], v[150:151], off offset:32 sc1
	v_pk_mul_f32 v[148:149], v[136:137], s[34:35] op_sel_hi:[1,0]
	v_pk_mul_f32 v[150:151], v[134:135], s[34:35] op_sel_hi:[1,0]
	s_nop 0
	v_cvt_pk_bf16_f32 v150, v150, v151
	v_cvt_pk_bf16_f32 v151, v148, v149
	global_store_dwordx2 v[146:147], v[150:151], off offset:64 sc1
	v_pk_mul_f32 v[148:149], v[132:133], s[34:35] op_sel_hi:[1,0]
	v_pk_mul_f32 v[150:151], v[130:131], s[34:35] op_sel_hi:[1,0]
	s_nop 0
	v_cvt_pk_bf16_f32 v150, v150, v151
	v_cvt_pk_bf16_f32 v151, v148, v149
	global_store_dwordx2 v[146:147], v[150:151], off offset:96 sc1

.LBB0_1660:
	v_lshlrev_b64 v[148:149], 11, v[172:173]
	v_lshl_add_u64 v[148:149], s[0:1], 0, v[148:149]
	v_lshl_add_u64 v[148:149], s[72:73], 2, v[148:149]
	v_mov_b32_e32 v185, v173
	v_lshl_add_u64 v[148:149], v[148:149], 0, v[184:185]
	v_cmp_ne_u64_e32 vcc, 0, v[146:147]
	global_store_dwordx4 v[148:149], v[142:145], off sc1
	s_and_saveexec_b64 s[6:7], vcc
	s_xor_b64 s[6:7], exec, s[6:7]
	s_cbranch_execz .LBB0_1662
	global_store_dwordx4 v[146:147], v[142:145], off sc1
	global_store_dwordx4 v[148:149], v[138:141], off offset:64 sc1
	global_store_dwordx4 v[146:147], v[138:141], off offset:64 sc1
	global_store_dwordx4 v[148:149], v[134:137], off offset:128 sc1
	global_store_dwordx4 v[146:147], v[134:137], off offset:128 sc1
.LBB0_1662:
	s_or_saveexec_b64 s[6:7], s[6:7]
	v_mov_b64_e32 v[144:145], v[132:133]
	v_mov_b64_e32 v[150:151], 0xc0
	v_mov_b64_e32 v[142:143], v[130:131]
	s_xor_b64 exec, exec, s[6:7]
	s_cbranch_execz .LBB0_1664
	v_mov_b64_e32 v[144:145], v[136:137]
	v_mov_b64_e32 v[150:151], 0x80
	v_mov_b64_e32 v[142:143], v[134:135]
	v_mov_b64_e32 v[146:147], v[148:149]
	global_store_dwordx4 v[148:149], v[138:141], off offset:64 sc1
.LBB0_1664:
	s_or_b64 exec, exec, s[6:7]
	v_lshl_add_u64 v[134:135], v[148:149], 0, v[150:151]
	global_store_dwordx4 v[134:135], v[142:145], off sc1
	global_store_dwordx4 v[146:147], v[130:133], off offset:192 sc1

.LBB0_1672:
	v_mov_b32_e32 v187, v173
	v_lshlrev_b64 v[132:133], 11, v[186:187]
	v_lshl_add_u64 v[132:133], s[88:89], 0, v[132:133]
	v_lshl_add_u64 v[132:133], s[18:19], 2, v[132:133]
	v_mov_b32_e32 v185, v173
	v_lshl_add_u64 v[132:133], v[132:133], 0, v[184:185]
	v_cmp_ne_u64_e32 vcc, 0, v[130:131]
	global_store_dwordx4 v[132:133], v[126:129], off sc1
	s_and_saveexec_b64 s[6:7], vcc
	s_xor_b64 s[6:7], exec, s[6:7]
	s_cbranch_execz .LBB0_1674
	global_store_dwordx4 v[130:131], v[126:129], off sc1
	global_store_dwordx4 v[132:133], v[122:125], off offset:64 sc1
	global_store_dwordx4 v[130:131], v[122:125], off offset:64 sc1
	global_store_dwordx4 v[132:133], v[118:121], off offset:128 sc1
	global_store_dwordx4 v[130:131], v[118:121], off offset:128 sc1
.LBB0_1674:
	s_or_saveexec_b64 s[6:7], s[6:7]
	v_mov_b64_e32 v[128:129], v[116:117]
	v_mov_b64_e32 v[134:135], 0xc0
	v_mov_b64_e32 v[126:127], v[114:115]
	s_xor_b64 exec, exec, s[6:7]
	s_cbranch_execz .LBB0_1676
	v_mov_b64_e32 v[128:129], v[120:121]
	v_mov_b64_e32 v[134:135], 0x80
	v_mov_b64_e32 v[126:127], v[118:119]
	v_mov_b64_e32 v[130:131], v[132:133]
	global_store_dwordx4 v[132:133], v[122:125], off offset:64 sc1
.LBB0_1676:
	s_or_b64 exec, exec, s[6:7]
	v_lshl_add_u64 v[118:119], v[132:133], 0, v[134:135]
	global_store_dwordx4 v[118:119], v[126:129], off sc1
	global_store_dwordx4 v[130:131], v[114:117], off offset:192 sc1
	v_or_b32_e32 v172, 16, v186
	s_andn2_b64 vcc, exec, s[72:73]
	v_cndmask_b32_e64 v114, 0, 1, s[72:73]
	v_cmp_ne_u32_e64 s[6:7], 1, v114
	s_mov_b64 s[40:41], -1
	s_cbranch_vccnz .LBB0_1678
	v_and_b32_e32 v116, 0x7df, v172
	v_add_u32_e32 v114, 0xfffff880, v116
	v_mov_b32_e32 v115, v173
	s_add_u32 s40, s30, s8
	s_addc_u32 s41, s31, s9
	v_lshlrev_b64 v[114:115], 11, v[114:115]
	v_lshl_add_u64 v[114:115], s[40:41], 0, v[114:115]
	v_lshl_add_u64 v[114:115], s[18:19], 2, v[114:115]
	v_mov_b32_e32 v185, v173
	v_lshl_add_u64 v[114:115], v[114:115], 0, v[184:185]
	v_cmp_lt_u32_e32 vcc, s11, v116
	s_mov_b64 s[40:41], 0
	s_nop 0
	v_cndmask_b32_e32 v115, 0, v115, vcc
	v_cndmask_b32_e32 v114, 0, v114, vcc

.LBB0_1680:
	v_lshlrev_b64 v[116:117], 11, v[172:173]
	v_lshl_add_u64 v[116:117], s[88:89], 0, v[116:117]
	v_lshl_add_u64 v[116:117], s[18:19], 2, v[116:117]
	v_mov_b32_e32 v185, v173
	v_lshl_add_u64 v[116:117], v[116:117], 0, v[184:185]
	v_cmp_ne_u64_e32 vcc, 0, v[114:115]
	global_store_dwordx4 v[116:117], v[110:113], off sc1
	s_and_saveexec_b64 s[40:41], vcc
	s_xor_b64 s[40:41], exec, s[40:41]
	s_cbranch_execz .LBB0_1682
	global_store_dwordx4 v[114:115], v[110:113], off sc1
	global_store_dwordx4 v[116:117], v[106:109], off offset:64 sc1
	global_store_dwordx4 v[114:115], v[106:109], off offset:64 sc1
	global_store_dwordx4 v[116:117], v[102:105], off offset:128 sc1
	global_store_dwordx4 v[114:115], v[102:105], off offset:128 sc1
.LBB0_1682:
	s_or_saveexec_b64 s[40:41], s[40:41]
	v_mov_b64_e32 v[112:113], v[100:101]
	v_mov_b64_e32 v[118:119], 0xc0
	v_mov_b64_e32 v[110:111], v[98:99]
	s_xor_b64 exec, exec, s[40:41]
	s_cbranch_execz .LBB0_1684
	v_mov_b64_e32 v[112:113], v[104:105]
	v_mov_b64_e32 v[118:119], 0x80
	v_mov_b64_e32 v[110:111], v[102:103]
	v_mov_b64_e32 v[114:115], v[116:117]
	global_store_dwordx4 v[116:117], v[106:109], off offset:64 sc1
.LBB0_1684:
	s_or_b64 exec, exec, s[40:41]
	v_lshl_add_u64 v[102:103], v[116:117], 0, v[118:119]
	v_or_b32_e32 v172, 32, v186
	s_and_b64 vcc, exec, s[6:7]
	s_mov_b64 s[40:41], -1
	global_store_dwordx4 v[102:103], v[110:113], off sc1
	global_store_dwordx4 v[114:115], v[98:101], off offset:192 sc1
	s_cbranch_vccnz .LBB0_1686
	s_nop 0
	v_and_b32_e32 v100, 0x7ef, v172
	v_add_u32_e32 v98, 0xfffff880, v100
	v_mov_b32_e32 v99, v173
	s_add_u32 s40, s30, s8
	s_addc_u32 s41, s31, s9
	v_lshlrev_b64 v[98:99], 11, v[98:99]
	v_lshl_add_u64 v[98:99], s[40:41], 0, v[98:99]
	v_lshl_add_u64 v[98:99], s[18:19], 2, v[98:99]
	v_mov_b32_e32 v185, v173
	v_lshl_add_u64 v[98:99], v[98:99], 0, v[184:185]
	v_cmp_lt_u32_e32 vcc, s11, v100
	s_mov_b64 s[40:41], 0
	s_nop 0
	v_cndmask_b32_e32 v99, 0, v99, vcc
	v_cndmask_b32_e32 v98, 0, v98, vcc

.LBB0_1688:
	v_lshlrev_b64 v[100:101], 11, v[172:173]
	v_lshl_add_u64 v[100:101], s[88:89], 0, v[100:101]
	v_lshl_add_u64 v[100:101], s[18:19], 2, v[100:101]
	v_mov_b32_e32 v185, v173
	v_lshl_add_u64 v[100:101], v[100:101], 0, v[184:185]
	v_cmp_ne_u64_e32 vcc, 0, v[98:99]
	global_store_dwordx4 v[100:101], v[94:97], off sc1
	s_and_saveexec_b64 s[40:41], vcc
	s_xor_b64 s[40:41], exec, s[40:41]
	s_cbranch_execz .LBB0_1690
	global_store_dwordx4 v[98:99], v[94:97], off sc1
	global_store_dwordx4 v[100:101], v[90:93], off offset:64 sc1
	global_store_dwordx4 v[98:99], v[90:93], off offset:64 sc1
	global_store_dwordx4 v[100:101], v[86:89], off offset:128 sc1
	global_store_dwordx4 v[98:99], v[86:89], off offset:128 sc1
.LBB0_1690:
	s_or_saveexec_b64 s[40:41], s[40:41]
	v_mov_b64_e32 v[96:97], v[84:85]
	v_mov_b64_e32 v[102:103], 0xc0
	v_mov_b64_e32 v[94:95], v[82:83]
	s_xor_b64 exec, exec, s[40:41]
	s_cbranch_execz .LBB0_1692
	v_mov_b64_e32 v[96:97], v[88:89]
	v_mov_b64_e32 v[102:103], 0x80
	v_mov_b64_e32 v[94:95], v[86:87]
	v_mov_b64_e32 v[98:99], v[100:101]
	global_store_dwordx4 v[100:101], v[90:93], off offset:64 sc1
.LBB0_1692:
	s_or_b64 exec, exec, s[40:41]
	v_lshl_add_u64 v[86:87], v[100:101], 0, v[102:103]
	v_or_b32_e32 v172, 48, v186
	s_and_b64 vcc, exec, s[6:7]
	s_mov_b64 s[6:7], -1
	global_store_dwordx4 v[86:87], v[94:97], off sc1
	global_store_dwordx4 v[98:99], v[82:85], off offset:192 sc1
	s_cbranch_vccnz .LBB0_1694
	s_nop 0
	v_and_b32_e32 v84, 0x7ff, v172
	v_add_u32_e32 v82, 0xfffff880, v84
	v_mov_b32_e32 v83, v173
	s_add_u32 s6, s30, s8
	s_addc_u32 s7, s31, s9
	v_lshlrev_b64 v[82:83], 11, v[82:83]
	v_lshl_add_u64 v[82:83], s[6:7], 0, v[82:83]
	v_lshl_add_u64 v[82:83], s[18:19], 2, v[82:83]
	v_mov_b32_e32 v185, v173
	v_lshl_add_u64 v[82:83], v[82:83], 0, v[184:185]
	v_cmp_lt_u32_e32 vcc, s11, v84
	s_mov_b64 s[6:7], 0
	s_nop 0
	v_cndmask_b32_e32 v83, 0, v83, vcc
	v_cndmask_b32_e32 v82, 0, v82, vcc

.LBB0_1696:
	v_lshlrev_b64 v[84:85], 11, v[172:173]
	v_lshl_add_u64 v[84:85], s[88:89], 0, v[84:85]
	v_lshl_add_u64 v[84:85], s[18:19], 2, v[84:85]
	v_mov_b32_e32 v185, v173
	v_lshl_add_u64 v[84:85], v[84:85], 0, v[184:185]
	v_cmp_ne_u64_e32 vcc, 0, v[82:83]
	global_store_dwordx4 v[84:85], v[78:81], off sc1
	s_and_saveexec_b64 s[6:7], vcc
	s_xor_b64 s[6:7], exec, s[6:7]
	s_cbranch_execz .LBB0_1698
	global_store_dwordx4 v[82:83], v[78:81], off sc1
	global_store_dwordx4 v[84:85], v[74:77], off offset:64 sc1
	global_store_dwordx4 v[82:83], v[74:77], off offset:64 sc1
	global_store_dwordx4 v[84:85], v[70:73], off offset:128 sc1
	global_store_dwordx4 v[82:83], v[70:73], off offset:128 sc1
.LBB0_1698:
	s_or_saveexec_b64 s[6:7], s[6:7]
	v_mov_b64_e32 v[80:81], v[68:69]
	v_mov_b64_e32 v[86:87], 0xc0
	v_mov_b64_e32 v[78:79], v[66:67]
	s_xor_b64 exec, exec, s[6:7]
	s_cbranch_execz .LBB0_1700
	v_mov_b64_e32 v[80:81], v[72:73]
	v_mov_b64_e32 v[86:87], 0x80
	v_mov_b64_e32 v[78:79], v[70:71]
	v_mov_b64_e32 v[82:83], v[84:85]
	global_store_dwordx4 v[84:85], v[74:77], off offset:64 sc1
.LBB0_1700:
	s_or_b64 exec, exec, s[6:7]
	v_lshl_add_u64 v[70:71], v[84:85], 0, v[86:87]
	global_store_dwordx4 v[70:71], v[78:81], off sc1
	global_store_dwordx4 v[82:83], v[66:69], off offset:192 sc1
	v_add_u32_e32 v70, 0x80, v186
	v_lshrrev_b32_e32 v172, 11, v70
	v_lshlrev_b64 v[66:67], 18, v[172:173]
	s_mov_b64 s[6:7], -1
	s_cmpk_gt_u32 s13, 0x1f7f
	v_lshl_add_u64 v[66:67], s[30:31], 0, v[66:67]
	s_cbranch_scc1 .LBB0_1702
	v_and_b32_e32 v68, 0x7cf, v70
	v_add_u32_e32 v172, 0xfffff880, v68
	v_cmp_lt_u32_e32 vcc, s11, v68
	v_lshlrev_b64 v[68:69], 11, v[172:173]
	v_lshl_add_u64 v[68:69], v[66:67], 0, v[68:69]
	v_lshl_add_u64 v[68:69], s[18:19], 2, v[68:69]
	v_mov_b32_e32 v185, v173
	v_lshl_add_u64 v[68:69], v[68:69], 0, v[184:185]
	v_cndmask_b32_e32 v69, 0, v69, vcc
	v_cndmask_b32_e32 v68, 0, v68, vcc
	s_mov_b64 s[6:7], 0

.LBB0_1704:
	v_mov_b32_e32 v71, v173
	v_lshlrev_b64 v[70:71], 11, v[70:71]
	v_lshl_add_u64 v[70:71], s[88:89], 0, v[70:71]
	v_lshl_add_u64 v[70:71], s[18:19], 2, v[70:71]
	v_mov_b32_e32 v185, v173
	v_lshl_add_u64 v[70:71], v[70:71], 0, v[184:185]
	v_cmp_ne_u64_e32 vcc, 0, v[68:69]
	global_store_dwordx4 v[70:71], v[62:65], off sc1
	s_and_saveexec_b64 s[6:7], vcc
	s_xor_b64 s[6:7], exec, s[6:7]
	s_cbranch_execz .LBB0_1706
	global_store_dwordx4 v[68:69], v[62:65], off sc1
	global_store_dwordx4 v[70:71], v[58:61], off offset:64 sc1
	global_store_dwordx4 v[68:69], v[58:61], off offset:64 sc1
	global_store_dwordx4 v[70:71], v[54:57], off offset:128 sc1
	global_store_dwordx4 v[68:69], v[54:57], off offset:128 sc1
.LBB0_1706:
	s_or_saveexec_b64 s[6:7], s[6:7]
	v_mov_b64_e32 v[64:65], v[52:53]
	v_mov_b64_e32 v[72:73], 0xc0
	v_mov_b64_e32 v[62:63], v[50:51]
	s_xor_b64 exec, exec, s[6:7]
	s_cbranch_execz .LBB0_1708
	v_mov_b64_e32 v[64:65], v[56:57]
	v_mov_b64_e32 v[72:73], 0x80
	v_mov_b64_e32 v[62:63], v[54:55]
	v_mov_b64_e32 v[68:69], v[70:71]
	global_store_dwordx4 v[70:71], v[58:61], off offset:64 sc1
.LBB0_1708:
	s_or_b64 exec, exec, s[6:7]
	v_lshl_add_u64 v[54:55], v[70:71], 0, v[72:73]
	v_add_u32_e32 v172, 0x90, v186
	s_cmpk_gt_u32 s13, 0x1f6f
	s_mov_b64 s[6:7], -1
	global_store_dwordx4 v[54:55], v[62:65], off sc1
	global_store_dwordx4 v[68:69], v[50:53], off offset:192 sc1
	s_cbranch_scc1 .LBB0_1710
	s_nop 0
	v_and_b32_e32 v50, 0x7df, v172
	v_cmp_lt_u32_e32 vcc, s11, v50
	v_add_u32_e32 v50, 0xfffff880, v50
	v_mov_b32_e32 v51, v173
	v_lshlrev_b64 v[50:51], 11, v[50:51]
	v_lshl_add_u64 v[50:51], v[66:67], 0, v[50:51]
	v_lshl_add_u64 v[50:51], s[18:19], 2, v[50:51]
	v_mov_b32_e32 v185, v173
	v_lshl_add_u64 v[50:51], v[50:51], 0, v[184:185]
	v_cndmask_b32_e32 v51, 0, v51, vcc
	v_cndmask_b32_e32 v50, 0, v50, vcc
	s_mov_b64 s[6:7], 0

.LBB0_1712:
	v_lshlrev_b64 v[52:53], 11, v[172:173]
	v_lshl_add_u64 v[52:53], s[88:89], 0, v[52:53]
	v_lshl_add_u64 v[52:53], s[18:19], 2, v[52:53]
	v_mov_b32_e32 v185, v173
	v_lshl_add_u64 v[52:53], v[52:53], 0, v[184:185]
	v_cmp_ne_u64_e32 vcc, 0, v[50:51]
	global_store_dwordx4 v[52:53], v[46:49], off sc1
	s_and_saveexec_b64 s[6:7], vcc
	s_xor_b64 s[6:7], exec, s[6:7]
	s_cbranch_execz .LBB0_1714
	global_store_dwordx4 v[50:51], v[46:49], off sc1
	global_store_dwordx4 v[52:53], v[42:45], off offset:64 sc1
	global_store_dwordx4 v[50:51], v[42:45], off offset:64 sc1
	global_store_dwordx4 v[52:53], v[38:41], off offset:128 sc1
	global_store_dwordx4 v[50:51], v[38:41], off offset:128 sc1
.LBB0_1714:
	s_or_saveexec_b64 s[6:7], s[6:7]
	v_mov_b64_e32 v[48:49], v[36:37]
	v_mov_b64_e32 v[54:55], 0xc0
	v_mov_b64_e32 v[46:47], v[34:35]
	s_xor_b64 exec, exec, s[6:7]
	s_cbranch_execz .LBB0_1716
	v_mov_b64_e32 v[48:49], v[40:41]
	v_mov_b64_e32 v[54:55], 0x80
	v_mov_b64_e32 v[46:47], v[38:39]
	v_mov_b64_e32 v[50:51], v[52:53]
	global_store_dwordx4 v[52:53], v[42:45], off offset:64 sc1
.LBB0_1716:
	s_or_b64 exec, exec, s[6:7]
	v_lshl_add_u64 v[38:39], v[52:53], 0, v[54:55]
	v_add_u32_e32 v172, 0xa0, v186
	s_cmpk_gt_u32 s13, 0x1f5f
	s_mov_b64 s[6:7], -1
	global_store_dwordx4 v[38:39], v[46:49], off sc1
	global_store_dwordx4 v[50:51], v[34:37], off offset:192 sc1
	s_cbranch_scc1 .LBB0_1718
	s_nop 0
	v_and_b32_e32 v34, 0x7ef, v172
	v_cmp_lt_u32_e32 vcc, s11, v34
	v_add_u32_e32 v34, 0xfffff880, v34
	v_mov_b32_e32 v35, v173
	v_lshlrev_b64 v[34:35], 11, v[34:35]
	v_lshl_add_u64 v[34:35], v[66:67], 0, v[34:35]
	v_lshl_add_u64 v[34:35], s[18:19], 2, v[34:35]
	v_mov_b32_e32 v185, v173
	v_lshl_add_u64 v[34:35], v[34:35], 0, v[184:185]
	v_cndmask_b32_e32 v35, 0, v35, vcc
	v_cndmask_b32_e32 v34, 0, v34, vcc
	s_mov_b64 s[6:7], 0

.LBB0_1720:
	v_lshlrev_b64 v[36:37], 11, v[172:173]
	v_lshl_add_u64 v[36:37], s[88:89], 0, v[36:37]
	v_lshl_add_u64 v[36:37], s[18:19], 2, v[36:37]
	v_mov_b32_e32 v185, v173
	v_lshl_add_u64 v[36:37], v[36:37], 0, v[184:185]
	v_cmp_ne_u64_e32 vcc, 0, v[34:35]
	global_store_dwordx4 v[36:37], v[30:33], off sc1
	s_and_saveexec_b64 s[6:7], vcc
	s_xor_b64 s[6:7], exec, s[6:7]
	s_cbranch_execz .LBB0_1722
	global_store_dwordx4 v[34:35], v[30:33], off sc1
	global_store_dwordx4 v[36:37], v[26:29], off offset:64 sc1
	global_store_dwordx4 v[34:35], v[26:29], off offset:64 sc1
	global_store_dwordx4 v[36:37], v[22:25], off offset:128 sc1
	global_store_dwordx4 v[34:35], v[22:25], off offset:128 sc1
.LBB0_1722:
	s_or_saveexec_b64 s[6:7], s[6:7]
	v_mov_b64_e32 v[32:33], v[20:21]
	v_mov_b64_e32 v[38:39], 0xc0
	v_mov_b64_e32 v[30:31], v[18:19]
	s_xor_b64 exec, exec, s[6:7]
	s_cbranch_execz .LBB0_1724
	v_mov_b64_e32 v[32:33], v[24:25]
	v_mov_b64_e32 v[38:39], 0x80
	v_mov_b64_e32 v[30:31], v[22:23]
	v_mov_b64_e32 v[34:35], v[36:37]
	global_store_dwordx4 v[36:37], v[26:29], off offset:64 sc1
.LBB0_1724:
	s_or_b64 exec, exec, s[6:7]
	v_lshl_add_u64 v[22:23], v[36:37], 0, v[38:39]
	v_add_u32_e32 v172, 0xb0, v186
	s_cmpk_gt_u32 s13, 0x1f4f
	s_mov_b64 s[6:7], -1
	global_store_dwordx4 v[22:23], v[30:33], off sc1
	global_store_dwordx4 v[34:35], v[18:21], off offset:192 sc1
	s_cbranch_scc1 .LBB0_1726
	s_nop 0
	v_and_b32_e32 v18, 0x7ff, v172
	v_cmp_lt_u32_e32 vcc, s11, v18
	v_add_u32_e32 v18, 0xfffff880, v18
	v_mov_b32_e32 v19, v173
	v_lshlrev_b64 v[18:19], 11, v[18:19]
	v_lshl_add_u64 v[18:19], v[66:67], 0, v[18:19]
	v_lshl_add_u64 v[18:19], s[18:19], 2, v[18:19]
	v_mov_b32_e32 v185, v173
	v_lshl_add_u64 v[18:19], v[18:19], 0, v[184:185]
	v_cndmask_b32_e32 v19, 0, v19, vcc
	v_cndmask_b32_e32 v18, 0, v18, vcc
	s_mov_b64 s[6:7], 0

.LBB0_1728:
	v_lshlrev_b64 v[20:21], 11, v[172:173]
	v_lshl_add_u64 v[20:21], s[88:89], 0, v[20:21]
	v_lshl_add_u64 v[20:21], s[18:19], 2, v[20:21]
	v_mov_b32_e32 v185, v173
	v_lshl_add_u64 v[20:21], v[20:21], 0, v[184:185]
	v_cmp_ne_u64_e32 vcc, 0, v[18:19]
	global_store_dwordx4 v[20:21], v[14:17], off sc1
	s_and_saveexec_b64 s[6:7], vcc
	s_xor_b64 s[6:7], exec, s[6:7]
	s_cbranch_execz .LBB0_1730
	global_store_dwordx4 v[18:19], v[14:17], off sc1
	global_store_dwordx4 v[20:21], v[10:13], off offset:64 sc1
	global_store_dwordx4 v[18:19], v[10:13], off offset:64 sc1
	global_store_dwordx4 v[20:21], v[6:9], off offset:128 sc1
	global_store_dwordx4 v[18:19], v[6:9], off offset:128 sc1
.LBB0_1730:
	s_or_saveexec_b64 s[6:7], s[6:7]
	v_mov_b64_e32 v[16:17], v[4:5]
	v_mov_b64_e32 v[22:23], 0xc0
	v_mov_b64_e32 v[14:15], v[2:3]
	s_xor_b64 exec, exec, s[6:7]
	s_cbranch_execz .LBB0_1732
	v_mov_b64_e32 v[16:17], v[8:9]
	v_mov_b64_e32 v[22:23], 0x80
	v_mov_b64_e32 v[14:15], v[6:7]
	v_mov_b64_e32 v[18:19], v[20:21]
	global_store_dwordx4 v[20:21], v[10:13], off offset:64 sc1
.LBB0_1732:
	s_or_b64 exec, exec, s[6:7]
	v_lshl_add_u64 v[6:7], v[20:21], 0, v[22:23]
	global_store_dwordx4 v[6:7], v[14:17], off sc1
	global_store_dwordx4 v[18:19], v[2:5], off offset:192 sc1
	s_andn2_b64 vcc, exec, s[64:65]
	s_mov_b64 s[6:7], -1
	s_cbranch_vccnz .LBB0_1563

.LBB0_2233:
	v_lshl_add_u32 v144, s43, 8, v151
	v_lshl_or_b32 v142, s42, 8, v153
	v_ashrrev_i32_e32 v145, 31, v144
	v_ashrrev_i32_e32 v143, 31, v142
	v_lshlrev_b64 v[146:147], 13, v[144:145]
	v_lshl_add_u64 v[158:159], s[96:97], 0, v[146:147]
	v_lshlrev_b64 v[146:147], 1, v[142:143]
	v_lshl_add_u64 v[142:143], v[158:159], 0, v[146:147]
	global_load_dwordx4 v[158:161], v[142:143], off
	global_load_dwordx4 v[168:171], v[142:143], off offset:256
	v_or_b32_e32 v172, 16, v144
	v_ashrrev_i32_e32 v173, 31, v172
	v_lshlrev_b64 v[172:173], 13, v[172:173]
	v_lshl_add_u64 v[172:173], s[96:97], 0, v[172:173]
	v_lshl_add_u64 v[172:173], v[172:173], 0, v[146:147]
	s_mov_b32 s7, 0x100000
	s_mov_b64 s[22:23], 0x100000
	s_waitcnt vmcnt(0)
	v_lshlrev_b32_e32 v176, 16, v158
	v_and_b32_e32 v177, 0xffff0000, v158
	v_lshlrev_b32_e32 v158, 16, v159
	v_and_b32_e32 v159, 0xffff0000, v159
	v_lshlrev_b32_e32 v178, 16, v160
	v_and_b32_e32 v179, 0xffff0000, v160
	v_lshlrev_b32_e32 v160, 16, v161
	v_and_b32_e32 v161, 0xffff0000, v161
	v_lshlrev_b32_e32 v180, 16, v168
	v_and_b32_e32 v181, 0xffff0000, v168
	v_lshlrev_b32_e32 v168, 16, v169
	v_and_b32_e32 v169, 0xffff0000, v169
	v_lshlrev_b32_e32 v182, 16, v170
	v_and_b32_e32 v183, 0xffff0000, v170
	v_lshlrev_b32_e32 v170, 16, v171
	v_and_b32_e32 v171, 0xffff0000, v171
	v_pk_add_f32 v[128:129], v[128:129], v[158:159]
	v_pk_add_f32 v[126:127], v[126:127], v[176:177]
	v_pk_add_f32 v[124:125], v[124:125], v[160:161]
	v_pk_add_f32 v[122:123], v[122:123], v[178:179]
	v_pk_add_f32 v[120:121], v[120:121], v[168:169]
	v_pk_add_f32 v[118:119], v[118:119], v[180:181]
	v_pk_add_f32 v[158:159], v[116:117], v[170:171]
	v_pk_add_f32 v[160:161], v[114:115], v[182:183]
	v_cvt_pk_bf16_f32 v114, v126, v127
	v_cvt_pk_bf16_f32 v115, v128, v129
	v_cvt_pk_bf16_f32 v116, v122, v123
	v_cvt_pk_bf16_f32 v117, v124, v125
	global_store_dwordx4 v[142:143], v[114:117], off sc1
	v_or_b32_e32 v126, 32, v144
	v_ashrrev_i32_e32 v127, 31, v126
	v_cvt_pk_bf16_f32 v114, v118, v119
	v_cvt_pk_bf16_f32 v115, v120, v121
	v_cvt_pk_bf16_f32 v116, v160, v161
	v_cvt_pk_bf16_f32 v117, v158, v159
	global_load_dwordx4 v[118:121], v[172:173], off
	global_load_dwordx4 v[122:125], v[172:173], off offset:256
	v_lshlrev_b64 v[126:127], 13, v[126:127]
	v_lshl_add_u64 v[126:127], s[96:97], 0, v[126:127]
	global_store_dwordx4 v[142:143], v[114:117], off offset:256 sc1
	v_lshl_add_u64 v[126:127], v[126:127], 0, v[146:147]
	s_waitcnt vmcnt(1)
	v_lshlrev_b32_e32 v128, 16, v122
	v_lshlrev_b32_e32 v114, 16, v118
	v_and_b32_e32 v115, 0xffff0000, v118
	v_lshlrev_b32_e32 v116, 16, v119
	v_and_b32_e32 v117, 0xffff0000, v119
	v_lshlrev_b32_e32 v118, 16, v120
	v_and_b32_e32 v119, 0xffff0000, v120
	v_lshlrev_b32_e32 v120, 16, v121
	v_and_b32_e32 v121, 0xffff0000, v121
	v_and_b32_e32 v129, 0xffff0000, v122
	v_lshlrev_b32_e32 v122, 16, v123
	v_and_b32_e32 v123, 0xffff0000, v123
	v_lshlrev_b32_e32 v158, 16, v124
	v_and_b32_e32 v159, 0xffff0000, v124
	v_lshlrev_b32_e32 v124, 16, v125
	v_and_b32_e32 v125, 0xffff0000, v125
	v_pk_add_f32 v[112:113], v[112:113], v[116:117]
	v_pk_add_f32 v[110:111], v[110:111], v[114:115]
	v_pk_add_f32 v[108:109], v[108:109], v[120:121]
	v_pk_add_f32 v[106:107], v[106:107], v[118:119]
	v_pk_add_f32 v[104:105], v[104:105], v[122:123]
	v_pk_add_f32 v[102:103], v[102:103], v[128:129]
	v_pk_add_f32 v[114:115], v[100:101], v[124:125]
	v_pk_add_f32 v[116:117], v[98:99], v[158:159]
	v_cvt_pk_bf16_f32 v98, v110, v111
	v_cvt_pk_bf16_f32 v99, v112, v113
	v_cvt_pk_bf16_f32 v100, v106, v107
	v_cvt_pk_bf16_f32 v101, v108, v109
	global_store_dwordx4 v[172:173], v[98:101], off sc1
	v_or_b32_e32 v110, 48, v144
	v_ashrrev_i32_e32 v111, 31, v110
	v_cvt_pk_bf16_f32 v98, v102, v103
	v_cvt_pk_bf16_f32 v99, v104, v105
	v_cvt_pk_bf16_f32 v100, v116, v117
	v_cvt_pk_bf16_f32 v101, v114, v115
	global_load_dwordx4 v[102:105], v[126:127], off
	global_load_dwordx4 v[106:109], v[126:127], off offset:256
	v_lshlrev_b64 v[110:111], 13, v[110:111]
	v_lshl_add_u64 v[110:111], s[96:97], 0, v[110:111]
	global_store_dwordx4 v[172:173], v[98:101], off offset:256 sc1
	v_lshl_add_u64 v[110:111], v[110:111], 0, v[146:147]
	s_waitcnt vmcnt(1)
	v_lshlrev_b32_e32 v112, 16, v106
	v_lshlrev_b32_e32 v98, 16, v102
	v_and_b32_e32 v99, 0xffff0000, v102
	v_lshlrev_b32_e32 v100, 16, v103
	v_and_b32_e32 v101, 0xffff0000, v103
	v_lshlrev_b32_e32 v102, 16, v104
	v_and_b32_e32 v103, 0xffff0000, v104
	v_lshlrev_b32_e32 v104, 16, v105
	v_and_b32_e32 v105, 0xffff0000, v105
	v_and_b32_e32 v113, 0xffff0000, v106
	v_lshlrev_b32_e32 v106, 16, v107
	v_and_b32_e32 v107, 0xffff0000, v107
	v_lshlrev_b32_e32 v114, 16, v108
	v_and_b32_e32 v115, 0xffff0000, v108
	v_lshlrev_b32_e32 v108, 16, v109
	v_and_b32_e32 v109, 0xffff0000, v109
	v_pk_add_f32 v[96:97], v[96:97], v[100:101]
	v_pk_add_f32 v[94:95], v[94:95], v[98:99]
	v_pk_add_f32 v[92:93], v[92:93], v[104:105]
	v_pk_add_f32 v[90:91], v[90:91], v[102:103]
	v_pk_add_f32 v[88:89], v[88:89], v[106:107]
	v_pk_add_f32 v[86:87], v[86:87], v[112:113]
	v_pk_add_f32 v[98:99], v[84:85], v[108:109]
	v_pk_add_f32 v[100:101], v[82:83], v[114:115]
	v_cvt_pk_bf16_f32 v82, v94, v95
	v_cvt_pk_bf16_f32 v83, v96, v97
	v_cvt_pk_bf16_f32 v84, v90, v91
	v_cvt_pk_bf16_f32 v85, v92, v93
	global_store_dwordx4 v[126:127], v[82:85], off sc1
	v_add_co_u32_e32 v94, vcc, s7, v142
	s_nop 0
	v_cvt_pk_bf16_f32 v82, v86, v87
	v_cvt_pk_bf16_f32 v83, v88, v89
	v_cvt_pk_bf16_f32 v84, v100, v101
	v_cvt_pk_bf16_f32 v85, v98, v99
	global_load_dwordx4 v[86:89], v[110:111], off
	global_load_dwordx4 v[90:93], v[110:111], off offset:256
	v_addc_co_u32_e32 v95, vcc, 0, v143, vcc
	global_store_dwordx4 v[126:127], v[82:85], off offset:256 sc1
	s_mov_b32 s7, 0x120000
	s_waitcnt vmcnt(1)
	v_lshlrev_b32_e32 v96, 16, v90
	v_lshlrev_b32_e32 v82, 16, v86
	v_and_b32_e32 v83, 0xffff0000, v86
	v_lshlrev_b32_e32 v84, 16, v87
	v_and_b32_e32 v85, 0xffff0000, v87
	v_lshlrev_b32_e32 v86, 16, v88
	v_and_b32_e32 v87, 0xffff0000, v88
	v_lshlrev_b32_e32 v88, 16, v89
	v_and_b32_e32 v89, 0xffff0000, v89
	v_and_b32_e32 v97, 0xffff0000, v90
	v_lshlrev_b32_e32 v90, 16, v91
	v_and_b32_e32 v91, 0xffff0000, v91
	v_lshlrev_b32_e32 v98, 16, v92
	v_and_b32_e32 v99, 0xffff0000, v92
	v_lshlrev_b32_e32 v92, 16, v93
	v_and_b32_e32 v93, 0xffff0000, v93
	v_pk_add_f32 v[80:81], v[80:81], v[84:85]
	v_pk_add_f32 v[78:79], v[78:79], v[82:83]
	v_pk_add_f32 v[76:77], v[76:77], v[88:89]
	v_pk_add_f32 v[74:75], v[74:75], v[86:87]
	v_pk_add_f32 v[72:73], v[72:73], v[90:91]
	v_pk_add_f32 v[70:71], v[70:71], v[96:97]
	v_pk_add_f32 v[82:83], v[68:69], v[92:93]
	v_pk_add_f32 v[84:85], v[66:67], v[98:99]
	v_cvt_pk_bf16_f32 v66, v78, v79
	v_cvt_pk_bf16_f32 v67, v80, v81
	v_cvt_pk_bf16_f32 v68, v74, v75
	v_cvt_pk_bf16_f32 v69, v76, v77
	global_store_dwordx4 v[110:111], v[66:69], off sc1
	v_lshl_add_u64 v[78:79], v[142:143], 0, s[22:23]
	v_add_co_u32_e32 v80, vcc, s7, v142
	v_cvt_pk_bf16_f32 v66, v70, v71
	v_cvt_pk_bf16_f32 v67, v72, v73
	v_cvt_pk_bf16_f32 v68, v84, v85
	v_cvt_pk_bf16_f32 v69, v82, v83
	global_load_dwordx4 v[70:73], v[94:95], off
	global_load_dwordx4 v[74:77], v[78:79], off offset:256
	s_mov_b64 s[22:23], 0x120000
	global_store_dwordx4 v[110:111], v[66:69], off offset:256 sc1
	v_addc_co_u32_e32 v81, vcc, 0, v143, vcc
	s_mov_b32 s7, 0x140000
	s_waitcnt vmcnt(2)
	v_lshlrev_b32_e32 v66, 16, v70
	v_and_b32_e32 v67, 0xffff0000, v70
	v_lshlrev_b32_e32 v68, 16, v71
	v_and_b32_e32 v69, 0xffff0000, v71
	v_lshlrev_b32_e32 v70, 16, v72
	v_and_b32_e32 v71, 0xffff0000, v72
	v_lshlrev_b32_e32 v72, 16, v73
	v_and_b32_e32 v73, 0xffff0000, v73
	s_waitcnt vmcnt(1)
	v_lshlrev_b32_e32 v82, 16, v74
	v_and_b32_e32 v83, 0xffff0000, v74
	v_lshlrev_b32_e32 v74, 16, v75
	v_and_b32_e32 v75, 0xffff0000, v75
	v_lshlrev_b32_e32 v84, 16, v76
	v_and_b32_e32 v85, 0xffff0000, v76
	v_lshlrev_b32_e32 v76, 16, v77
	v_and_b32_e32 v77, 0xffff0000, v77
	v_pk_add_f32 v[62:63], v[62:63], v[66:67]
	v_pk_add_f32 v[64:65], v[64:65], v[68:69]
	v_pk_add_f32 v[60:61], v[60:61], v[72:73]
	v_pk_add_f32 v[58:59], v[58:59], v[70:71]
	v_pk_add_f32 v[56:57], v[56:57], v[74:75]
	v_pk_add_f32 v[54:55], v[54:55], v[82:83]
	v_pk_add_f32 v[66:67], v[52:53], v[76:77]
	v_pk_add_f32 v[68:69], v[50:51], v[84:85]
	v_cvt_pk_bf16_f32 v50, v62, v63
	v_cvt_pk_bf16_f32 v51, v64, v65
	v_cvt_pk_bf16_f32 v52, v58, v59
	v_cvt_pk_bf16_f32 v53, v60, v61
	v_lshl_add_u64 v[62:63], v[142:143], 0, s[22:23]
	global_store_dwordx4 v[94:95], v[50:53], off sc1
	v_add_co_u32_e32 v64, vcc, s7, v142
	s_nop 0
	v_cvt_pk_bf16_f32 v50, v54, v55
	v_cvt_pk_bf16_f32 v51, v56, v57
	v_cvt_pk_bf16_f32 v52, v68, v69
	v_cvt_pk_bf16_f32 v53, v66, v67
	global_load_dwordx4 v[54:57], v[80:81], off
	global_load_dwordx4 v[58:61], v[62:63], off offset:256
	v_addc_co_u32_e32 v65, vcc, 0, v143, vcc
	global_store_dwordx4 v[78:79], v[50:53], off offset:256 sc1
	s_mov_b64 s[22:23], 0x140000
	s_mov_b32 s7, 0x160000
	s_waitcnt vmcnt(2)
	v_lshlrev_b32_e32 v50, 16, v54
	v_and_b32_e32 v51, 0xffff0000, v54
	v_lshlrev_b32_e32 v52, 16, v55
	v_and_b32_e32 v53, 0xffff0000, v55
	v_lshlrev_b32_e32 v54, 16, v56
	v_and_b32_e32 v55, 0xffff0000, v56
	v_lshlrev_b32_e32 v56, 16, v57
	v_and_b32_e32 v57, 0xffff0000, v57
	s_waitcnt vmcnt(1)
	v_lshlrev_b32_e32 v66, 16, v58
	v_and_b32_e32 v67, 0xffff0000, v58
	v_lshlrev_b32_e32 v58, 16, v59
	v_and_b32_e32 v59, 0xffff0000, v59
	v_lshlrev_b32_e32 v68, 16, v60
	v_and_b32_e32 v69, 0xffff0000, v60
	v_lshlrev_b32_e32 v60, 16, v61
	v_and_b32_e32 v61, 0xffff0000, v61
	v_pk_add_f32 v[48:49], v[48:49], v[52:53]
	v_pk_add_f32 v[46:47], v[46:47], v[50:51]
	v_pk_add_f32 v[44:45], v[44:45], v[56:57]
	v_pk_add_f32 v[42:43], v[42:43], v[54:55]
	v_pk_add_f32 v[40:41], v[40:41], v[58:59]
	v_pk_add_f32 v[38:39], v[38:39], v[66:67]
	v_pk_add_f32 v[50:51], v[36:37], v[60:61]
	v_pk_add_f32 v[52:53], v[34:35], v[68:69]
	v_cvt_pk_bf16_f32 v34, v46, v47
	v_cvt_pk_bf16_f32 v35, v48, v49
	v_cvt_pk_bf16_f32 v36, v42, v43
	v_cvt_pk_bf16_f32 v37, v44, v45
	global_store_dwordx4 v[80:81], v[34:37], off sc1
	v_lshl_add_u64 v[46:47], v[142:143], 0, s[22:23]
	v_add_co_u32_e32 v48, vcc, s7, v142
	v_cvt_pk_bf16_f32 v34, v38, v39
	v_cvt_pk_bf16_f32 v35, v40, v41
	v_cvt_pk_bf16_f32 v36, v52, v53
	v_cvt_pk_bf16_f32 v37, v50, v51
	global_load_dwordx4 v[38:41], v[64:65], off
	global_load_dwordx4 v[42:45], v[46:47], off offset:256
	s_mov_b64 s[22:23], 0x160000
	global_store_dwordx4 v[62:63], v[34:37], off offset:256 sc1
	v_addc_co_u32_e32 v49, vcc, 0, v143, vcc
	s_andn2_b64 vcc, exec, s[20:21]
	s_mov_b64 s[20:21], -1
	s_waitcnt vmcnt(2)
	v_lshlrev_b32_e32 v34, 16, v38
	v_and_b32_e32 v35, 0xffff0000, v38
	v_lshlrev_b32_e32 v36, 16, v39
	v_and_b32_e32 v37, 0xffff0000, v39
	v_lshlrev_b32_e32 v38, 16, v40
	v_and_b32_e32 v39, 0xffff0000, v40
	v_lshlrev_b32_e32 v40, 16, v41
	v_and_b32_e32 v41, 0xffff0000, v41
	s_waitcnt vmcnt(1)
	v_lshlrev_b32_e32 v50, 16, v42
	v_and_b32_e32 v51, 0xffff0000, v42
	v_lshlrev_b32_e32 v42, 16, v43
	v_and_b32_e32 v43, 0xffff0000, v43
	v_lshlrev_b32_e32 v52, 16, v44
	v_and_b32_e32 v53, 0xffff0000, v44
	v_lshlrev_b32_e32 v44, 16, v45
	v_and_b32_e32 v45, 0xffff0000, v45
	v_pk_add_f32 v[30:31], v[30:31], v[34:35]
	v_pk_add_f32 v[32:33], v[32:33], v[36:37]
	v_pk_add_f32 v[28:29], v[28:29], v[40:41]
	v_pk_add_f32 v[26:27], v[26:27], v[38:39]
	v_pk_add_f32 v[24:25], v[24:25], v[42:43]
	v_pk_add_f32 v[22:23], v[22:23], v[50:51]
	v_pk_add_f32 v[34:35], v[20:21], v[44:45]
	v_pk_add_f32 v[36:37], v[18:19], v[52:53]
	v_cvt_pk_bf16_f32 v18, v30, v31
	v_cvt_pk_bf16_f32 v19, v32, v33
	v_cvt_pk_bf16_f32 v20, v26, v27
	v_cvt_pk_bf16_f32 v21, v28, v29
	v_lshl_add_u64 v[30:31], v[142:143], 0, s[22:23]
	global_store_dwordx4 v[64:65], v[18:21], off sc1
	s_nop 1
	v_cvt_pk_bf16_f32 v18, v22, v23
	v_cvt_pk_bf16_f32 v19, v24, v25
	v_cvt_pk_bf16_f32 v20, v36, v37
	v_cvt_pk_bf16_f32 v21, v34, v35
	global_load_dwordx4 v[22:25], v[48:49], off
	global_load_dwordx4 v[26:29], v[30:31], off offset:256
	s_waitcnt vmcnt(0)
	v_lshlrev_b32_e32 v34, 16, v28
	global_store_dwordx4 v[46:47], v[18:21], off offset:256 sc1
	v_and_b32_e32 v35, 0xffff0000, v28
	v_lshlrev_b32_e32 v28, 16, v29
	v_lshlrev_b32_e32 v18, 16, v22
	v_and_b32_e32 v19, 0xffff0000, v22
	v_lshlrev_b32_e32 v20, 16, v23
	v_and_b32_e32 v21, 0xffff0000, v23
	v_lshlrev_b32_e32 v22, 16, v24
	v_and_b32_e32 v23, 0xffff0000, v24
	v_lshlrev_b32_e32 v24, 16, v25
	v_and_b32_e32 v25, 0xffff0000, v25
	v_and_b32_e32 v29, 0xffff0000, v29
	v_lshlrev_b32_e32 v32, 16, v26
	v_and_b32_e32 v33, 0xffff0000, v26
	v_lshlrev_b32_e32 v26, 16, v27
	v_and_b32_e32 v27, 0xffff0000, v27
	v_pk_add_f32 v[16:17], v[16:17], v[20:21]
	v_pk_add_f32 v[14:15], v[14:15], v[18:19]
	v_pk_add_f32 v[12:13], v[12:13], v[24:25]
	v_pk_add_f32 v[10:11], v[10:11], v[22:23]
	v_pk_add_f32 v[18:19], v[4:5], v[28:29]
	v_pk_add_f32 v[20:21], v[2:3], v[34:35]
	v_cvt_pk_bf16_f32 v2, v14, v15
	v_cvt_pk_bf16_f32 v3, v16, v17
	v_cvt_pk_bf16_f32 v4, v10, v11
	v_cvt_pk_bf16_f32 v5, v12, v13
	v_pk_add_f32 v[8:9], v[8:9], v[26:27]
	v_pk_add_f32 v[6:7], v[6:7], v[32:33]
	global_store_dwordx4 v[48:49], v[2:5], off sc1
	s_nop 1
	v_cvt_pk_bf16_f32 v2, v6, v7
	v_cvt_pk_bf16_f32 v3, v8, v9
	v_cvt_pk_bf16_f32 v4, v20, v21
	v_cvt_pk_bf16_f32 v5, v18, v19
	global_store_dwordx4 v[30:31], v[2:5], off offset:256 sc1
	s_cbranch_vccnz .LBB0_2228
	s_andn2_b64 vcc, exec, s[12:13]
	s_cbranch_vccnz .LBB0_2227
	s_barrier
	s_branch .LBB0_2227

.LBB0_2240:
	s_add_i32 s20, s24, 0x100
	s_and_b64 s[18:19], s[18:19], exec
	s_cselect_b32 s19, 0, s20
	s_cselect_b32 s18, 0, 0
	s_add_u32 s20, s8, s19
	ds_read_b128 v[144:147], v139
	ds_read_b128 v[150:153], v139 offset:1024
	ds_read_b128 v[154:157], v139 offset:2048
	ds_read_b128 v[158:161], v139 offset:3072
	ds_read_b128 v[168:171], v140
	ds_read_b128 v[176:179], v140 offset:1024
	ds_read_b128 v[180:183], v140 offset:2048
	ds_read_b128 v[184:187], v140 offset:3072
	s_addc_u32 s21, s9, s18
	s_add_u32 s22, s10, s19
	s_addc_u32 s23, s11, s18
	s_add_u32 s28, s12, s24
	s_addc_u32 s29, s13, 0
	s_add_u32 s24, s22, 0x100000
	s_addc_u32 s25, s23, 0
	s_add_u32 s18, s20, 0x100000
	s_addc_u32 s19, s21, 0
	s_add_u32 s26, s22, 0x100080
	s_addc_u32 s27, s23, 0
	v_lshl_add_u64 v[172:173], s[28:29], 0, v[130:131]
	s_mov_b32 m0, s38
	v_lshl_add_u64 v[172:173], v[172:173], 0, s[14:15]
	ds_read_b128 v[188:191], v141
	ds_read_b128 v[192:195], v141 offset:1024
	ds_read_b128 v[204:207], v141 offset:2048
	ds_read_b128 v[208:211], v141 offset:3072
	ds_read_b128 v[212:215], v141 offset:4096
	ds_read_b128 v[216:219], v141 offset:5120
	ds_read_b128 v[220:223], v141 offset:6144
	ds_read_b128 v[224:227], v141 offset:7168
	global_load_lds_dwordx4 v[172:173], off
	v_lshl_add_u64 v[172:173], s[28:29], 0, v[134:135]
	v_lshl_add_u64 v[172:173], v[172:173], 0, s[14:15]
	s_mov_b32 m0, s39
	s_nop 0
	global_load_lds_dwordx4 v[172:173], off
	s_waitcnt vmcnt(8)
	s_waitcnt lgkmcnt(0)
	s_barrier
	v_mfma_f32_16x16x32_bf16 v[126:129], v[144:147], v[188:191], v[126:129]
	v_mfma_f32_16x16x32_bf16 v[126:129], v[150:153], v[192:195], v[126:129]
	v_mfma_f32_16x16x32_bf16 v[122:125], v[158:161], v[192:195], v[122:125]
	v_mfma_f32_16x16x32_bf16 v[122:125], v[154:157], v[188:191], v[122:125]
	v_mfma_f32_16x16x32_bf16 v[114:117], v[154:157], v[204:207], v[114:117]
	v_mfma_f32_16x16x32_bf16 v[114:117], v[158:161], v[208:211], v[114:117]
	v_mfma_f32_16x16x32_bf16 v[118:121], v[150:153], v[208:211], v[118:121]
	v_mfma_f32_16x16x32_bf16 v[118:121], v[144:147], v[204:207], v[118:121]
	v_mfma_f32_16x16x32_bf16 v[102:105], v[144:147], v[212:215], v[102:105]
	v_mfma_f32_16x16x32_bf16 v[102:105], v[150:153], v[216:219], v[102:105]
	v_mfma_f32_16x16x32_bf16 v[98:101], v[158:161], v[216:219], v[98:101]
	v_mfma_f32_16x16x32_bf16 v[98:101], v[154:157], v[212:215], v[98:101]
	v_mfma_f32_16x16x32_bf16 v[82:85], v[154:157], v[220:223], v[82:85]
	v_mfma_f32_16x16x32_bf16 v[82:85], v[158:161], v[224:227], v[82:85]
	v_mfma_f32_16x16x32_bf16 v[86:89], v[150:153], v[224:227], v[86:89]
	v_mfma_f32_16x16x32_bf16 v[86:89], v[144:147], v[220:223], v[86:89]
	v_mfma_f32_16x16x32_bf16 v[70:73], v[168:171], v[220:223], v[70:73]
	v_mfma_f32_16x16x32_bf16 v[70:73], v[176:179], v[224:227], v[70:73]
	v_mfma_f32_16x16x32_bf16 v[66:69], v[184:187], v[224:227], v[66:69]
	v_mfma_f32_16x16x32_bf16 v[66:69], v[180:183], v[220:223], v[66:69]
	v_mfma_f32_16x16x32_bf16 v[74:77], v[180:183], v[212:215], v[74:77]
	v_mfma_f32_16x16x32_bf16 v[74:77], v[184:187], v[216:219], v[74:77]
	v_mfma_f32_16x16x32_bf16 v[78:81], v[176:179], v[216:219], v[78:81]
	v_mfma_f32_16x16x32_bf16 v[78:81], v[168:171], v[212:215], v[78:81]
	v_mfma_f32_16x16x32_bf16 v[94:97], v[168:171], v[204:207], v[94:97]
	v_mfma_f32_16x16x32_bf16 v[94:97], v[176:179], v[208:211], v[94:97]
	v_mfma_f32_16x16x32_bf16 v[90:93], v[184:187], v[208:211], v[90:93]
	v_mfma_f32_16x16x32_bf16 v[90:93], v[180:183], v[204:207], v[90:93]
	v_mfma_f32_16x16x32_bf16 v[106:109], v[180:183], v[188:191], v[106:109]
	v_mfma_f32_16x16x32_bf16 v[106:109], v[184:187], v[192:195], v[106:109]
	v_mfma_f32_16x16x32_bf16 v[110:113], v[176:179], v[192:195], v[110:113]
	v_mfma_f32_16x16x32_bf16 v[110:113], v[168:171], v[188:191], v[110:113]
	s_barrier
	s_mov_b32 m0, s40
	v_lshl_add_u64 v[172:173], s[22:23], 0, v[132:133]
	ds_read_b128 v[188:191], v141 offset:16384
	ds_read_b128 v[192:195], v141 offset:17408
	ds_read_b128 v[204:207], v141 offset:18432
	ds_read_b128 v[208:211], v141 offset:19456
	ds_read_b128 v[212:215], v141 offset:20480
	ds_read_b128 v[216:219], v141 offset:21504
	ds_read_b128 v[220:223], v141 offset:22528
	ds_read_b128 v[224:227], v141 offset:23552
	global_load_lds_dwordx4 v[172:173], off
	v_lshl_add_u64 v[196:197], s[22:23], 0, v[136:137]
	s_mov_b32 m0, s41
	v_lshl_add_u64 v[228:229], s[24:25], 0, v[132:133]
	global_load_lds_dwordx4 v[196:197], off
	s_mov_b32 m0, s42
	v_lshl_add_u64 v[230:231], s[20:21], 0, v[134:135]
	global_load_lds_dwordx4 v[228:229], off
	v_lshl_add_u64 v[228:229], s[24:25], 0, v[136:137]
	s_mov_b32 m0, s43
	s_nop 0
	global_load_lds_dwordx4 v[228:229], off
	v_lshl_add_u64 v[228:229], s[20:21], 0, v[130:131]
	s_mov_b32 m0, s7
	s_nop 0
	global_load_lds_dwordx4 v[228:229], off
	s_mov_b32 m0, s31
	s_nop 0
	global_load_lds_dwordx4 v[230:231], off
	s_waitcnt vmcnt(8)
	s_waitcnt lgkmcnt(0)
	s_barrier
	v_mfma_f32_16x16x32_bf16 v[62:65], v[144:147], v[188:191], v[62:65]
	v_mfma_f32_16x16x32_bf16 v[62:65], v[150:153], v[192:195], v[62:65]
	v_mfma_f32_16x16x32_bf16 v[58:61], v[158:161], v[192:195], v[58:61]
	v_mfma_f32_16x16x32_bf16 v[58:61], v[154:157], v[188:191], v[58:61]
	v_mfma_f32_16x16x32_bf16 v[50:53], v[154:157], v[204:207], v[50:53]
	v_mfma_f32_16x16x32_bf16 v[50:53], v[158:161], v[208:211], v[50:53]
	v_mfma_f32_16x16x32_bf16 v[54:57], v[150:153], v[208:211], v[54:57]
	v_mfma_f32_16x16x32_bf16 v[54:57], v[144:147], v[204:207], v[54:57]
	v_mfma_f32_16x16x32_bf16 v[38:41], v[144:147], v[212:215], v[38:41]
	v_mfma_f32_16x16x32_bf16 v[38:41], v[150:153], v[216:219], v[38:41]
	v_mfma_f32_16x16x32_bf16 v[34:37], v[158:161], v[216:219], v[34:37]
	v_mfma_f32_16x16x32_bf16 v[34:37], v[154:157], v[212:215], v[34:37]
	v_mfma_f32_16x16x32_bf16 v[18:21], v[154:157], v[220:223], v[18:21]
	v_mfma_f32_16x16x32_bf16 v[18:21], v[158:161], v[224:227], v[18:21]
	v_mfma_f32_16x16x32_bf16 v[22:25], v[150:153], v[224:227], v[22:25]
	v_mfma_f32_16x16x32_bf16 v[22:25], v[144:147], v[220:223], v[22:25]
	v_mfma_f32_16x16x32_bf16 v[6:9], v[168:171], v[220:223], v[6:9]
	v_mfma_f32_16x16x32_bf16 v[6:9], v[176:179], v[224:227], v[6:9]
	v_mfma_f32_16x16x32_bf16 v[2:5], v[184:187], v[224:227], v[2:5]
	v_mfma_f32_16x16x32_bf16 v[2:5], v[180:183], v[220:223], v[2:5]
	v_mfma_f32_16x16x32_bf16 v[10:13], v[180:183], v[212:215], v[10:13]
	v_mfma_f32_16x16x32_bf16 v[10:13], v[184:187], v[216:219], v[10:13]
	v_mfma_f32_16x16x32_bf16 v[14:17], v[176:179], v[216:219], v[14:17]
	v_mfma_f32_16x16x32_bf16 v[14:17], v[168:171], v[212:215], v[14:17]
	v_mfma_f32_16x16x32_bf16 v[30:33], v[168:171], v[204:207], v[30:33]
	v_mfma_f32_16x16x32_bf16 v[30:33], v[176:179], v[208:211], v[30:33]
	v_mfma_f32_16x16x32_bf16 v[26:29], v[184:187], v[208:211], v[26:29]
	v_mfma_f32_16x16x32_bf16 v[26:29], v[180:183], v[204:207], v[26:29]
	v_mfma_f32_16x16x32_bf16 v[42:45], v[180:183], v[188:191], v[42:45]
	v_mfma_f32_16x16x32_bf16 v[42:45], v[184:187], v[192:195], v[42:45]
	v_mfma_f32_16x16x32_bf16 v[46:49], v[176:179], v[192:195], v[46:49]
	v_mfma_f32_16x16x32_bf16 v[46:49], v[168:171], v[188:191], v[46:49]
	s_barrier
	ds_read_b128 v[144:147], v142
	ds_read_b128 v[150:153], v142 offset:1024
	ds_read_b128 v[154:157], v142 offset:2048
	ds_read_b128 v[158:161], v142 offset:3072
	ds_read_b128 v[168:171], v143
	ds_read_b128 v[176:179], v143 offset:1024
	ds_read_b128 v[180:183], v143 offset:2048
	ds_read_b128 v[184:187], v143 offset:3072
	s_mov_b32 m0, s33
	v_lshl_add_u64 v[232:233], s[18:19], 0, v[130:131]
	ds_read_b128 v[188:191], v141 offset:32768
	ds_read_b128 v[192:195], v141 offset:33792
	ds_read_b128 v[204:207], v141 offset:34816
	ds_read_b128 v[208:211], v141 offset:35840
	ds_read_b128 v[212:215], v141 offset:36864
	ds_read_b128 v[216:219], v141 offset:37888
	ds_read_b128 v[220:223], v141 offset:38912
	ds_read_b128 v[224:227], v141 offset:39936
	global_load_lds_dwordx4 v[232:233], off
	v_lshl_add_u64 v[232:233], s[18:19], 0, v[134:135]
	s_mov_b32 m0, s34
	s_nop 0
	global_load_lds_dwordx4 v[232:233], off
	s_waitcnt vmcnt(8)
	s_waitcnt lgkmcnt(0)
	s_barrier
	v_mfma_f32_16x16x32_bf16 v[126:129], v[144:147], v[188:191], v[126:129]
	v_mfma_f32_16x16x32_bf16 v[126:129], v[150:153], v[192:195], v[126:129]
	v_mfma_f32_16x16x32_bf16 v[122:125], v[158:161], v[192:195], v[122:125]
	v_mfma_f32_16x16x32_bf16 v[122:125], v[154:157], v[188:191], v[122:125]
	v_mfma_f32_16x16x32_bf16 v[114:117], v[154:157], v[204:207], v[114:117]
	v_mfma_f32_16x16x32_bf16 v[114:117], v[158:161], v[208:211], v[114:117]
	v_mfma_f32_16x16x32_bf16 v[118:121], v[150:153], v[208:211], v[118:121]
	v_mfma_f32_16x16x32_bf16 v[118:121], v[144:147], v[204:207], v[118:121]
	v_mfma_f32_16x16x32_bf16 v[102:105], v[144:147], v[212:215], v[102:105]
	v_mfma_f32_16x16x32_bf16 v[102:105], v[150:153], v[216:219], v[102:105]
	v_mfma_f32_16x16x32_bf16 v[98:101], v[158:161], v[216:219], v[98:101]
	v_mfma_f32_16x16x32_bf16 v[98:101], v[154:157], v[212:215], v[98:101]
	v_mfma_f32_16x16x32_bf16 v[82:85], v[154:157], v[220:223], v[82:85]
	v_mfma_f32_16x16x32_bf16 v[82:85], v[158:161], v[224:227], v[82:85]
	v_mfma_f32_16x16x32_bf16 v[86:89], v[150:153], v[224:227], v[86:89]
	v_mfma_f32_16x16x32_bf16 v[86:89], v[144:147], v[220:223], v[86:89]
	v_mfma_f32_16x16x32_bf16 v[70:73], v[168:171], v[220:223], v[70:73]
	v_mfma_f32_16x16x32_bf16 v[70:73], v[176:179], v[224:227], v[70:73]
	v_mfma_f32_16x16x32_bf16 v[66:69], v[184:187], v[224:227], v[66:69]
	v_mfma_f32_16x16x32_bf16 v[66:69], v[180:183], v[220:223], v[66:69]
	v_mfma_f32_16x16x32_bf16 v[74:77], v[180:183], v[212:215], v[74:77]
	v_mfma_f32_16x16x32_bf16 v[74:77], v[184:187], v[216:219], v[74:77]
	v_mfma_f32_16x16x32_bf16 v[78:81], v[176:179], v[216:219], v[78:81]
	v_mfma_f32_16x16x32_bf16 v[78:81], v[168:171], v[212:215], v[78:81]
	v_mfma_f32_16x16x32_bf16 v[94:97], v[168:171], v[204:207], v[94:97]
	v_mfma_f32_16x16x32_bf16 v[94:97], v[176:179], v[208:211], v[94:97]
	v_mfma_f32_16x16x32_bf16 v[90:93], v[184:187], v[208:211], v[90:93]
	v_mfma_f32_16x16x32_bf16 v[90:93], v[180:183], v[204:207], v[90:93]
	v_mfma_f32_16x16x32_bf16 v[106:109], v[180:183], v[188:191], v[106:109]
	v_mfma_f32_16x16x32_bf16 v[106:109], v[184:187], v[192:195], v[106:109]
	v_mfma_f32_16x16x32_bf16 v[110:113], v[176:179], v[192:195], v[110:113]
	v_mfma_f32_16x16x32_bf16 v[110:113], v[168:171], v[188:191], v[110:113]
	s_barrier
	s_mov_b32 m0, s44
	v_lshl_add_u64 v[172:173], v[172:173], 0, s[14:15]
	ds_read_b128 v[188:191], v141 offset:49152
	ds_read_b128 v[192:195], v141 offset:50176
	ds_read_b128 v[204:207], v141 offset:51200
	ds_read_b128 v[208:211], v141 offset:52224
	ds_read_b128 v[212:215], v141 offset:53248
	ds_read_b128 v[216:219], v141 offset:54272
	ds_read_b128 v[220:223], v141 offset:55296
	ds_read_b128 v[224:227], v141 offset:56320
	global_load_lds_dwordx4 v[172:173], off
	v_lshl_add_u64 v[172:173], v[196:197], 0, s[14:15]
	s_mov_b32 m0, s45
	s_nop 0
	global_load_lds_dwordx4 v[172:173], off
	v_lshl_add_u64 v[172:173], s[26:27], 0, v[132:133]
	s_mov_b32 m0, s46
	s_nop 0
	global_load_lds_dwordx4 v[172:173], off
	v_lshl_add_u64 v[172:173], s[26:27], 0, v[136:137]
	s_mov_b32 m0, s47
	s_nop 0
	global_load_lds_dwordx4 v[172:173], off
	v_lshl_add_u64 v[172:173], v[228:229], 0, s[14:15]
	s_mov_b32 m0, s36
	s_nop 0
	global_load_lds_dwordx4 v[172:173], off
	v_lshl_add_u64 v[172:173], v[230:231], 0, s[14:15]
	s_mov_b32 m0, s37
	s_nop 0
	global_load_lds_dwordx4 v[172:173], off
	s_waitcnt vmcnt(8)
	s_waitcnt lgkmcnt(0)
	s_barrier
	v_mfma_f32_16x16x32_bf16 v[62:65], v[144:147], v[188:191], v[62:65]
	v_mfma_f32_16x16x32_bf16 v[62:65], v[150:153], v[192:195], v[62:65]
	v_mfma_f32_16x16x32_bf16 v[58:61], v[158:161], v[192:195], v[58:61]
	v_mfma_f32_16x16x32_bf16 v[58:61], v[154:157], v[188:191], v[58:61]
	v_mfma_f32_16x16x32_bf16 v[50:53], v[154:157], v[204:207], v[50:53]
	v_mfma_f32_16x16x32_bf16 v[50:53], v[158:161], v[208:211], v[50:53]
	v_mfma_f32_16x16x32_bf16 v[54:57], v[150:153], v[208:211], v[54:57]
	v_mfma_f32_16x16x32_bf16 v[54:57], v[144:147], v[204:207], v[54:57]
	v_mfma_f32_16x16x32_bf16 v[38:41], v[144:147], v[212:215], v[38:41]
	v_mfma_f32_16x16x32_bf16 v[38:41], v[150:153], v[216:219], v[38:41]
	v_mfma_f32_16x16x32_bf16 v[34:37], v[158:161], v[216:219], v[34:37]
	v_mfma_f32_16x16x32_bf16 v[34:37], v[154:157], v[212:215], v[34:37]
	v_mfma_f32_16x16x32_bf16 v[18:21], v[154:157], v[220:223], v[18:21]
	v_mfma_f32_16x16x32_bf16 v[18:21], v[158:161], v[224:227], v[18:21]
	v_mfma_f32_16x16x32_bf16 v[22:25], v[150:153], v[224:227], v[22:25]
	v_mfma_f32_16x16x32_bf16 v[22:25], v[144:147], v[220:223], v[22:25]
	v_mfma_f32_16x16x32_bf16 v[6:9], v[168:171], v[220:223], v[6:9]
	v_mfma_f32_16x16x32_bf16 v[6:9], v[176:179], v[224:227], v[6:9]
	v_mfma_f32_16x16x32_bf16 v[2:5], v[184:187], v[224:227], v[2:5]
	v_mfma_f32_16x16x32_bf16 v[2:5], v[180:183], v[220:223], v[2:5]
	v_mfma_f32_16x16x32_bf16 v[10:13], v[180:183], v[212:215], v[10:13]
	v_mfma_f32_16x16x32_bf16 v[10:13], v[184:187], v[216:219], v[10:13]
	v_mfma_f32_16x16x32_bf16 v[14:17], v[176:179], v[216:219], v[14:17]
	v_mfma_f32_16x16x32_bf16 v[14:17], v[168:171], v[212:215], v[14:17]
	v_mfma_f32_16x16x32_bf16 v[30:33], v[168:171], v[204:207], v[30:33]
	v_mfma_f32_16x16x32_bf16 v[30:33], v[176:179], v[208:211], v[30:33]
	v_mfma_f32_16x16x32_bf16 v[26:29], v[184:187], v[208:211], v[26:29]
	v_mfma_f32_16x16x32_bf16 v[26:29], v[180:183], v[204:207], v[26:29]
	v_mfma_f32_16x16x32_bf16 v[42:45], v[180:183], v[188:191], v[42:45]
	v_mfma_f32_16x16x32_bf16 v[42:45], v[184:187], v[192:195], v[42:45]
	v_mfma_f32_16x16x32_bf16 v[46:49], v[176:179], v[192:195], v[46:49]
	v_mfma_f32_16x16x32_bf16 v[46:49], v[168:171], v[188:191], v[46:49]
	s_barrier
	s_andn2_b64 vcc, exec, s[16:17]
	s_mov_b64 s[18:19], -1
	s_mov_b64 s[16:17], 0
	s_movk_i32 s24, 0x100
	s_cbranch_vccz .LBB0_2240
	s_lshl_b32 s7, s30, 21
	v_readlane_b32 s0, v249, 29
	v_lshl_or_b32 v130, s6, 8, v148
	v_mov_b32_e32 v139, 0
	s_add_u32 s8, s0, s7
	v_readlane_b32 s0, v249, 31
	v_or_b32_e32 v130, s35, v130
	v_cvt_pk_bf16_f32 v70, v70, v71
	v_cvt_pk_bf16_f32 v71, v72, v73
	v_cvt_pk_bf16_f32 v72, v66, v67
	v_add_u32_e32 v66, 0x80, v138
	v_mov_b32_e32 v67, v139
	s_addc_u32 s9, s0, 0
	v_ashrrev_i32_e32 v131, 31, v130
	v_lshlrev_b64 v[132:133], 13, v[138:139]
	v_cvt_pk_bf16_f32 v110, v110, v111
	v_cvt_pk_bf16_f32 v111, v112, v113
	v_cvt_pk_bf16_f32 v112, v106, v107
	v_or_b32_e32 v106, 16, v138
	v_mov_b32_e32 v107, v139
	v_lshlrev_b64 v[66:67], 13, v[66:67]
	v_cvt_pk_bf16_f32 v46, v46, v47
	v_cvt_pk_bf16_f32 v47, v48, v49
	v_cvt_pk_bf16_f32 v48, v42, v43
	v_add_u32_e32 v42, 0x90, v138
	v_mov_b32_e32 v43, v139
	v_lshl_add_u64 v[132:133], s[8:9], 0, v[132:133]
	v_lshlrev_b64 v[130:131], 1, v[130:131]
	v_lshlrev_b64 v[106:107], 13, v[106:107]
	v_cvt_pk_bf16_f32 v94, v94, v95
	v_cvt_pk_bf16_f32 v95, v96, v97
	v_cvt_pk_bf16_f32 v96, v90, v91
	v_or_b32_e32 v90, 32, v138
	v_mov_b32_e32 v91, v139
	v_lshl_add_u64 v[66:67], s[8:9], 0, v[66:67]
	v_lshlrev_b64 v[42:43], 13, v[42:43]
	v_cvt_pk_bf16_f32 v30, v30, v31
	v_cvt_pk_bf16_f32 v31, v32, v33
	v_cvt_pk_bf16_f32 v32, v26, v27
	v_add_u32_e32 v26, 0xa0, v138
	v_mov_b32_e32 v27, v139
	v_lshl_add_u64 v[132:133], v[132:133], 0, v[130:131]
	v_cvt_pk_bf16_f32 v113, v108, v109
	v_lshl_add_u64 v[106:107], s[8:9], 0, v[106:107]
	v_lshlrev_b64 v[90:91], 13, v[90:91]
	v_cvt_pk_bf16_f32 v78, v78, v79
	v_cvt_pk_bf16_f32 v79, v80, v81
	v_cvt_pk_bf16_f32 v80, v74, v75
	v_or_b32_e32 v74, 48, v138
	v_mov_b32_e32 v75, v139
	v_lshl_add_u64 v[66:67], v[66:67], 0, v[130:131]
	v_cvt_pk_bf16_f32 v49, v44, v45
	v_lshl_add_u64 v[42:43], s[8:9], 0, v[42:43]
	v_lshlrev_b64 v[26:27], 13, v[26:27]
	v_add_u32_e32 v138, 0xb0, v138
	global_store_dwordx4 v[132:133], v[110:113], off offset:256 sc1
	v_cvt_pk_bf16_f32 v97, v92, v93
	v_lshl_add_u64 v[90:91], s[8:9], 0, v[90:91]
	v_lshl_add_u64 v[110:111], v[106:107], 0, v[130:131]
	v_lshlrev_b64 v[74:75], 13, v[74:75]
	global_store_dwordx4 v[66:67], v[46:49], off offset:256 sc1
	v_cvt_pk_bf16_f32 v33, v28, v29
	v_lshl_add_u64 v[26:27], s[8:9], 0, v[26:27]
	v_lshl_add_u64 v[46:47], v[42:43], 0, v[130:131]
	v_cvt_pk_bf16_f32 v14, v14, v15
	v_cvt_pk_bf16_f32 v15, v16, v17
	v_cvt_pk_bf16_f32 v16, v10, v11
	v_lshlrev_b64 v[10:11], 13, v[138:139]
	global_store_dwordx4 v[110:111], v[94:97], off offset:256 sc1
	v_cvt_pk_bf16_f32 v81, v76, v77
	v_lshl_add_u64 v[74:75], s[8:9], 0, v[74:75]
	v_lshl_add_u64 v[94:95], v[90:91], 0, v[130:131]
	global_store_dwordx4 v[46:47], v[30:33], off offset:256 sc1
	v_cvt_pk_bf16_f32 v17, v12, v13
	v_lshl_add_u64 v[10:11], s[8:9], 0, v[10:11]
	v_lshl_add_u64 v[30:31], v[26:27], 0, v[130:131]
	v_cvt_pk_bf16_f32 v126, v126, v127
	v_cvt_pk_bf16_f32 v127, v128, v129
	v_cvt_pk_bf16_f32 v128, v122, v123
	v_cvt_pk_bf16_f32 v129, v124, v125
	v_cvt_pk_bf16_f32 v106, v118, v119
	v_cvt_pk_bf16_f32 v107, v120, v121
	v_cvt_pk_bf16_f32 v108, v114, v115
	v_cvt_pk_bf16_f32 v109, v116, v117
	v_cvt_pk_bf16_f32 v90, v102, v103
	v_cvt_pk_bf16_f32 v91, v104, v105
	v_cvt_pk_bf16_f32 v92, v98, v99
	v_cvt_pk_bf16_f32 v93, v100, v101
	global_store_dwordx4 v[94:95], v[78:81], off offset:256 sc1
	v_cvt_pk_bf16_f32 v76, v82, v83
	v_cvt_pk_bf16_f32 v77, v84, v85
	v_lshl_add_u64 v[78:79], v[74:75], 0, v[130:131]
	v_cvt_pk_bf16_f32 v74, v86, v87
	v_cvt_pk_bf16_f32 v75, v88, v89
	v_cvt_pk_bf16_f32 v73, v68, v69
	v_cvt_pk_bf16_f32 v62, v62, v63
	v_cvt_pk_bf16_f32 v63, v64, v65
	v_cvt_pk_bf16_f32 v64, v58, v59
	v_cvt_pk_bf16_f32 v65, v60, v61
	v_cvt_pk_bf16_f32 v42, v54, v55
	v_cvt_pk_bf16_f32 v43, v56, v57
	v_cvt_pk_bf16_f32 v44, v50, v51
	v_cvt_pk_bf16_f32 v45, v52, v53
	v_cvt_pk_bf16_f32 v26, v38, v39
	v_cvt_pk_bf16_f32 v27, v40, v41
	v_cvt_pk_bf16_f32 v28, v34, v35
	v_cvt_pk_bf16_f32 v29, v36, v37
	global_store_dwordx4 v[30:31], v[14:17], off offset:256 sc1
	v_cvt_pk_bf16_f32 v12, v18, v19
	v_cvt_pk_bf16_f32 v13, v20, v21
	v_lshl_add_u64 v[14:15], v[10:11], 0, v[130:131]
	v_cvt_pk_bf16_f32 v10, v22, v23
	v_cvt_pk_bf16_f32 v11, v24, v25
	v_cvt_pk_bf16_f32 v6, v6, v7
	v_cvt_pk_bf16_f32 v7, v8, v9
	v_cvt_pk_bf16_f32 v8, v2, v3
	v_cvt_pk_bf16_f32 v9, v4, v5
	global_store_dwordx4 v[132:133], v[126:129], off sc1
	global_store_dwordx4 v[110:111], v[106:109], off sc1
	global_store_dwordx4 v[94:95], v[90:93], off sc1
	global_store_dwordx4 v[78:79], v[74:77], off sc1
	global_store_dwordx4 v[78:79], v[70:73], off offset:256 sc1
	global_store_dwordx4 v[66:67], v[62:65], off sc1
	global_store_dwordx4 v[46:47], v[42:45], off sc1
	global_store_dwordx4 v[30:31], v[26:29], off sc1
	global_store_dwordx4 v[14:15], v[10:13], off sc1
	global_store_dwordx4 v[14:15], v[6:9], off offset:256 sc1
	s_waitcnt vmcnt(0)
	s_cmpk_lt_u32 s3, 0x100
	s_cbranch_scc0 .LBB0_2243
	s_barrier

.LBB0_2376:
	v_readlane_b32 s0, v249, 6
	v_lshl_or_b32 v144, s50, 7, v147
	v_readlane_b32 s1, v249, 7
	v_lshl_add_u32 v153, s51, 8, v146
	v_ashrrev_i32_e32 v145, 31, v144
	v_mov_b64_e32 v[142:143], s[0:1]
	v_mad_u64_u32 v[154:155], s[20:21], v153, s39, v[142:143]
	v_lshlrev_b64 v[144:145], 1, v[144:145]
	v_lshl_add_u64 v[154:155], v[154:155], 0, v[144:145]
	v_mov_b32_e32 v192, 0xbfb8aa3b
	v_mov_b32_e32 v193, 0xbfb8aa3b
	v_mov_b32_e32 v194, 1.0
	v_mov_b32_e32 v195, 1.0
	s_mov_b64 s[22:23], 0x56000
	s_mov_b64 s[24:25], 0x1ae000
	v_pk_mul_f32 v[176:177], v[126:127], v[192:193]
	v_pk_mul_f32 v[178:179], v[128:129], v[192:193]
	v_pk_mul_f32 v[180:181], v[122:123], v[192:193]
	v_pk_mul_f32 v[182:183], v[124:125], v[192:193]
	v_exp_f32_e32 v176, v176
	v_exp_f32_e32 v177, v177
	v_exp_f32_e32 v178, v178
	v_exp_f32_e32 v179, v179
	v_exp_f32_e32 v180, v180
	v_exp_f32_e32 v181, v181
	v_exp_f32_e32 v182, v182
	v_exp_f32_e32 v183, v183
	v_pk_add_f32 v[176:177], v[176:177], v[194:195]
	v_pk_add_f32 v[178:179], v[178:179], v[194:195]
	v_pk_add_f32 v[180:181], v[180:181], v[194:195]
	v_pk_add_f32 v[182:183], v[182:183], v[194:195]
	v_rcp_f32_e32 v176, v176
	v_rcp_f32_e32 v177, v177
	v_rcp_f32_e32 v178, v178
	v_rcp_f32_e32 v179, v179
	v_rcp_f32_e32 v180, v180
	v_rcp_f32_e32 v181, v181
	v_rcp_f32_e32 v182, v182
	v_rcp_f32_e32 v183, v183
	v_lshl_add_u64 v[156:157], v[154:155], 0, s[22:23]
	v_pk_mul_f32 v[126:127], v[126:127], v[176:177]
	v_pk_mul_f32 v[128:129], v[128:129], v[178:179]
	v_pk_mul_f32 v[122:123], v[122:123], v[180:181]
	v_pk_mul_f32 v[124:125], v[124:125], v[182:183]
	v_pk_mul_f32 v[126:127], v[126:127], v[118:119]
	v_pk_mul_f32 v[128:129], v[128:129], v[120:121]
	v_pk_mul_f32 v[122:123], v[122:123], v[114:115]
	v_pk_mul_f32 v[124:125], v[124:125], v[116:117]
	v_cvt_pk_bf16_f32 v184, v126, v127
	v_cvt_pk_bf16_f32 v185, v128, v129
	v_cvt_pk_bf16_f32 v186, v122, v123
	v_cvt_pk_bf16_f32 v187, v124, v125
	global_store_dwordx4 v[154:155], v[184:187], off sc1
	v_pk_mul_f32 v[176:177], v[110:111], v[192:193]
	v_pk_mul_f32 v[178:179], v[112:113], v[192:193]
	v_pk_mul_f32 v[180:181], v[106:107], v[192:193]
	v_pk_mul_f32 v[182:183], v[108:109], v[192:193]
	v_exp_f32_e32 v176, v176
	v_exp_f32_e32 v177, v177
	v_exp_f32_e32 v178, v178
	v_exp_f32_e32 v179, v179
	v_exp_f32_e32 v180, v180
	v_exp_f32_e32 v181, v181
	v_exp_f32_e32 v182, v182
	v_exp_f32_e32 v183, v183
	v_pk_add_f32 v[176:177], v[176:177], v[194:195]
	v_pk_add_f32 v[178:179], v[178:179], v[194:195]
	v_pk_add_f32 v[180:181], v[180:181], v[194:195]
	v_pk_add_f32 v[182:183], v[182:183], v[194:195]
	v_rcp_f32_e32 v176, v176
	v_rcp_f32_e32 v177, v177
	v_rcp_f32_e32 v178, v178
	v_rcp_f32_e32 v179, v179
	v_rcp_f32_e32 v180, v180
	v_rcp_f32_e32 v181, v181
	v_rcp_f32_e32 v182, v182
	v_rcp_f32_e32 v183, v183
	v_lshl_add_u64 v[154:155], v[156:157], 0, s[22:23]
	v_pk_mul_f32 v[110:111], v[110:111], v[176:177]
	v_pk_mul_f32 v[112:113], v[112:113], v[178:179]
	v_pk_mul_f32 v[106:107], v[106:107], v[180:181]
	v_pk_mul_f32 v[108:109], v[108:109], v[182:183]
	v_pk_mul_f32 v[110:111], v[110:111], v[102:103]
	v_pk_mul_f32 v[112:113], v[112:113], v[104:105]
	v_pk_mul_f32 v[106:107], v[106:107], v[98:99]
	v_pk_mul_f32 v[108:109], v[108:109], v[100:101]
	v_cvt_pk_bf16_f32 v188, v110, v111
	v_cvt_pk_bf16_f32 v189, v112, v113
	v_cvt_pk_bf16_f32 v190, v106, v107
	v_cvt_pk_bf16_f32 v191, v108, v109
	global_store_dwordx4 v[156:157], v[188:191], off sc1
	v_pk_mul_f32 v[176:177], v[94:95], v[192:193]
	v_pk_mul_f32 v[178:179], v[96:97], v[192:193]
	v_pk_mul_f32 v[180:181], v[90:91], v[192:193]
	v_pk_mul_f32 v[182:183], v[92:93], v[192:193]
	v_exp_f32_e32 v176, v176
	v_exp_f32_e32 v177, v177
	v_exp_f32_e32 v178, v178
	v_exp_f32_e32 v179, v179
	v_exp_f32_e32 v180, v180
	v_exp_f32_e32 v181, v181
	v_exp_f32_e32 v182, v182
	v_exp_f32_e32 v183, v183
	v_pk_add_f32 v[176:177], v[176:177], v[194:195]
	v_pk_add_f32 v[178:179], v[178:179], v[194:195]
	v_pk_add_f32 v[180:181], v[180:181], v[194:195]
	v_pk_add_f32 v[182:183], v[182:183], v[194:195]
	v_rcp_f32_e32 v176, v176
	v_rcp_f32_e32 v177, v177
	v_rcp_f32_e32 v178, v178
	v_rcp_f32_e32 v179, v179
	v_rcp_f32_e32 v180, v180
	v_rcp_f32_e32 v181, v181
	v_rcp_f32_e32 v182, v182
	v_rcp_f32_e32 v183, v183
	v_lshl_add_u64 v[156:157], v[154:155], 0, s[22:23]
	v_pk_mul_f32 v[94:95], v[94:95], v[176:177]
	v_pk_mul_f32 v[96:97], v[96:97], v[178:179]
	v_pk_mul_f32 v[90:91], v[90:91], v[180:181]
	v_pk_mul_f32 v[92:93], v[92:93], v[182:183]
	v_pk_mul_f32 v[94:95], v[94:95], v[86:87]
	v_pk_mul_f32 v[96:97], v[96:97], v[88:89]
	v_pk_mul_f32 v[90:91], v[90:91], v[82:83]
	v_pk_mul_f32 v[92:93], v[92:93], v[84:85]
	v_cvt_pk_bf16_f32 v184, v94, v95
	v_cvt_pk_bf16_f32 v185, v96, v97
	v_cvt_pk_bf16_f32 v186, v90, v91
	v_cvt_pk_bf16_f32 v187, v92, v93
	global_store_dwordx4 v[154:155], v[184:187], off sc1
	v_pk_mul_f32 v[176:177], v[78:79], v[192:193]
	v_pk_mul_f32 v[178:179], v[80:81], v[192:193]
	v_pk_mul_f32 v[180:181], v[74:75], v[192:193]
	v_pk_mul_f32 v[182:183], v[76:77], v[192:193]
	v_exp_f32_e32 v176, v176
	v_exp_f32_e32 v177, v177
	v_exp_f32_e32 v178, v178
	v_exp_f32_e32 v179, v179
	v_exp_f32_e32 v180, v180
	v_exp_f32_e32 v181, v181
	v_exp_f32_e32 v182, v182
	v_exp_f32_e32 v183, v183
	v_pk_add_f32 v[176:177], v[176:177], v[194:195]
	v_pk_add_f32 v[178:179], v[178:179], v[194:195]
	v_pk_add_f32 v[180:181], v[180:181], v[194:195]
	v_pk_add_f32 v[182:183], v[182:183], v[194:195]
	v_rcp_f32_e32 v176, v176
	v_rcp_f32_e32 v177, v177
	v_rcp_f32_e32 v178, v178
	v_rcp_f32_e32 v179, v179
	v_rcp_f32_e32 v180, v180
	v_rcp_f32_e32 v181, v181
	v_rcp_f32_e32 v182, v182
	v_rcp_f32_e32 v183, v183
	v_lshl_add_u64 v[154:155], v[156:157], 0, s[24:25]
	v_pk_mul_f32 v[78:79], v[78:79], v[176:177]
	v_pk_mul_f32 v[80:81], v[80:81], v[178:179]
	v_pk_mul_f32 v[74:75], v[74:75], v[180:181]
	v_pk_mul_f32 v[76:77], v[76:77], v[182:183]
	v_pk_mul_f32 v[78:79], v[78:79], v[70:71]
	v_pk_mul_f32 v[80:81], v[80:81], v[72:73]
	v_pk_mul_f32 v[74:75], v[74:75], v[66:67]
	v_pk_mul_f32 v[76:77], v[76:77], v[68:69]
	v_cvt_pk_bf16_f32 v188, v78, v79
	v_cvt_pk_bf16_f32 v189, v80, v81
	v_cvt_pk_bf16_f32 v190, v74, v75
	v_cvt_pk_bf16_f32 v191, v76, v77
	global_store_dwordx4 v[156:157], v[188:191], off sc1
	v_pk_mul_f32 v[176:177], v[62:63], v[192:193]
	v_pk_mul_f32 v[178:179], v[64:65], v[192:193]
	v_pk_mul_f32 v[180:181], v[58:59], v[192:193]
	v_pk_mul_f32 v[182:183], v[60:61], v[192:193]
	v_exp_f32_e32 v176, v176
	v_exp_f32_e32 v177, v177
	v_exp_f32_e32 v178, v178
	v_exp_f32_e32 v179, v179
	v_exp_f32_e32 v180, v180
	v_exp_f32_e32 v181, v181
	v_exp_f32_e32 v182, v182
	v_exp_f32_e32 v183, v183
	v_pk_add_f32 v[176:177], v[176:177], v[194:195]
	v_pk_add_f32 v[178:179], v[178:179], v[194:195]
	v_pk_add_f32 v[180:181], v[180:181], v[194:195]
	v_pk_add_f32 v[182:183], v[182:183], v[194:195]
	v_rcp_f32_e32 v176, v176
	v_rcp_f32_e32 v177, v177
	v_rcp_f32_e32 v178, v178
	v_rcp_f32_e32 v179, v179
	v_rcp_f32_e32 v180, v180
	v_rcp_f32_e32 v181, v181
	v_rcp_f32_e32 v182, v182
	v_rcp_f32_e32 v183, v183
	v_lshl_add_u64 v[156:157], v[154:155], 0, s[22:23]
	v_pk_mul_f32 v[62:63], v[62:63], v[176:177]
	v_pk_mul_f32 v[64:65], v[64:65], v[178:179]
	v_pk_mul_f32 v[58:59], v[58:59], v[180:181]
	v_pk_mul_f32 v[60:61], v[60:61], v[182:183]
	v_pk_mul_f32 v[62:63], v[62:63], v[54:55]
	v_pk_mul_f32 v[64:65], v[64:65], v[56:57]
	v_pk_mul_f32 v[58:59], v[58:59], v[50:51]
	v_pk_mul_f32 v[60:61], v[60:61], v[52:53]
	v_cvt_pk_bf16_f32 v184, v62, v63
	v_cvt_pk_bf16_f32 v185, v64, v65
	v_cvt_pk_bf16_f32 v186, v58, v59
	v_cvt_pk_bf16_f32 v187, v60, v61
	global_store_dwordx4 v[154:155], v[184:187], off sc1
	v_pk_mul_f32 v[176:177], v[46:47], v[192:193]
	v_pk_mul_f32 v[178:179], v[48:49], v[192:193]
	v_pk_mul_f32 v[180:181], v[42:43], v[192:193]
	v_pk_mul_f32 v[182:183], v[44:45], v[192:193]
	v_exp_f32_e32 v176, v176
	v_exp_f32_e32 v177, v177
	v_exp_f32_e32 v178, v178
	v_exp_f32_e32 v179, v179
	v_exp_f32_e32 v180, v180
	v_exp_f32_e32 v181, v181
	v_exp_f32_e32 v182, v182
	v_exp_f32_e32 v183, v183
	v_pk_add_f32 v[176:177], v[176:177], v[194:195]
	v_pk_add_f32 v[178:179], v[178:179], v[194:195]
	v_pk_add_f32 v[180:181], v[180:181], v[194:195]
	v_pk_add_f32 v[182:183], v[182:183], v[194:195]
	v_rcp_f32_e32 v176, v176
	v_rcp_f32_e32 v177, v177
	v_rcp_f32_e32 v178, v178
	v_rcp_f32_e32 v179, v179
	v_rcp_f32_e32 v180, v180
	v_rcp_f32_e32 v181, v181
	v_rcp_f32_e32 v182, v182
	v_rcp_f32_e32 v183, v183
	v_lshl_add_u64 v[154:155], v[156:157], 0, s[22:23]
	v_pk_mul_f32 v[46:47], v[46:47], v[176:177]
	v_pk_mul_f32 v[48:49], v[48:49], v[178:179]
	v_pk_mul_f32 v[42:43], v[42:43], v[180:181]
	v_pk_mul_f32 v[44:45], v[44:45], v[182:183]
	v_pk_mul_f32 v[46:47], v[46:47], v[38:39]
	v_pk_mul_f32 v[48:49], v[48:49], v[40:41]
	v_pk_mul_f32 v[42:43], v[42:43], v[34:35]
	v_pk_mul_f32 v[44:45], v[44:45], v[36:37]
	v_cvt_pk_bf16_f32 v188, v46, v47
	v_cvt_pk_bf16_f32 v189, v48, v49
	v_cvt_pk_bf16_f32 v190, v42, v43
	v_cvt_pk_bf16_f32 v191, v44, v45
	global_store_dwordx4 v[156:157], v[188:191], off sc1
	v_pk_mul_f32 v[176:177], v[30:31], v[192:193]
	v_pk_mul_f32 v[178:179], v[32:33], v[192:193]
	v_pk_mul_f32 v[180:181], v[26:27], v[192:193]
	v_pk_mul_f32 v[182:183], v[28:29], v[192:193]
	v_exp_f32_e32 v176, v176
	v_exp_f32_e32 v177, v177
	v_exp_f32_e32 v178, v178
	v_exp_f32_e32 v179, v179
	v_exp_f32_e32 v180, v180
	v_exp_f32_e32 v181, v181
	v_exp_f32_e32 v182, v182
	v_exp_f32_e32 v183, v183
	v_pk_add_f32 v[176:177], v[176:177], v[194:195]
	v_pk_add_f32 v[178:179], v[178:179], v[194:195]
	v_pk_add_f32 v[180:181], v[180:181], v[194:195]
	v_pk_add_f32 v[182:183], v[182:183], v[194:195]
	v_rcp_f32_e32 v176, v176
	v_rcp_f32_e32 v177, v177
	v_rcp_f32_e32 v178, v178
	v_rcp_f32_e32 v179, v179
	v_rcp_f32_e32 v180, v180
	v_rcp_f32_e32 v181, v181
	v_rcp_f32_e32 v182, v182
	v_rcp_f32_e32 v183, v183
	v_lshl_add_u64 v[156:157], v[154:155], 0, s[22:23]
	v_pk_mul_f32 v[30:31], v[30:31], v[176:177]
	v_pk_mul_f32 v[32:33], v[32:33], v[178:179]
	v_pk_mul_f32 v[26:27], v[26:27], v[180:181]
	v_pk_mul_f32 v[28:29], v[28:29], v[182:183]
	v_pk_mul_f32 v[30:31], v[30:31], v[22:23]
	v_pk_mul_f32 v[32:33], v[32:33], v[24:25]
	v_pk_mul_f32 v[26:27], v[26:27], v[18:19]
	v_pk_mul_f32 v[28:29], v[28:29], v[20:21]
	v_cvt_pk_bf16_f32 v184, v30, v31
	v_cvt_pk_bf16_f32 v185, v32, v33
	v_cvt_pk_bf16_f32 v186, v26, v27
	v_cvt_pk_bf16_f32 v187, v28, v29
	global_store_dwordx4 v[154:155], v[184:187], off sc1
	v_pk_mul_f32 v[176:177], v[14:15], v[192:193]
	v_pk_mul_f32 v[178:179], v[16:17], v[192:193]
	v_pk_mul_f32 v[180:181], v[10:11], v[192:193]
	v_pk_mul_f32 v[182:183], v[12:13], v[192:193]
	v_exp_f32_e32 v176, v176
	v_exp_f32_e32 v177, v177
	v_exp_f32_e32 v178, v178
	v_exp_f32_e32 v179, v179
	v_exp_f32_e32 v180, v180
	v_exp_f32_e32 v181, v181
	v_exp_f32_e32 v182, v182
	v_exp_f32_e32 v183, v183
	v_pk_add_f32 v[176:177], v[176:177], v[194:195]
	v_pk_add_f32 v[178:179], v[178:179], v[194:195]
	v_pk_add_f32 v[180:181], v[180:181], v[194:195]
	v_pk_add_f32 v[182:183], v[182:183], v[194:195]
	v_rcp_f32_e32 v176, v176
	v_rcp_f32_e32 v177, v177
	v_rcp_f32_e32 v178, v178
	v_rcp_f32_e32 v179, v179
	v_rcp_f32_e32 v180, v180
	v_rcp_f32_e32 v181, v181
	v_rcp_f32_e32 v182, v182
	v_rcp_f32_e32 v183, v183
	s_nop 0
	v_pk_mul_f32 v[14:15], v[14:15], v[176:177]
	v_pk_mul_f32 v[16:17], v[16:17], v[178:179]
	v_pk_mul_f32 v[10:11], v[10:11], v[180:181]
	v_pk_mul_f32 v[12:13], v[12:13], v[182:183]
	v_pk_mul_f32 v[14:15], v[14:15], v[6:7]
	v_pk_mul_f32 v[16:17], v[16:17], v[8:9]
	v_pk_mul_f32 v[10:11], v[10:11], v[2:3]
	v_pk_mul_f32 v[12:13], v[12:13], v[4:5]
	v_cvt_pk_bf16_f32 v188, v14, v15
	v_cvt_pk_bf16_f32 v189, v16, v17
	v_cvt_pk_bf16_f32 v190, v10, v11
	v_cvt_pk_bf16_f32 v191, v12, v13
	global_store_dwordx4 v[156:157], v[188:191], off sc1
	v_readlane_b32 s60, v250, 50
	v_readlane_b32 s72, v250, 62
	v_readlane_b32 s73, v250, 63
	v_readlane_b32 s61, v250, 51
	v_readlane_b32 s62, v250, 52
	v_readlane_b32 s63, v250, 53
	v_readlane_b32 s64, v250, 54
	v_readlane_b32 s65, v250, 55
	v_readlane_b32 s66, v250, 56
	v_readlane_b32 s67, v250, 57
	v_readlane_b32 s68, v250, 58
	v_readlane_b32 s69, v250, 59
	v_readlane_b32 s70, v250, 60
	v_readlane_b32 s71, v250, 61
	v_readlane_b32 s74, v249, 0
	v_readlane_b32 s75, v249, 1
	s_andn2_b64 vcc, exec, s[18:19]
	s_mov_b64 s[18:19], -1
	s_cbranch_vccnz .LBB0_2371
	s_andn2_b64 vcc, exec, s[12:13]
	s_cbranch_vccnz .LBB0_2370
	s_barrier
	s_branch .LBB0_2370

.LBB0_2621:
	v_lshl_add_u32 v146, s56, 8, v154
	v_lshl_or_b32 v144, s37, 8, v155
	v_ashrrev_i32_e32 v147, 31, v146
	v_ashrrev_i32_e32 v145, 31, v144
	v_lshlrev_b64 v[142:143], 12, v[146:147]
	v_lshl_add_u64 v[142:143], v[142:143], 0, v[144:145]
	v_lshl_add_u64 v[162:163], v[142:143], 1, s[96:97]
	global_load_dwordx4 v[168:171], v[162:163], off
	global_load_dwordx4 v[172:175], v[162:163], off offset:256
	v_or_b32_e32 v162, 16, v146
	v_readlane_b32 s60, v250, 18
	v_ashrrev_i32_e32 v163, 31, v162
	v_readlane_b32 s74, v250, 32
	v_readlane_b32 s75, v250, 33
	v_lshlrev_b64 v[162:163], 12, v[162:163]
	s_mov_b64 s[30:31], s[74:75]
	v_lshl_add_u64 v[176:177], v[142:143], 2, s[30:31]
	v_lshl_add_u64 v[162:163], v[162:163], 0, v[144:145]
	v_lshl_add_u64 v[178:179], v[162:163], 1, s[96:97]
	s_and_b64 vcc, exec, s[4:5]
	s_mov_b64 s[4:5], -1
	v_readlane_b32 s61, v250, 19
	v_readlane_b32 s62, v250, 20
	v_readlane_b32 s63, v250, 21
	v_readlane_b32 s64, v250, 22
	v_readlane_b32 s65, v250, 23
	v_readlane_b32 s66, v250, 24
	v_readlane_b32 s67, v250, 25
	v_readlane_b32 s68, v250, 26
	v_readlane_b32 s69, v250, 27
	v_readlane_b32 s70, v250, 28
	v_readlane_b32 s71, v250, 29
	v_readlane_b32 s72, v250, 30
	v_readlane_b32 s73, v250, 31
	s_waitcnt vmcnt(0)
	v_lshlrev_b32_e32 v180, 16, v168
	v_and_b32_e32 v181, 0xffff0000, v168
	v_lshlrev_b32_e32 v168, 16, v169
	v_and_b32_e32 v169, 0xffff0000, v169
	v_lshlrev_b32_e32 v182, 16, v170
	v_and_b32_e32 v183, 0xffff0000, v170
	v_lshlrev_b32_e32 v170, 16, v171
	v_and_b32_e32 v171, 0xffff0000, v171
	v_lshlrev_b32_e32 v184, 16, v172
	v_and_b32_e32 v185, 0xffff0000, v172
	v_lshlrev_b32_e32 v172, 16, v173
	v_and_b32_e32 v173, 0xffff0000, v173
	v_lshlrev_b32_e32 v186, 16, v174
	v_and_b32_e32 v187, 0xffff0000, v174
	v_lshlrev_b32_e32 v174, 16, v175
	v_and_b32_e32 v175, 0xffff0000, v175
	v_pk_add_f32 v[128:129], v[128:129], v[168:169]
	v_pk_add_f32 v[126:127], v[126:127], v[180:181]
	v_pk_add_f32 v[124:125], v[124:125], v[170:171]
	v_pk_add_f32 v[122:123], v[122:123], v[182:183]
	v_pk_add_f32 v[120:121], v[120:121], v[172:173]
	v_pk_add_f32 v[118:119], v[118:119], v[184:185]
	v_pk_add_f32 v[116:117], v[116:117], v[174:175]
	v_pk_add_f32 v[114:115], v[114:115], v[186:187]
	global_store_dwordx4 v[176:177], v[126:129], off sc1
	global_store_dwordx4 v[176:177], v[122:125], off offset:16 sc1
	global_store_dwordx4 v[176:177], v[118:121], off offset:512 sc1
	global_store_dwordx4 v[176:177], v[114:117], off offset:528 sc1
	global_load_dwordx4 v[114:117], v[178:179], off
	s_nop 0
	global_load_dwordx4 v[118:121], v[178:179], off offset:256
	v_or_b32_e32 v122, 32, v146
	v_ashrrev_i32_e32 v123, 31, v122
	v_lshlrev_b64 v[122:123], 12, v[122:123]
	v_lshl_add_u64 v[122:123], v[122:123], 0, v[144:145]
	v_lshl_add_u64 v[124:125], v[162:163], 2, s[30:31]
	v_lshl_add_u64 v[126:127], v[122:123], 1, s[96:97]
	s_waitcnt vmcnt(1)
	v_lshlrev_b32_e32 v128, 16, v114
	v_and_b32_e32 v129, 0xffff0000, v114
	v_lshlrev_b32_e32 v114, 16, v115
	v_and_b32_e32 v115, 0xffff0000, v115
	v_lshlrev_b32_e32 v162, 16, v116
	v_and_b32_e32 v163, 0xffff0000, v116
	v_lshlrev_b32_e32 v116, 16, v117
	v_and_b32_e32 v117, 0xffff0000, v117
	s_waitcnt vmcnt(0)
	v_lshlrev_b32_e32 v168, 16, v118
	v_and_b32_e32 v169, 0xffff0000, v118
	v_lshlrev_b32_e32 v118, 16, v119
	v_and_b32_e32 v119, 0xffff0000, v119
	v_lshlrev_b32_e32 v170, 16, v120
	v_and_b32_e32 v171, 0xffff0000, v120
	v_lshlrev_b32_e32 v120, 16, v121
	v_and_b32_e32 v121, 0xffff0000, v121
	v_pk_add_f32 v[112:113], v[112:113], v[114:115]
	v_pk_add_f32 v[110:111], v[110:111], v[128:129]
	v_pk_add_f32 v[108:109], v[108:109], v[116:117]
	v_pk_add_f32 v[106:107], v[106:107], v[162:163]
	v_pk_add_f32 v[104:105], v[104:105], v[118:119]
	v_pk_add_f32 v[102:103], v[102:103], v[168:169]
	v_pk_add_f32 v[100:101], v[100:101], v[120:121]
	v_pk_add_f32 v[98:99], v[98:99], v[170:171]
	global_store_dwordx4 v[124:125], v[110:113], off sc1
	global_store_dwordx4 v[124:125], v[106:109], off offset:16 sc1
	global_store_dwordx4 v[124:125], v[102:105], off offset:512 sc1
	global_store_dwordx4 v[124:125], v[98:101], off offset:528 sc1
	global_load_dwordx4 v[98:101], v[126:127], off
	s_nop 0
	global_load_dwordx4 v[102:105], v[126:127], off offset:256
	v_or_b32_e32 v106, 48, v146
	v_ashrrev_i32_e32 v107, 31, v106
	v_lshlrev_b64 v[106:107], 12, v[106:107]
	v_lshl_add_u64 v[106:107], v[106:107], 0, v[144:145]
	v_lshl_add_u64 v[108:109], v[122:123], 2, s[30:31]
	v_lshl_add_u64 v[110:111], v[106:107], 1, s[96:97]
	s_waitcnt vmcnt(1)
	v_lshlrev_b32_e32 v112, 16, v98
	v_and_b32_e32 v113, 0xffff0000, v98
	v_lshlrev_b32_e32 v98, 16, v99
	v_and_b32_e32 v99, 0xffff0000, v99
	v_lshlrev_b32_e32 v114, 16, v100
	v_and_b32_e32 v115, 0xffff0000, v100
	v_lshlrev_b32_e32 v100, 16, v101
	v_and_b32_e32 v101, 0xffff0000, v101
	s_waitcnt vmcnt(0)
	v_lshlrev_b32_e32 v116, 16, v102
	v_and_b32_e32 v117, 0xffff0000, v102
	v_lshlrev_b32_e32 v102, 16, v103
	v_and_b32_e32 v103, 0xffff0000, v103
	v_lshlrev_b32_e32 v118, 16, v104
	v_and_b32_e32 v119, 0xffff0000, v104
	v_lshlrev_b32_e32 v104, 16, v105
	v_and_b32_e32 v105, 0xffff0000, v105
	v_pk_add_f32 v[96:97], v[96:97], v[98:99]
	v_pk_add_f32 v[94:95], v[94:95], v[112:113]
	v_pk_add_f32 v[92:93], v[92:93], v[100:101]
	v_pk_add_f32 v[90:91], v[90:91], v[114:115]
	v_pk_add_f32 v[88:89], v[88:89], v[102:103]
	v_pk_add_f32 v[86:87], v[86:87], v[116:117]
	v_pk_add_f32 v[84:85], v[84:85], v[104:105]
	v_pk_add_f32 v[82:83], v[82:83], v[118:119]
	global_store_dwordx4 v[108:109], v[94:97], off sc1
	global_store_dwordx4 v[108:109], v[90:93], off offset:16 sc1
	global_store_dwordx4 v[108:109], v[86:89], off offset:512 sc1
	global_store_dwordx4 v[108:109], v[82:85], off offset:528 sc1
	global_load_dwordx4 v[82:85], v[110:111], off
	s_nop 0
	global_load_dwordx4 v[86:89], v[110:111], off offset:256
	v_lshl_add_u64 v[90:91], v[142:143], 0, s[14:15]
	v_lshl_add_u64 v[92:93], v[106:107], 2, s[30:31]
	v_lshl_add_u64 v[94:95], v[90:91], 1, s[96:97]
	s_waitcnt vmcnt(1)
	v_lshlrev_b32_e32 v96, 16, v82
	v_and_b32_e32 v97, 0xffff0000, v82
	v_lshlrev_b32_e32 v82, 16, v83
	v_and_b32_e32 v83, 0xffff0000, v83
	v_lshlrev_b32_e32 v98, 16, v84
	v_and_b32_e32 v99, 0xffff0000, v84
	v_lshlrev_b32_e32 v84, 16, v85
	v_and_b32_e32 v85, 0xffff0000, v85
	s_waitcnt vmcnt(0)
	v_lshlrev_b32_e32 v100, 16, v86
	v_and_b32_e32 v101, 0xffff0000, v86
	v_lshlrev_b32_e32 v86, 16, v87
	v_and_b32_e32 v87, 0xffff0000, v87
	v_lshlrev_b32_e32 v102, 16, v88
	v_and_b32_e32 v103, 0xffff0000, v88
	v_lshlrev_b32_e32 v88, 16, v89
	v_and_b32_e32 v89, 0xffff0000, v89
	v_pk_add_f32 v[80:81], v[80:81], v[82:83]
	v_pk_add_f32 v[78:79], v[78:79], v[96:97]
	v_pk_add_f32 v[76:77], v[76:77], v[84:85]
	v_pk_add_f32 v[74:75], v[74:75], v[98:99]
	v_pk_add_f32 v[72:73], v[72:73], v[86:87]
	v_pk_add_f32 v[70:71], v[70:71], v[100:101]
	v_pk_add_f32 v[68:69], v[68:69], v[88:89]
	v_pk_add_f32 v[66:67], v[66:67], v[102:103]
	global_store_dwordx4 v[92:93], v[78:81], off sc1
	global_store_dwordx4 v[92:93], v[74:77], off offset:16 sc1
	global_store_dwordx4 v[92:93], v[70:73], off offset:512 sc1
	global_store_dwordx4 v[92:93], v[66:69], off offset:528 sc1
	global_load_dwordx4 v[66:69], v[94:95], off
	s_nop 0
	global_load_dwordx4 v[70:73], v[94:95], off offset:256
	v_lshl_add_u64 v[74:75], v[142:143], 0, s[16:17]
	v_lshl_add_u64 v[76:77], v[90:91], 2, s[30:31]
	v_lshl_add_u64 v[78:79], v[74:75], 1, s[96:97]
	s_waitcnt vmcnt(1)
	v_lshlrev_b32_e32 v80, 16, v66
	v_and_b32_e32 v81, 0xffff0000, v66
	v_lshlrev_b32_e32 v66, 16, v67
	v_and_b32_e32 v67, 0xffff0000, v67
	v_lshlrev_b32_e32 v82, 16, v68
	v_and_b32_e32 v83, 0xffff0000, v68
	v_lshlrev_b32_e32 v68, 16, v69
	v_and_b32_e32 v69, 0xffff0000, v69
	s_waitcnt vmcnt(0)
	v_lshlrev_b32_e32 v84, 16, v70
	v_and_b32_e32 v85, 0xffff0000, v70
	v_lshlrev_b32_e32 v70, 16, v71
	v_and_b32_e32 v71, 0xffff0000, v71
	v_lshlrev_b32_e32 v86, 16, v72
	v_and_b32_e32 v87, 0xffff0000, v72
	v_lshlrev_b32_e32 v72, 16, v73
	v_and_b32_e32 v73, 0xffff0000, v73
	v_pk_add_f32 v[64:65], v[64:65], v[66:67]
	v_pk_add_f32 v[62:63], v[62:63], v[80:81]
	v_pk_add_f32 v[60:61], v[60:61], v[68:69]
	v_pk_add_f32 v[58:59], v[58:59], v[82:83]
	v_pk_add_f32 v[56:57], v[56:57], v[70:71]
	v_pk_add_f32 v[54:55], v[54:55], v[84:85]
	v_pk_add_f32 v[52:53], v[52:53], v[72:73]
	v_pk_add_f32 v[50:51], v[50:51], v[86:87]
	global_store_dwordx4 v[76:77], v[62:65], off sc1
	global_store_dwordx4 v[76:77], v[58:61], off offset:16 sc1
	global_store_dwordx4 v[76:77], v[54:57], off offset:512 sc1
	global_store_dwordx4 v[76:77], v[50:53], off offset:528 sc1
	global_load_dwordx4 v[50:53], v[78:79], off
	s_nop 0
	global_load_dwordx4 v[54:57], v[78:79], off offset:256
	v_lshl_add_u64 v[58:59], v[142:143], 0, s[18:19]
	v_lshl_add_u64 v[60:61], v[74:75], 2, s[30:31]
	v_lshl_add_u64 v[62:63], v[58:59], 1, s[96:97]
	s_waitcnt vmcnt(1)
	v_lshlrev_b32_e32 v64, 16, v50
	v_and_b32_e32 v65, 0xffff0000, v50
	v_lshlrev_b32_e32 v50, 16, v51
	v_and_b32_e32 v51, 0xffff0000, v51
	v_lshlrev_b32_e32 v66, 16, v52
	v_and_b32_e32 v67, 0xffff0000, v52
	v_lshlrev_b32_e32 v52, 16, v53
	v_and_b32_e32 v53, 0xffff0000, v53
	s_waitcnt vmcnt(0)
	v_lshlrev_b32_e32 v68, 16, v54
	v_and_b32_e32 v69, 0xffff0000, v54
	v_lshlrev_b32_e32 v54, 16, v55
	v_and_b32_e32 v55, 0xffff0000, v55
	v_lshlrev_b32_e32 v70, 16, v56
	v_and_b32_e32 v71, 0xffff0000, v56
	v_lshlrev_b32_e32 v56, 16, v57
	v_and_b32_e32 v57, 0xffff0000, v57
	v_pk_add_f32 v[48:49], v[48:49], v[50:51]
	v_pk_add_f32 v[46:47], v[46:47], v[64:65]
	v_pk_add_f32 v[44:45], v[44:45], v[52:53]
	v_pk_add_f32 v[42:43], v[42:43], v[66:67]
	v_pk_add_f32 v[40:41], v[40:41], v[54:55]
	v_pk_add_f32 v[38:39], v[38:39], v[68:69]
	v_pk_add_f32 v[36:37], v[36:37], v[56:57]
	v_pk_add_f32 v[34:35], v[34:35], v[70:71]
	global_store_dwordx4 v[60:61], v[46:49], off sc1
	global_store_dwordx4 v[60:61], v[42:45], off offset:16 sc1
	global_store_dwordx4 v[60:61], v[38:41], off offset:512 sc1
	global_store_dwordx4 v[60:61], v[34:37], off offset:528 sc1
	global_load_dwordx4 v[34:37], v[62:63], off
	s_nop 0
	global_load_dwordx4 v[38:41], v[62:63], off offset:256
	v_lshl_add_u64 v[42:43], v[142:143], 0, s[20:21]
	v_lshl_add_u64 v[44:45], v[58:59], 2, s[30:31]
	v_lshl_add_u64 v[46:47], v[42:43], 1, s[96:97]
	s_waitcnt vmcnt(1)
	v_lshlrev_b32_e32 v48, 16, v34
	v_and_b32_e32 v49, 0xffff0000, v34
	v_lshlrev_b32_e32 v34, 16, v35
	v_and_b32_e32 v35, 0xffff0000, v35
	v_lshlrev_b32_e32 v50, 16, v36
	v_and_b32_e32 v51, 0xffff0000, v36
	v_lshlrev_b32_e32 v36, 16, v37
	v_and_b32_e32 v37, 0xffff0000, v37
	s_waitcnt vmcnt(0)
	v_lshlrev_b32_e32 v52, 16, v38
	v_and_b32_e32 v53, 0xffff0000, v38
	v_lshlrev_b32_e32 v38, 16, v39
	v_and_b32_e32 v39, 0xffff0000, v39
	v_lshlrev_b32_e32 v54, 16, v40
	v_and_b32_e32 v55, 0xffff0000, v40
	v_lshlrev_b32_e32 v40, 16, v41
	v_and_b32_e32 v41, 0xffff0000, v41
	v_pk_add_f32 v[32:33], v[32:33], v[34:35]
	v_pk_add_f32 v[30:31], v[30:31], v[48:49]
	v_pk_add_f32 v[28:29], v[28:29], v[36:37]
	v_pk_add_f32 v[26:27], v[26:27], v[50:51]
	v_pk_add_f32 v[24:25], v[24:25], v[38:39]
	v_pk_add_f32 v[22:23], v[22:23], v[52:53]
	v_pk_add_f32 v[20:21], v[20:21], v[40:41]
	v_pk_add_f32 v[18:19], v[18:19], v[54:55]
	global_store_dwordx4 v[44:45], v[30:33], off sc1
	global_store_dwordx4 v[44:45], v[26:29], off offset:16 sc1
	global_store_dwordx4 v[44:45], v[22:25], off offset:512 sc1
	global_store_dwordx4 v[44:45], v[18:21], off offset:528 sc1
	global_load_dwordx4 v[18:21], v[46:47], off
	s_nop 0
	global_load_dwordx4 v[22:25], v[46:47], off offset:256
	v_lshl_add_u64 v[26:27], v[42:43], 2, s[30:31]
	s_waitcnt vmcnt(1)
	v_lshlrev_b32_e32 v28, 16, v18
	v_and_b32_e32 v29, 0xffff0000, v18
	v_lshlrev_b32_e32 v18, 16, v19
	v_and_b32_e32 v19, 0xffff0000, v19
	v_lshlrev_b32_e32 v30, 16, v20
	v_and_b32_e32 v31, 0xffff0000, v20
	v_lshlrev_b32_e32 v20, 16, v21
	v_and_b32_e32 v21, 0xffff0000, v21
	s_waitcnt vmcnt(0)
	v_lshlrev_b32_e32 v32, 16, v22
	v_and_b32_e32 v33, 0xffff0000, v22
	v_lshlrev_b32_e32 v22, 16, v23
	v_and_b32_e32 v23, 0xffff0000, v23
	v_lshlrev_b32_e32 v34, 16, v24
	v_and_b32_e32 v35, 0xffff0000, v24
	v_lshlrev_b32_e32 v24, 16, v25
	v_and_b32_e32 v25, 0xffff0000, v25
	v_pk_add_f32 v[16:17], v[16:17], v[18:19]
	v_pk_add_f32 v[14:15], v[14:15], v[28:29]
	v_pk_add_f32 v[12:13], v[12:13], v[20:21]
	v_pk_add_f32 v[10:11], v[10:11], v[30:31]
	v_pk_add_f32 v[8:9], v[8:9], v[22:23]
	v_pk_add_f32 v[6:7], v[6:7], v[32:33]
	v_pk_add_f32 v[4:5], v[4:5], v[24:25]
	v_pk_add_f32 v[2:3], v[2:3], v[34:35]
	global_store_dwordx4 v[26:27], v[14:17], off sc1
	global_store_dwordx4 v[26:27], v[10:13], off offset:16 sc1
	global_store_dwordx4 v[26:27], v[6:9], off offset:512 sc1
	global_store_dwordx4 v[26:27], v[2:5], off offset:528 sc1
	s_cbranch_vccnz .LBB0_2614
	s_and_b64 s[4:5], s[26:27], exec
	s_cselect_b32 s37, s57, s37
	s_cselect_b32 s56, s38, s56
	s_andn2_b64 vcc, exec, s[8:9]
	s_cbranch_vccnz .LBB0_2613
	s_barrier
	s_branch .LBB0_2613

.LBB0_2632:
	ds_read_b128 v[150:153], v1
	ds_read_b128 v[154:157], v1 offset:1024
	ds_read_b128 v[158:161], v1 offset:2048
	ds_read_b128 v[166:169], v1 offset:3072
	ds_read_b128 v[170:173], v139
	ds_read_b128 v[174:177], v139 offset:1024
	ds_read_b128 v[178:181], v139 offset:2048
	ds_read_b128 v[182:185], v139 offset:3072
	s_add_i32 s38, s13, 2
	s_add_u32 s12, s10, 0xc2050080
	s_addc_u32 s14, s11, -1
	s_cmp_lg_u32 s26, s13
	s_cselect_b32 s12, s12, 0
	s_cselect_b32 s13, s14, 0
	s_add_u32 s14, s4, s12
	s_addc_u32 s15, s5, s13
	s_add_u32 s12, s6, s12
	s_addc_u32 s13, s7, s13
	s_mov_b32 m0, s27
	v_lshl_add_u64 v[162:163], v[140:141], 0, s[10:11]
	ds_read_b128 v[186:189], v144
	ds_read_b128 v[190:193], v144 offset:1024
	ds_read_b128 v[194:197], v144 offset:2048
	ds_read_b128 v[198:201], v144 offset:3072
	ds_read_b128 v[202:205], v144 offset:4096
	ds_read_b128 v[206:209], v144 offset:5120
	ds_read_b128 v[210:213], v144 offset:6144
	ds_read_b128 v[214:217], v144 offset:7168
	global_load_lds_dwordx4 v[162:163], off
	v_lshl_add_u64 v[162:163], v[142:143], 0, s[10:11]
	s_mov_b32 m0, s28
	s_nop 0
	global_load_lds_dwordx4 v[162:163], off
	s_waitcnt vmcnt(8)
	s_waitcnt lgkmcnt(0)
	s_barrier
	v_mfma_f32_16x16x32_bf16 v[126:129], v[150:153], v[186:189], v[126:129]
	v_mfma_f32_16x16x32_bf16 v[126:129], v[154:157], v[190:193], v[126:129]
	v_mfma_f32_16x16x32_bf16 v[122:125], v[166:169], v[190:193], v[122:125]
	v_mfma_f32_16x16x32_bf16 v[122:125], v[158:161], v[186:189], v[122:125]
	v_mfma_f32_16x16x32_bf16 v[114:117], v[158:161], v[194:197], v[114:117]
	v_mfma_f32_16x16x32_bf16 v[114:117], v[166:169], v[198:201], v[114:117]
	v_mfma_f32_16x16x32_bf16 v[118:121], v[154:157], v[198:201], v[118:121]
	v_mfma_f32_16x16x32_bf16 v[118:121], v[150:153], v[194:197], v[118:121]
	v_mfma_f32_16x16x32_bf16 v[102:105], v[150:153], v[202:205], v[102:105]
	v_mfma_f32_16x16x32_bf16 v[102:105], v[154:157], v[206:209], v[102:105]
	v_mfma_f32_16x16x32_bf16 v[98:101], v[166:169], v[206:209], v[98:101]
	v_mfma_f32_16x16x32_bf16 v[98:101], v[158:161], v[202:205], v[98:101]
	v_mfma_f32_16x16x32_bf16 v[82:85], v[158:161], v[210:213], v[82:85]
	v_mfma_f32_16x16x32_bf16 v[82:85], v[166:169], v[214:217], v[82:85]
	v_mfma_f32_16x16x32_bf16 v[86:89], v[154:157], v[214:217], v[86:89]
	v_mfma_f32_16x16x32_bf16 v[86:89], v[150:153], v[210:213], v[86:89]
	v_mfma_f32_16x16x32_bf16 v[70:73], v[170:173], v[210:213], v[70:73]
	v_mfma_f32_16x16x32_bf16 v[70:73], v[174:177], v[214:217], v[70:73]
	v_mfma_f32_16x16x32_bf16 v[66:69], v[182:185], v[214:217], v[66:69]
	v_mfma_f32_16x16x32_bf16 v[66:69], v[178:181], v[210:213], v[66:69]
	v_mfma_f32_16x16x32_bf16 v[74:77], v[178:181], v[202:205], v[74:77]
	v_mfma_f32_16x16x32_bf16 v[74:77], v[182:185], v[206:209], v[74:77]
	v_mfma_f32_16x16x32_bf16 v[78:81], v[174:177], v[206:209], v[78:81]
	v_mfma_f32_16x16x32_bf16 v[78:81], v[170:173], v[202:205], v[78:81]
	v_mfma_f32_16x16x32_bf16 v[94:97], v[170:173], v[194:197], v[94:97]
	v_mfma_f32_16x16x32_bf16 v[94:97], v[174:177], v[198:201], v[94:97]
	v_mfma_f32_16x16x32_bf16 v[90:93], v[182:185], v[198:201], v[90:93]
	v_mfma_f32_16x16x32_bf16 v[90:93], v[178:181], v[194:197], v[90:93]
	v_mfma_f32_16x16x32_bf16 v[106:109], v[178:181], v[186:189], v[106:109]
	v_mfma_f32_16x16x32_bf16 v[106:109], v[182:185], v[190:193], v[106:109]
	v_mfma_f32_16x16x32_bf16 v[110:113], v[174:177], v[190:193], v[110:113]
	v_mfma_f32_16x16x32_bf16 v[110:113], v[170:173], v[186:189], v[110:113]
	s_barrier
	s_mov_b32 m0, s29
	v_lshl_add_u64 v[162:163], s[12:13], 0, v[132:133]
	s_add_u32 s40, s12, 0x2b0000
	ds_read_b128 v[186:189], v144 offset:16384
	ds_read_b128 v[190:193], v144 offset:17408
	ds_read_b128 v[194:197], v144 offset:18432
	ds_read_b128 v[198:201], v144 offset:19456
	ds_read_b128 v[202:205], v144 offset:20480
	ds_read_b128 v[206:209], v144 offset:21504
	ds_read_b128 v[210:213], v144 offset:22528
	ds_read_b128 v[214:217], v144 offset:23552
	global_load_lds_dwordx4 v[162:163], off
	v_lshl_add_u64 v[218:219], s[12:13], 0, v[136:137]
	s_mov_b32 m0, s30
	s_addc_u32 s41, s13, 0
	global_load_lds_dwordx4 v[218:219], off
	v_lshl_add_u64 v[220:221], s[40:41], 0, v[132:133]
	s_mov_b32 m0, s31
	v_lshl_add_u64 v[222:223], s[14:15], 0, v[134:135]
	global_load_lds_dwordx4 v[220:221], off
	v_lshl_add_u64 v[220:221], s[40:41], 0, v[136:137]
	s_mov_b32 m0, s33
	s_nop 0
	global_load_lds_dwordx4 v[220:221], off
	v_lshl_add_u64 v[220:221], s[14:15], 0, v[130:131]
	s_mov_b32 m0, s19
	s_nop 0
	global_load_lds_dwordx4 v[220:221], off
	s_mov_b32 m0, s20
	s_nop 0
	global_load_lds_dwordx4 v[222:223], off
	s_waitcnt vmcnt(8)
	s_waitcnt lgkmcnt(0)
	s_barrier
	v_mfma_f32_16x16x32_bf16 v[62:65], v[150:153], v[186:189], v[62:65]
	v_mfma_f32_16x16x32_bf16 v[62:65], v[154:157], v[190:193], v[62:65]
	v_mfma_f32_16x16x32_bf16 v[58:61], v[166:169], v[190:193], v[58:61]
	v_mfma_f32_16x16x32_bf16 v[58:61], v[158:161], v[186:189], v[58:61]
	v_mfma_f32_16x16x32_bf16 v[50:53], v[158:161], v[194:197], v[50:53]
	v_mfma_f32_16x16x32_bf16 v[50:53], v[166:169], v[198:201], v[50:53]
	v_mfma_f32_16x16x32_bf16 v[54:57], v[154:157], v[198:201], v[54:57]
	v_mfma_f32_16x16x32_bf16 v[54:57], v[150:153], v[194:197], v[54:57]
	v_mfma_f32_16x16x32_bf16 v[38:41], v[150:153], v[202:205], v[38:41]
	v_mfma_f32_16x16x32_bf16 v[38:41], v[154:157], v[206:209], v[38:41]
	v_mfma_f32_16x16x32_bf16 v[34:37], v[166:169], v[206:209], v[34:37]
	v_mfma_f32_16x16x32_bf16 v[34:37], v[158:161], v[202:205], v[34:37]
	v_mfma_f32_16x16x32_bf16 v[18:21], v[158:161], v[210:213], v[18:21]
	v_mfma_f32_16x16x32_bf16 v[18:21], v[166:169], v[214:217], v[18:21]
	v_mfma_f32_16x16x32_bf16 v[22:25], v[154:157], v[214:217], v[22:25]
	v_mfma_f32_16x16x32_bf16 v[22:25], v[150:153], v[210:213], v[22:25]
	v_mfma_f32_16x16x32_bf16 v[6:9], v[170:173], v[210:213], v[6:9]
	v_mfma_f32_16x16x32_bf16 v[6:9], v[174:177], v[214:217], v[6:9]
	v_mfma_f32_16x16x32_bf16 v[2:5], v[182:185], v[214:217], v[2:5]
	v_mfma_f32_16x16x32_bf16 v[2:5], v[178:181], v[210:213], v[2:5]
	v_mfma_f32_16x16x32_bf16 v[10:13], v[178:181], v[202:205], v[10:13]
	v_mfma_f32_16x16x32_bf16 v[10:13], v[182:185], v[206:209], v[10:13]
	v_mfma_f32_16x16x32_bf16 v[14:17], v[174:177], v[206:209], v[14:17]
	v_mfma_f32_16x16x32_bf16 v[14:17], v[170:173], v[202:205], v[14:17]
	v_mfma_f32_16x16x32_bf16 v[30:33], v[170:173], v[194:197], v[30:33]
	v_mfma_f32_16x16x32_bf16 v[30:33], v[174:177], v[198:201], v[30:33]
	v_mfma_f32_16x16x32_bf16 v[26:29], v[182:185], v[198:201], v[26:29]
	v_mfma_f32_16x16x32_bf16 v[26:29], v[178:181], v[194:197], v[26:29]
	v_mfma_f32_16x16x32_bf16 v[42:45], v[178:181], v[186:189], v[42:45]
	v_mfma_f32_16x16x32_bf16 v[42:45], v[182:185], v[190:193], v[42:45]
	v_mfma_f32_16x16x32_bf16 v[46:49], v[174:177], v[190:193], v[46:49]
	v_mfma_f32_16x16x32_bf16 v[46:49], v[170:173], v[186:189], v[46:49]
	s_barrier
	ds_read_b128 v[150:153], v145
	ds_read_b128 v[154:157], v145 offset:1024
	ds_read_b128 v[158:161], v145 offset:2048
	ds_read_b128 v[166:169], v145 offset:3072
	ds_read_b128 v[170:173], v146
	ds_read_b128 v[174:177], v146 offset:1024
	ds_read_b128 v[178:181], v146 offset:2048
	ds_read_b128 v[182:185], v146 offset:3072
	s_add_u32 s14, s14, 0x2b0000
	s_addc_u32 s15, s15, 0
	s_mov_b32 m0, s21
	v_lshl_add_u64 v[224:225], s[14:15], 0, v[130:131]
	ds_read_b128 v[186:189], v144 offset:32768
	ds_read_b128 v[190:193], v144 offset:33792
	ds_read_b128 v[194:197], v144 offset:34816
	ds_read_b128 v[198:201], v144 offset:35840
	ds_read_b128 v[202:205], v144 offset:36864
	ds_read_b128 v[206:209], v144 offset:37888
	ds_read_b128 v[210:213], v144 offset:38912
	ds_read_b128 v[214:217], v144 offset:39936
	global_load_lds_dwordx4 v[224:225], off
	v_lshl_add_u64 v[224:225], s[14:15], 0, v[134:135]
	s_mov_b32 m0, s22
	s_nop 0
	global_load_lds_dwordx4 v[224:225], off
	s_waitcnt vmcnt(8)
	s_waitcnt lgkmcnt(0)
	s_barrier
	v_mfma_f32_16x16x32_bf16 v[126:129], v[150:153], v[186:189], v[126:129]
	v_mfma_f32_16x16x32_bf16 v[126:129], v[154:157], v[190:193], v[126:129]
	v_mfma_f32_16x16x32_bf16 v[122:125], v[166:169], v[190:193], v[122:125]
	v_mfma_f32_16x16x32_bf16 v[122:125], v[158:161], v[186:189], v[122:125]
	v_mfma_f32_16x16x32_bf16 v[114:117], v[158:161], v[194:197], v[114:117]
	v_mfma_f32_16x16x32_bf16 v[114:117], v[166:169], v[198:201], v[114:117]
	v_mfma_f32_16x16x32_bf16 v[118:121], v[154:157], v[198:201], v[118:121]
	v_mfma_f32_16x16x32_bf16 v[118:121], v[150:153], v[194:197], v[118:121]
	v_mfma_f32_16x16x32_bf16 v[102:105], v[150:153], v[202:205], v[102:105]
	v_mfma_f32_16x16x32_bf16 v[102:105], v[154:157], v[206:209], v[102:105]
	v_mfma_f32_16x16x32_bf16 v[98:101], v[166:169], v[206:209], v[98:101]
	v_mfma_f32_16x16x32_bf16 v[98:101], v[158:161], v[202:205], v[98:101]
	v_mfma_f32_16x16x32_bf16 v[82:85], v[158:161], v[210:213], v[82:85]
	v_mfma_f32_16x16x32_bf16 v[82:85], v[166:169], v[214:217], v[82:85]
	v_mfma_f32_16x16x32_bf16 v[86:89], v[154:157], v[214:217], v[86:89]
	v_mfma_f32_16x16x32_bf16 v[86:89], v[150:153], v[210:213], v[86:89]
	v_mfma_f32_16x16x32_bf16 v[70:73], v[170:173], v[210:213], v[70:73]
	v_mfma_f32_16x16x32_bf16 v[70:73], v[174:177], v[214:217], v[70:73]
	v_mfma_f32_16x16x32_bf16 v[66:69], v[182:185], v[214:217], v[66:69]
	v_mfma_f32_16x16x32_bf16 v[66:69], v[178:181], v[210:213], v[66:69]
	v_mfma_f32_16x16x32_bf16 v[74:77], v[178:181], v[202:205], v[74:77]
	v_mfma_f32_16x16x32_bf16 v[74:77], v[182:185], v[206:209], v[74:77]
	v_mfma_f32_16x16x32_bf16 v[78:81], v[174:177], v[206:209], v[78:81]
	v_mfma_f32_16x16x32_bf16 v[78:81], v[170:173], v[202:205], v[78:81]
	v_mfma_f32_16x16x32_bf16 v[94:97], v[170:173], v[194:197], v[94:97]
	v_mfma_f32_16x16x32_bf16 v[94:97], v[174:177], v[198:201], v[94:97]
	v_mfma_f32_16x16x32_bf16 v[90:93], v[182:185], v[198:201], v[90:93]
	v_mfma_f32_16x16x32_bf16 v[90:93], v[178:181], v[194:197], v[90:93]
	v_mfma_f32_16x16x32_bf16 v[106:109], v[178:181], v[186:189], v[106:109]
	v_mfma_f32_16x16x32_bf16 v[106:109], v[182:185], v[190:193], v[106:109]
	v_mfma_f32_16x16x32_bf16 v[110:113], v[174:177], v[190:193], v[110:113]
	v_mfma_f32_16x16x32_bf16 v[110:113], v[170:173], v[186:189], v[110:113]
	s_barrier
	s_mov_b32 m0, s34
	v_lshl_add_u64 v[162:163], v[162:163], 0, s[8:9]
	s_add_u32 s12, s12, 0x2b0080
	ds_read_b128 v[186:189], v144 offset:49152
	ds_read_b128 v[190:193], v144 offset:50176
	ds_read_b128 v[194:197], v144 offset:51200
	ds_read_b128 v[198:201], v144 offset:52224
	ds_read_b128 v[202:205], v144 offset:53248
	ds_read_b128 v[206:209], v144 offset:54272
	ds_read_b128 v[210:213], v144 offset:55296
	ds_read_b128 v[214:217], v144 offset:56320
	global_load_lds_dwordx4 v[162:163], off
	v_lshl_add_u64 v[162:163], v[218:219], 0, s[8:9]
	s_mov_b32 m0, s35
	s_addc_u32 s13, s13, 0
	global_load_lds_dwordx4 v[162:163], off
	v_lshl_add_u64 v[162:163], s[12:13], 0, v[132:133]
	s_mov_b32 m0, s36
	s_nop 0
	global_load_lds_dwordx4 v[162:163], off
	v_lshl_add_u64 v[162:163], s[12:13], 0, v[136:137]
	s_mov_b32 m0, s37
	s_nop 0
	global_load_lds_dwordx4 v[162:163], off
	v_lshl_add_u64 v[162:163], v[220:221], 0, s[8:9]
	s_mov_b32 m0, s24
	s_nop 0
	global_load_lds_dwordx4 v[162:163], off
	v_lshl_add_u64 v[162:163], v[222:223], 0, s[8:9]
	s_mov_b32 m0, s25
	s_nop 0
	global_load_lds_dwordx4 v[162:163], off
	s_waitcnt vmcnt(8)
	s_waitcnt lgkmcnt(0)
	s_barrier
	v_mfma_f32_16x16x32_bf16 v[62:65], v[150:153], v[186:189], v[62:65]
	v_mfma_f32_16x16x32_bf16 v[62:65], v[154:157], v[190:193], v[62:65]
	v_mfma_f32_16x16x32_bf16 v[58:61], v[166:169], v[190:193], v[58:61]
	v_mfma_f32_16x16x32_bf16 v[58:61], v[158:161], v[186:189], v[58:61]
	v_mfma_f32_16x16x32_bf16 v[50:53], v[158:161], v[194:197], v[50:53]
	v_mfma_f32_16x16x32_bf16 v[50:53], v[166:169], v[198:201], v[50:53]
	v_mfma_f32_16x16x32_bf16 v[54:57], v[154:157], v[198:201], v[54:57]
	v_mfma_f32_16x16x32_bf16 v[54:57], v[150:153], v[194:197], v[54:57]
	v_mfma_f32_16x16x32_bf16 v[38:41], v[150:153], v[202:205], v[38:41]
	v_mfma_f32_16x16x32_bf16 v[38:41], v[154:157], v[206:209], v[38:41]
	v_mfma_f32_16x16x32_bf16 v[34:37], v[166:169], v[206:209], v[34:37]
	v_mfma_f32_16x16x32_bf16 v[34:37], v[158:161], v[202:205], v[34:37]
	v_mfma_f32_16x16x32_bf16 v[18:21], v[158:161], v[210:213], v[18:21]
	v_mfma_f32_16x16x32_bf16 v[18:21], v[166:169], v[214:217], v[18:21]
	v_mfma_f32_16x16x32_bf16 v[22:25], v[154:157], v[214:217], v[22:25]
	v_mfma_f32_16x16x32_bf16 v[22:25], v[150:153], v[210:213], v[22:25]
	v_mfma_f32_16x16x32_bf16 v[6:9], v[170:173], v[210:213], v[6:9]
	v_mfma_f32_16x16x32_bf16 v[6:9], v[174:177], v[214:217], v[6:9]
	v_mfma_f32_16x16x32_bf16 v[2:5], v[182:185], v[214:217], v[2:5]
	v_mfma_f32_16x16x32_bf16 v[2:5], v[178:181], v[210:213], v[2:5]
	v_mfma_f32_16x16x32_bf16 v[10:13], v[178:181], v[202:205], v[10:13]
	v_mfma_f32_16x16x32_bf16 v[10:13], v[182:185], v[206:209], v[10:13]
	v_mfma_f32_16x16x32_bf16 v[14:17], v[174:177], v[206:209], v[14:17]
	v_mfma_f32_16x16x32_bf16 v[14:17], v[170:173], v[202:205], v[14:17]
	v_mfma_f32_16x16x32_bf16 v[30:33], v[170:173], v[194:197], v[30:33]
	v_mfma_f32_16x16x32_bf16 v[30:33], v[174:177], v[198:201], v[30:33]
	v_mfma_f32_16x16x32_bf16 v[26:29], v[182:185], v[198:201], v[26:29]
	v_mfma_f32_16x16x32_bf16 v[26:29], v[178:181], v[194:197], v[26:29]
	v_mfma_f32_16x16x32_bf16 v[42:45], v[178:181], v[186:189], v[42:45]
	v_mfma_f32_16x16x32_bf16 v[42:45], v[182:185], v[190:193], v[42:45]
	v_mfma_f32_16x16x32_bf16 v[46:49], v[174:177], v[190:193], v[46:49]
	v_mfma_f32_16x16x32_bf16 v[46:49], v[170:173], v[186:189], v[46:49]
	s_barrier
	s_add_u32 s10, s10, 0x100
	s_addc_u32 s11, s11, 0
	s_cmp_ge_u32 s38, s17
	s_mov_b32 s13, s38
	s_cbranch_scc0 .LBB0_2632
	s_lshl_b32 s4, s16, 21
	v_readlane_b32 s2, v249, 29
	v_lshl_or_b32 v1, s18, 8, v148
	v_mov_b32_e32 v139, 0
	s_add_u32 s4, s2, s4
	v_readlane_b32 s2, v249, 31
	v_or_b32_e32 v130, s23, v1
	v_cvt_pk_bf16_f32 v70, v70, v71
	v_cvt_pk_bf16_f32 v71, v72, v73
	v_cvt_pk_bf16_f32 v72, v66, v67
	v_add_u32_e32 v66, 0x80, v138
	v_mov_b32_e32 v67, v139
	s_addc_u32 s5, s2, 0
	v_ashrrev_i32_e32 v131, 31, v130
	v_lshlrev_b64 v[132:133], 13, v[138:139]
	v_cvt_pk_bf16_f32 v110, v110, v111
	v_cvt_pk_bf16_f32 v111, v112, v113
	v_cvt_pk_bf16_f32 v112, v106, v107
	v_or_b32_e32 v106, 16, v138
	v_mov_b32_e32 v107, v139
	v_lshlrev_b64 v[66:67], 13, v[66:67]
	v_cvt_pk_bf16_f32 v46, v46, v47
	v_cvt_pk_bf16_f32 v47, v48, v49
	v_cvt_pk_bf16_f32 v48, v42, v43
	v_add_u32_e32 v42, 0x90, v138
	v_mov_b32_e32 v43, v139
	v_lshl_add_u64 v[132:133], s[4:5], 0, v[132:133]
	v_lshlrev_b64 v[130:131], 1, v[130:131]
	v_lshlrev_b64 v[106:107], 13, v[106:107]
	v_cvt_pk_bf16_f32 v94, v94, v95
	v_cvt_pk_bf16_f32 v95, v96, v97
	v_cvt_pk_bf16_f32 v96, v90, v91
	v_or_b32_e32 v90, 32, v138
	v_mov_b32_e32 v91, v139
	v_lshl_add_u64 v[66:67], s[4:5], 0, v[66:67]
	v_lshlrev_b64 v[42:43], 13, v[42:43]
	v_cvt_pk_bf16_f32 v30, v30, v31
	v_cvt_pk_bf16_f32 v31, v32, v33
	v_cvt_pk_bf16_f32 v32, v26, v27
	v_add_u32_e32 v26, 0xa0, v138
	v_mov_b32_e32 v27, v139
	v_lshl_add_u64 v[132:133], v[132:133], 0, v[130:131]
	v_cvt_pk_bf16_f32 v113, v108, v109
	v_lshl_add_u64 v[106:107], s[4:5], 0, v[106:107]
	v_lshlrev_b64 v[90:91], 13, v[90:91]
	v_cvt_pk_bf16_f32 v78, v78, v79
	v_cvt_pk_bf16_f32 v79, v80, v81
	v_cvt_pk_bf16_f32 v80, v74, v75
	v_or_b32_e32 v74, 48, v138
	v_mov_b32_e32 v75, v139
	v_lshl_add_u64 v[66:67], v[66:67], 0, v[130:131]
	v_cvt_pk_bf16_f32 v49, v44, v45
	v_lshl_add_u64 v[42:43], s[4:5], 0, v[42:43]
	v_lshlrev_b64 v[26:27], 13, v[26:27]
	v_add_u32_e32 v138, 0xb0, v138
	global_store_dwordx4 v[132:133], v[110:113], off offset:256 sc1
	v_cvt_pk_bf16_f32 v97, v92, v93
	v_lshl_add_u64 v[90:91], s[4:5], 0, v[90:91]
	v_lshl_add_u64 v[110:111], v[106:107], 0, v[130:131]
	v_lshlrev_b64 v[74:75], 13, v[74:75]
	global_store_dwordx4 v[66:67], v[46:49], off offset:256 sc1
	v_cvt_pk_bf16_f32 v33, v28, v29
	v_lshl_add_u64 v[26:27], s[4:5], 0, v[26:27]
	v_lshl_add_u64 v[46:47], v[42:43], 0, v[130:131]
	v_cvt_pk_bf16_f32 v14, v14, v15
	v_cvt_pk_bf16_f32 v15, v16, v17
	v_cvt_pk_bf16_f32 v16, v10, v11
	v_lshlrev_b64 v[10:11], 13, v[138:139]
	global_store_dwordx4 v[110:111], v[94:97], off offset:256 sc1
	v_cvt_pk_bf16_f32 v81, v76, v77
	v_lshl_add_u64 v[74:75], s[4:5], 0, v[74:75]
	v_lshl_add_u64 v[94:95], v[90:91], 0, v[130:131]
	global_store_dwordx4 v[46:47], v[30:33], off offset:256 sc1
	v_cvt_pk_bf16_f32 v17, v12, v13
	v_lshl_add_u64 v[10:11], s[4:5], 0, v[10:11]
	v_lshl_add_u64 v[30:31], v[26:27], 0, v[130:131]
	v_cvt_pk_bf16_f32 v126, v126, v127
	v_cvt_pk_bf16_f32 v127, v128, v129
	v_cvt_pk_bf16_f32 v128, v122, v123
	v_cvt_pk_bf16_f32 v129, v124, v125
	v_cvt_pk_bf16_f32 v106, v118, v119
	v_cvt_pk_bf16_f32 v107, v120, v121
	v_cvt_pk_bf16_f32 v108, v114, v115
	v_cvt_pk_bf16_f32 v109, v116, v117
	v_cvt_pk_bf16_f32 v90, v102, v103
	v_cvt_pk_bf16_f32 v91, v104, v105
	v_cvt_pk_bf16_f32 v92, v98, v99
	v_cvt_pk_bf16_f32 v93, v100, v101
	global_store_dwordx4 v[94:95], v[78:81], off offset:256 sc1
	v_cvt_pk_bf16_f32 v76, v82, v83
	v_cvt_pk_bf16_f32 v77, v84, v85
	v_lshl_add_u64 v[78:79], v[74:75], 0, v[130:131]
	v_cvt_pk_bf16_f32 v74, v86, v87
	v_cvt_pk_bf16_f32 v75, v88, v89
	v_cvt_pk_bf16_f32 v73, v68, v69
	v_cvt_pk_bf16_f32 v62, v62, v63
	v_cvt_pk_bf16_f32 v63, v64, v65
	v_cvt_pk_bf16_f32 v64, v58, v59
	v_cvt_pk_bf16_f32 v65, v60, v61
	v_cvt_pk_bf16_f32 v42, v54, v55
	v_cvt_pk_bf16_f32 v43, v56, v57
	v_cvt_pk_bf16_f32 v44, v50, v51
	v_cvt_pk_bf16_f32 v45, v52, v53
	v_cvt_pk_bf16_f32 v26, v38, v39
	v_cvt_pk_bf16_f32 v27, v40, v41
	v_cvt_pk_bf16_f32 v28, v34, v35
	v_cvt_pk_bf16_f32 v29, v36, v37
	global_store_dwordx4 v[30:31], v[14:17], off offset:256 sc1
	v_cvt_pk_bf16_f32 v12, v18, v19
	v_cvt_pk_bf16_f32 v13, v20, v21
	v_lshl_add_u64 v[14:15], v[10:11], 0, v[130:131]
	v_cvt_pk_bf16_f32 v10, v22, v23
	v_cvt_pk_bf16_f32 v11, v24, v25
	v_cvt_pk_bf16_f32 v6, v6, v7
	v_cvt_pk_bf16_f32 v7, v8, v9
	v_cvt_pk_bf16_f32 v8, v2, v3
	v_cvt_pk_bf16_f32 v9, v4, v5
	global_store_dwordx4 v[132:133], v[126:129], off sc1
	global_store_dwordx4 v[110:111], v[106:109], off sc1
	global_store_dwordx4 v[94:95], v[90:93], off sc1
	global_store_dwordx4 v[78:79], v[74:77], off sc1
	global_store_dwordx4 v[78:79], v[70:73], off offset:256 sc1
	global_store_dwordx4 v[66:67], v[62:65], off sc1
	global_store_dwordx4 v[46:47], v[42:45], off sc1
	global_store_dwordx4 v[30:31], v[26:29], off sc1
	global_store_dwordx4 v[14:15], v[10:13], off sc1
	global_store_dwordx4 v[14:15], v[6:9], off offset:256 sc1
	s_waitcnt vmcnt(0)
	s_cmpk_lt_u32 s3, 0x100
	s_cbranch_scc0 .LBB0_2635
	s_barrier
